# v62 + loop-invariant LDS read base addresses hoisted out of the K-loop bodies (4 fewer VALU per body)
# speedup vs baseline: 1.0067x; 1.0047x over previous
; template <class Epi, class Sched, bool ALIGN_EPI = false, bool SP2 = false>
; __device__ __forceinline__ void gemm_phase(PG8_LAS unsigned char* lds, const Gemm g, const Sched& S, const Epi& E, const int wv) {
;     ...
; #pragma unroll
;     for (int a = 0; a < 2; ++a)
; #pragma unroll
;         for (int b = 0; b < 2; ++b)
; #pragma unroll
;             for (int m = 0; m < 4; ++m)
; #pragma unroll
;                 for (int n = 0; n < 2; ++n) acc[a][b][m][n] = (f32x4){0.f, 0.f, 0.f, 0.f};
;     ...
;         const char* nA = has_next ? (const char*)g.A + (size_t)nxt.pm * tstepA + (g.amod ? (size_t)(nxt.pn % g.amod) * K * 2 : (size_t)0) : cA; const char* nB = has_next ? (const char*)g.Bt + (size_t)nxt.pn * tstepB : cB;
;         for (int t = 0; t < nt; t += 2) {
;             const bool last = (t == nt - 2);
;             const char* a1 = cA + (size_t)(t + 1) * kstep;
;             const char* a2 = last ? nA : cA + (size_t)(t + 2) * kstep; const char* b2 = last ? nB : cB + (size_t)(t + 2) * kstep;
.LBB0_174:
	s_ashr_i32 s35, s34, 31
	s_lshl_b64 s[46:47], s[34:35], 20
	s_add_u32 s46, s51, s46
	v_mov_b32_e32 v153, 0
	s_addc_u32 s47, s52, s47
	s_andn2_b64 vcc, exec, s[28:29]
	v_mov_b32_e32 v152, v153
	v_pk_mov_b32 v[150:151], v[152:153], v[152:153]
	v_pk_mov_b32 v[148:149], v[152:153], v[152:153]
	v_pk_mov_b32 v[146:147], v[152:153], v[152:153]
	v_pk_mov_b32 v[136:137], v[152:153], v[152:153]
	v_pk_mov_b32 v[134:135], v[152:153], v[152:153]
	v_pk_mov_b32 v[132:133], v[152:153], v[152:153]
	v_pk_mov_b32 v[130:131], v[152:153], v[152:153]
	v_pk_mov_b32 v[120:121], v[152:153], v[152:153]
	v_pk_mov_b32 v[118:119], v[152:153], v[152:153]
	v_pk_mov_b32 v[116:117], v[152:153], v[152:153]
	v_pk_mov_b32 v[114:115], v[152:153], v[152:153]
	v_pk_mov_b32 v[104:105], v[152:153], v[152:153]
	v_pk_mov_b32 v[102:103], v[152:153], v[152:153]
	v_pk_mov_b32 v[100:101], v[152:153], v[152:153]
	v_pk_mov_b32 v[98:99], v[152:153], v[152:153]
	v_pk_mov_b32 v[144:145], v[152:153], v[152:153]
	v_pk_mov_b32 v[142:143], v[152:153], v[152:153]
	v_pk_mov_b32 v[140:141], v[152:153], v[152:153]
	v_pk_mov_b32 v[138:139], v[152:153], v[152:153]
	v_pk_mov_b32 v[128:129], v[152:153], v[152:153]
	v_pk_mov_b32 v[126:127], v[152:153], v[152:153]
	v_pk_mov_b32 v[124:125], v[152:153], v[152:153]
	v_pk_mov_b32 v[122:123], v[152:153], v[152:153]
	v_pk_mov_b32 v[112:113], v[152:153], v[152:153]
	v_pk_mov_b32 v[110:111], v[152:153], v[152:153]
	v_pk_mov_b32 v[108:109], v[152:153], v[152:153]
	v_pk_mov_b32 v[106:107], v[152:153], v[152:153]
	v_pk_mov_b32 v[96:97], v[152:153], v[152:153]
	v_pk_mov_b32 v[94:95], v[152:153], v[152:153]
	v_pk_mov_b32 v[92:93], v[152:153], v[152:153]
	v_pk_mov_b32 v[90:91], v[152:153], v[152:153]
	v_pk_mov_b32 v[80:81], v[152:153], v[152:153]
	v_pk_mov_b32 v[78:79], v[152:153], v[152:153]
	v_pk_mov_b32 v[72:73], v[152:153], v[152:153]
	v_pk_mov_b32 v[70:71], v[152:153], v[152:153]
	v_pk_mov_b32 v[48:49], v[152:153], v[152:153]
	v_pk_mov_b32 v[46:47], v[152:153], v[152:153]
	v_pk_mov_b32 v[44:45], v[152:153], v[152:153]
	v_pk_mov_b32 v[42:43], v[152:153], v[152:153]
	v_pk_mov_b32 v[32:33], v[152:153], v[152:153]
	v_pk_mov_b32 v[30:31], v[152:153], v[152:153]
	v_pk_mov_b32 v[28:29], v[152:153], v[152:153]
	v_pk_mov_b32 v[26:27], v[152:153], v[152:153]
	v_pk_mov_b32 v[16:17], v[152:153], v[152:153]
	v_pk_mov_b32 v[14:15], v[152:153], v[152:153]
	v_pk_mov_b32 v[12:13], v[152:153], v[152:153]
	v_pk_mov_b32 v[10:11], v[152:153], v[152:153]
	v_pk_mov_b32 v[64:65], v[152:153], v[152:153]
	v_pk_mov_b32 v[62:63], v[152:153], v[152:153]
	v_pk_mov_b32 v[56:57], v[152:153], v[152:153]
	v_pk_mov_b32 v[54:55], v[152:153], v[152:153]
	v_pk_mov_b32 v[40:41], v[152:153], v[152:153]
	v_pk_mov_b32 v[38:39], v[152:153], v[152:153]
	v_pk_mov_b32 v[36:37], v[152:153], v[152:153]
	v_pk_mov_b32 v[34:35], v[152:153], v[152:153]
	v_pk_mov_b32 v[24:25], v[152:153], v[152:153]
	v_pk_mov_b32 v[22:23], v[152:153], v[152:153]
	v_pk_mov_b32 v[20:21], v[152:153], v[152:153]
	v_pk_mov_b32 v[18:19], v[152:153], v[152:153]
	v_pk_mov_b32 v[8:9], v[152:153], v[152:153]
	v_pk_mov_b32 v[6:7], v[152:153], v[152:153]
	v_pk_mov_b32 v[4:5], v[152:153], v[152:153]
	v_pk_mov_b32 v[2:3], v[152:153], v[152:153]
	s_cbranch_vccnz .LBB0_178
	s_and_b64 s[42:43], s[42:43], exec
	s_cselect_b32 s11, s47, s13
	s_cselect_b32 s35, s46, s12
	s_add_u32 s12, s12, 0x80080
	s_addc_u32 s13, s13, 0
	s_add_u32 s42, s14, 0x100
	v_mov_b32_e32 v2, 0
	s_addc_u32 s43, s15, 0
	s_mov_b32 s14, 0
	v_mov_b32_e32 v3, v2
	v_pk_mov_b32 v[4:5], v[2:3], v[2:3]
	v_pk_mov_b32 v[6:7], v[2:3], v[2:3]
	v_pk_mov_b32 v[8:9], v[2:3], v[2:3]
	v_pk_mov_b32 v[18:19], v[2:3], v[2:3]
	v_pk_mov_b32 v[20:21], v[2:3], v[2:3]
	v_pk_mov_b32 v[22:23], v[2:3], v[2:3]
	v_pk_mov_b32 v[24:25], v[2:3], v[2:3]
	v_pk_mov_b32 v[34:35], v[2:3], v[2:3]
	v_pk_mov_b32 v[36:37], v[2:3], v[2:3]
	v_pk_mov_b32 v[38:39], v[2:3], v[2:3]
	v_pk_mov_b32 v[40:41], v[2:3], v[2:3]
	v_pk_mov_b32 v[54:55], v[2:3], v[2:3]
	v_pk_mov_b32 v[56:57], v[2:3], v[2:3]
	v_pk_mov_b32 v[62:63], v[2:3], v[2:3]
	v_pk_mov_b32 v[64:65], v[2:3], v[2:3]
	v_pk_mov_b32 v[10:11], v[2:3], v[2:3]
	v_pk_mov_b32 v[12:13], v[2:3], v[2:3]
	v_pk_mov_b32 v[14:15], v[2:3], v[2:3]
	v_pk_mov_b32 v[16:17], v[2:3], v[2:3]
	v_pk_mov_b32 v[26:27], v[2:3], v[2:3]
	v_pk_mov_b32 v[28:29], v[2:3], v[2:3]
	v_pk_mov_b32 v[30:31], v[2:3], v[2:3]
	v_pk_mov_b32 v[32:33], v[2:3], v[2:3]
	v_pk_mov_b32 v[42:43], v[2:3], v[2:3]
	v_pk_mov_b32 v[44:45], v[2:3], v[2:3]
	v_pk_mov_b32 v[46:47], v[2:3], v[2:3]
	v_pk_mov_b32 v[48:49], v[2:3], v[2:3]
	v_pk_mov_b32 v[70:71], v[2:3], v[2:3]
	v_pk_mov_b32 v[72:73], v[2:3], v[2:3]
	v_pk_mov_b32 v[78:79], v[2:3], v[2:3]
	v_pk_mov_b32 v[80:81], v[2:3], v[2:3]
	v_pk_mov_b32 v[90:91], v[2:3], v[2:3]
	v_pk_mov_b32 v[92:93], v[2:3], v[2:3]
	v_pk_mov_b32 v[94:95], v[2:3], v[2:3]
	v_pk_mov_b32 v[96:97], v[2:3], v[2:3]
	v_pk_mov_b32 v[106:107], v[2:3], v[2:3]
	v_pk_mov_b32 v[108:109], v[2:3], v[2:3]
	v_pk_mov_b32 v[110:111], v[2:3], v[2:3]
	v_pk_mov_b32 v[112:113], v[2:3], v[2:3]
	v_pk_mov_b32 v[122:123], v[2:3], v[2:3]
	v_pk_mov_b32 v[124:125], v[2:3], v[2:3]
	v_pk_mov_b32 v[126:127], v[2:3], v[2:3]
	v_pk_mov_b32 v[128:129], v[2:3], v[2:3]
	v_pk_mov_b32 v[138:139], v[2:3], v[2:3]
	v_pk_mov_b32 v[140:141], v[2:3], v[2:3]
	v_pk_mov_b32 v[142:143], v[2:3], v[2:3]
	v_pk_mov_b32 v[144:145], v[2:3], v[2:3]
	v_pk_mov_b32 v[98:99], v[2:3], v[2:3]
	v_pk_mov_b32 v[100:101], v[2:3], v[2:3]
	v_pk_mov_b32 v[102:103], v[2:3], v[2:3]
	v_pk_mov_b32 v[104:105], v[2:3], v[2:3]
	v_pk_mov_b32 v[114:115], v[2:3], v[2:3]
	v_pk_mov_b32 v[116:117], v[2:3], v[2:3]
	v_pk_mov_b32 v[118:119], v[2:3], v[2:3]
	v_pk_mov_b32 v[120:121], v[2:3], v[2:3]
	v_pk_mov_b32 v[130:131], v[2:3], v[2:3]
	v_pk_mov_b32 v[132:133], v[2:3], v[2:3]
	v_pk_mov_b32 v[134:135], v[2:3], v[2:3]
	v_pk_mov_b32 v[136:137], v[2:3], v[2:3]
	v_pk_mov_b32 v[146:147], v[2:3], v[2:3]
	v_pk_mov_b32 v[148:149], v[2:3], v[2:3]
	v_pk_mov_b32 v[150:151], v[2:3], v[2:3]
	v_pk_mov_b32 v[152:153], v[2:3], v[2:3]
	v_add_u32_e32 v171, 0x10000, v185
	v_add_u32_e32 v173, 0x14000, v185
	v_add_u32_e32 v201, 0x18000, v185
	v_add_u32_e32 v227, 0x1c000, v185
; #define PG8_STAGE(bufoff, gbase, voff) do { _Pragma("unroll") for (int _i = 0; _i < 2; ++_i) \
;         __builtin_amdgcn_global_load_lds((const unsigned*)((const char*)(gbase) + (voff)[_i]), (PG8_LAS unsigned*)(lds + (bufoff) + ldsw + _i * 8192), 16, 0, 0); } while (0)
; #define PG8_LDA(dst, b, h) do { _Pragma("unroll") for (int m = 0; m < 4; ++m) _Pragma("unroll") for (int k = 0; k < 2; ++k) dst[m][k] = *(const PG8_LAS bf16x8*)(lds + PG8_SA(b, h) + aoff + m * 2048 + k * 1024); } while (0)
; #define PG8_LDB(dst, b, h) do { _Pragma("unroll") for (int n = 0; n < 2; ++n) _Pragma("unroll") for (int k = 0; k < 2; ++k) dst[n][k] = *(const PG8_LAS bf16x8*)(lds + PG8_SB(b, h) + boff + n * 2048 + k * 1024); } while (0)
; #define PG8_MMA(ai, bj, At, Bt) do { __builtin_amdgcn_s_setprio(1); _Pragma("unroll") for (int m = 0; m < 4; ++m) _Pragma("unroll") for (int n = 0; n < 2; ++n) _Pragma("unroll") for (int k = 0; k < 2; ++k) \
;         acc[ai][bj][m][n] = __builtin_amdgcn_mfma_f32_16x16x32_bf16(Bt[n][k], At[m][k], acc[ai][bj][m][n], 0, 0, 0); __builtin_amdgcn_s_setprio(0); } while (0)
; #define PG8_WAIT_V(n) asm volatile("s_waitcnt vmcnt(" #n ")" ::: "memory")
; #define PG8_WAIT_L(n) asm volatile("s_waitcnt lgkmcnt(" #n ")" ::: "memory")
; template <class Epi, class Sched, bool ALIGN_EPI = false, bool SP2 = false>
; __device__ __forceinline__ void gemm_phase(PG8_LAS unsigned char* lds, const Gemm g, const Sched& S, const Epi& E, const int wv) {
;     ...
;             const bool last = (t == nt - 2);
;             const char* a1 = cA + (size_t)(t + 1) * kstep;
;             const char* a2 = last ? nA : cA + (size_t)(t + 2) * kstep; const char* b2 = last ? nB : cB + (size_t)(t + 2) * kstep;
;             const char* a3 = a2 + kstep; const char* b3 = b2 + kstep;
;             if (last && has_next) S.a_ready(nxt);
;             if constexpr (SP2) {
;             PG8_LDB(B0, 0, 0); PG8_LDB(B1, 0, 1); PG8_SCHED; PG8_LDA(At, 0, 0); PG8_STAGE(PG8_SA(1, 1), a1 + hstepA, voffA);
;             PG8_WAIT_V(8); PG8_WAIT_L(0); PG8_BAR; PG8_MMA(0, 0, At, B0); PG8_MMA(0, 1, At, B1); PG8_BAR; PG8_SCHED;
;             PG8_LDA(At, 0, 1); PG8_STAGE(PG8_SB(0, 0), b2, voffB); PG8_STAGE(PG8_SB(0, 1), b2 + hstepB, voffB); PG8_STAGE(PG8_SA(0, 0), a2, voffA);
;             PG8_WAIT_V(8); PG8_WAIT_L(0); PG8_BAR; PG8_MMA(1, 0, At, B0); PG8_MMA(1, 1, At, B1); PG8_BAR; PG8_SCHED;
.LBB0_176:
	s_add_i32 s67, s14, 2
	s_add_u32 s68, s12, 0xfff80080
	s_addc_u32 s15, s13, -1
	s_add_i32 s70, 0, 0x10000
	s_cmp_eq_u32 s61, s14
	s_cselect_b32 s15, s11, s15
	s_cselect_b32 s14, s35, s68
	s_cselect_b32 s69, s45, s43
	s_cselect_b32 s68, s44, s42
	s_add_i32 s71, 0, 0x14000
	ds_read_b128 v[66:69], v171
	ds_read_b128 v[74:77], v171 offset:1024
	ds_read_b128 v[82:85], v171 offset:2048
	ds_read_b128 v[86:89], v171 offset:3072
	ds_read_b128 v[154:157], v173
	ds_read_b128 v[158:161], v173 offset:1024
	ds_read_b128 v[174:177], v173 offset:2048
	ds_read_b128 v[178:181], v173 offset:3072
	s_add_i32 m0, s54, 0xc000
	ds_read_b128 v[202:205], v200
	ds_read_b128 v[206:209], v200 offset:1024
	ds_read_b128 v[210:213], v200 offset:2048
	ds_read_b128 v[214:217], v200 offset:3072
	ds_read_b128 v[228:231], v200 offset:4096
	ds_read_b128 v[232:235], v200 offset:5120
	ds_read_b128 v[236:239], v200 offset:6144
	ds_read_b128 v[240:243], v200 offset:7168
	global_load_lds_dwordx4 v170, s[12:13]
	s_add_i32 m0, s54, 0xe000
	s_nop 0
	global_load_lds_dwordx4 v172, s[12:13]
	s_waitcnt vmcnt(8)
	s_waitcnt lgkmcnt(0)
	s_barrier
	v_mfma_f32_16x16x32_bf16 v[150:153], v[66:69], v[202:205], v[150:153]
	v_mfma_f32_16x16x32_bf16 v[146:149], v[82:85], v[202:205], v[146:149]
	v_mfma_f32_16x16x32_bf16 v[134:137], v[66:69], v[210:213], v[134:137]
	v_mfma_f32_16x16x32_bf16 v[130:133], v[82:85], v[210:213], v[130:133]
	v_mfma_f32_16x16x32_bf16 v[118:121], v[66:69], v[228:231], v[118:121]
	v_mfma_f32_16x16x32_bf16 v[114:117], v[82:85], v[228:231], v[114:117]
	v_mfma_f32_16x16x32_bf16 v[102:105], v[66:69], v[236:239], v[102:105]
	v_mfma_f32_16x16x32_bf16 v[98:101], v[82:85], v[236:239], v[98:101]
	v_mfma_f32_16x16x32_bf16 v[150:153], v[74:77], v[206:209], v[150:153]
	v_mfma_f32_16x16x32_bf16 v[146:149], v[86:89], v[206:209], v[146:149]
	v_mfma_f32_16x16x32_bf16 v[134:137], v[74:77], v[214:217], v[134:137]
	v_mfma_f32_16x16x32_bf16 v[130:133], v[86:89], v[214:217], v[130:133]
	v_mfma_f32_16x16x32_bf16 v[118:121], v[74:77], v[232:235], v[118:121]
	v_mfma_f32_16x16x32_bf16 v[114:117], v[86:89], v[232:235], v[114:117]
	v_mfma_f32_16x16x32_bf16 v[102:105], v[74:77], v[240:243], v[102:105]
	v_mfma_f32_16x16x32_bf16 v[98:101], v[86:89], v[240:243], v[98:101]
	v_mfma_f32_16x16x32_bf16 v[142:145], v[154:157], v[202:205], v[142:145]
	v_mfma_f32_16x16x32_bf16 v[138:141], v[174:177], v[202:205], v[138:141]
	v_mfma_f32_16x16x32_bf16 v[126:129], v[154:157], v[210:213], v[126:129]
	v_mfma_f32_16x16x32_bf16 v[122:125], v[174:177], v[210:213], v[122:125]
	v_mfma_f32_16x16x32_bf16 v[110:113], v[154:157], v[228:231], v[110:113]
	v_mfma_f32_16x16x32_bf16 v[106:109], v[174:177], v[228:231], v[106:109]
	v_mfma_f32_16x16x32_bf16 v[94:97], v[154:157], v[236:239], v[94:97]
	v_mfma_f32_16x16x32_bf16 v[90:93], v[174:177], v[236:239], v[90:93]
	v_mfma_f32_16x16x32_bf16 v[142:145], v[158:161], v[206:209], v[142:145]
	v_mfma_f32_16x16x32_bf16 v[138:141], v[178:181], v[206:209], v[138:141]
	v_mfma_f32_16x16x32_bf16 v[126:129], v[158:161], v[214:217], v[126:129]
	v_mfma_f32_16x16x32_bf16 v[122:125], v[178:181], v[214:217], v[122:125]
	v_mfma_f32_16x16x32_bf16 v[110:113], v[158:161], v[232:235], v[110:113]
	v_mfma_f32_16x16x32_bf16 v[106:109], v[178:181], v[232:235], v[106:109]
	v_mfma_f32_16x16x32_bf16 v[94:97], v[158:161], v[240:243], v[94:97]
	v_mfma_f32_16x16x32_bf16 v[90:93], v[178:181], v[240:243], v[90:93]
	s_barrier
	s_add_i32 s70, s70, s53
	v_lshl_add_u64 v[218:219], s[68:69], 0, v[0:1]
	s_mov_b32 m0, s70
	ds_read_b128 v[202:205], v200 offset:16384
	ds_read_b128 v[206:209], v200 offset:17408
	ds_read_b128 v[210:213], v200 offset:18432
	ds_read_b128 v[214:217], v200 offset:19456
	ds_read_b128 v[228:231], v200 offset:20480
	ds_read_b128 v[232:235], v200 offset:21504
	ds_read_b128 v[236:239], v200 offset:22528
	ds_read_b128 v[240:243], v200 offset:23552
	global_load_lds_dwordx4 v[218:219], off
	s_add_i32 m0, s70, 0x2000
	v_lshl_add_u64 v[244:245], s[68:69], 0, v[166:167]
	s_add_u32 s68, s68, s24
	s_addc_u32 s69, s69, s25
	s_add_i32 s70, s71, s53
	global_load_lds_dwordx4 v[244:245], off
	v_lshl_add_u64 v[246:247], s[68:69], 0, v[0:1]
	s_mov_b32 m0, s70
	v_lshl_add_u64 v[248:249], s[68:69], 0, v[166:167]
	global_load_lds_dwordx4 v[246:247], off
	s_add_i32 m0, s70, 0x2000
	v_lshl_add_u64 v[250:251], s[14:15], 0, v[162:163]
	global_load_lds_dwordx4 v[248:249], off
	s_mov_b32 m0, s54
	v_lshl_add_u64 v[252:253], s[14:15], 0, v[164:165]
	global_load_lds_dwordx4 v[250:251], off
	s_mov_b32 m0, s55
	s_nop 0
	global_load_lds_dwordx4 v[252:253], off
	s_waitcnt vmcnt(8)
	s_waitcnt lgkmcnt(0)
	s_barrier
; #define PG8_STAGE(bufoff, gbase, voff) do { _Pragma("unroll") for (int _i = 0; _i < 2; ++_i) \
;         __builtin_amdgcn_global_load_lds((const unsigned*)((const char*)(gbase) + (voff)[_i]), (PG8_LAS unsigned*)(lds + (bufoff) + ldsw + _i * 8192), 16, 0, 0); } while (0)
; #define PG8_LDA(dst, b, h) do { _Pragma("unroll") for (int m = 0; m < 4; ++m) _Pragma("unroll") for (int k = 0; k < 2; ++k) dst[m][k] = *(const PG8_LAS bf16x8*)(lds + PG8_SA(b, h) + aoff + m * 2048 + k * 1024); } while (0)
; #define PG8_LDB(dst, b, h) do { _Pragma("unroll") for (int n = 0; n < 2; ++n) _Pragma("unroll") for (int k = 0; k < 2; ++k) dst[n][k] = *(const PG8_LAS bf16x8*)(lds + PG8_SB(b, h) + boff + n * 2048 + k * 1024); } while (0)
; #define PG8_MMA(ai, bj, At, Bt) do { __builtin_amdgcn_s_setprio(1); _Pragma("unroll") for (int m = 0; m < 4; ++m) _Pragma("unroll") for (int n = 0; n < 2; ++n) _Pragma("unroll") for (int k = 0; k < 2; ++k) \
;         acc[ai][bj][m][n] = __builtin_amdgcn_mfma_f32_16x16x32_bf16(Bt[n][k], At[m][k], acc[ai][bj][m][n], 0, 0, 0); __builtin_amdgcn_s_setprio(0); } while (0)
; #define PG8_WAIT_V(n) asm volatile("s_waitcnt vmcnt(" #n ")" ::: "memory")
; #define PG8_WAIT_L(n) asm volatile("s_waitcnt lgkmcnt(" #n ")" ::: "memory")
; #define PG8_BAR __builtin_amdgcn_s_barrier()
; #define PG8_SCHED __builtin_amdgcn_sched_barrier(0)
; template <class Epi, class Sched, bool ALIGN_EPI = false, bool SP2 = false>
; __device__ __forceinline__ void gemm_phase(PG8_LAS unsigned char* lds, const Gemm g, const Sched& S, const Epi& E, const int wv) {
;     ...
;             PG8_WAIT_V(8); PG8_WAIT_L(0); PG8_BAR; PG8_MMA(1, 0, At, B0); PG8_MMA(1, 1, At, B1); PG8_BAR; PG8_SCHED;
;             PG8_LDB(B0, 1, 0); PG8_LDB(B1, 1, 1); PG8_SCHED; PG8_LDA(At, 1, 0); PG8_STAGE(PG8_SA(0, 1), a2 + hstepA, voffA);
;             PG8_WAIT_V(8); PG8_WAIT_L(0); PG8_BAR; PG8_MMA(0, 0, At, B0); PG8_MMA(0, 1, At, B1); PG8_BAR; PG8_SCHED;
	v_mfma_f32_16x16x32_bf16 v[78:81], v[66:69], v[202:205], v[78:81]
	v_mfma_f32_16x16x32_bf16 v[70:73], v[82:85], v[202:205], v[70:73]
	v_mfma_f32_16x16x32_bf16 v[46:49], v[66:69], v[210:213], v[46:49]
	v_mfma_f32_16x16x32_bf16 v[42:45], v[82:85], v[210:213], v[42:45]
	v_mfma_f32_16x16x32_bf16 v[30:33], v[66:69], v[228:231], v[30:33]
	v_mfma_f32_16x16x32_bf16 v[26:29], v[82:85], v[228:231], v[26:29]
	v_mfma_f32_16x16x32_bf16 v[14:17], v[66:69], v[236:239], v[14:17]
	v_mfma_f32_16x16x32_bf16 v[10:13], v[82:85], v[236:239], v[10:13]
	v_mfma_f32_16x16x32_bf16 v[78:81], v[74:77], v[206:209], v[78:81]
	v_mfma_f32_16x16x32_bf16 v[70:73], v[86:89], v[206:209], v[70:73]
	v_mfma_f32_16x16x32_bf16 v[46:49], v[74:77], v[214:217], v[46:49]
	v_mfma_f32_16x16x32_bf16 v[42:45], v[86:89], v[214:217], v[42:45]
	v_mfma_f32_16x16x32_bf16 v[30:33], v[74:77], v[232:235], v[30:33]
	v_mfma_f32_16x16x32_bf16 v[26:29], v[86:89], v[232:235], v[26:29]
	v_mfma_f32_16x16x32_bf16 v[14:17], v[74:77], v[240:243], v[14:17]
	v_mfma_f32_16x16x32_bf16 v[10:13], v[86:89], v[240:243], v[10:13]
	v_mfma_f32_16x16x32_bf16 v[60:63], v[154:157], v[202:205], v[62:65]
	v_mfma_f32_16x16x32_bf16 v[54:57], v[174:177], v[202:205], v[54:57]
	v_mfma_f32_16x16x32_bf16 v[38:41], v[154:157], v[210:213], v[38:41]
	v_mfma_f32_16x16x32_bf16 v[34:37], v[174:177], v[210:213], v[34:37]
	v_mfma_f32_16x16x32_bf16 v[22:25], v[154:157], v[228:231], v[22:25]
	v_mfma_f32_16x16x32_bf16 v[18:21], v[174:177], v[228:231], v[18:21]
	v_mfma_f32_16x16x32_bf16 v[6:9], v[154:157], v[236:239], v[6:9]
	v_mfma_f32_16x16x32_bf16 v[2:5], v[174:177], v[236:239], v[2:5]
	v_mfma_f32_16x16x32_bf16 v[60:63], v[158:161], v[206:209], v[60:63]
	v_mfma_f32_16x16x32_bf16 v[54:57], v[178:181], v[206:209], v[54:57]
	v_mfma_f32_16x16x32_bf16 v[38:41], v[158:161], v[214:217], v[38:41]
	v_mfma_f32_16x16x32_bf16 v[34:37], v[178:181], v[214:217], v[34:37]
	v_mfma_f32_16x16x32_bf16 v[22:25], v[158:161], v[232:235], v[22:25]
	v_mfma_f32_16x16x32_bf16 v[18:21], v[178:181], v[232:235], v[18:21]
	v_mfma_f32_16x16x32_bf16 v[6:9], v[158:161], v[240:243], v[6:9]
	v_mfma_f32_16x16x32_bf16 v[2:5], v[178:181], v[240:243], v[2:5]
	s_barrier
	s_add_i32 s68, 0, 0x18000
	s_add_i32 s69, 0, 0x1c000
	ds_read_b128 v[64:67], v201
	ds_read_b128 v[74:77], v201 offset:1024
	ds_read_b128 v[82:85], v201 offset:2048
	ds_read_b128 v[86:89], v201 offset:3072
	ds_read_b128 v[154:157], v227
	ds_read_b128 v[158:161], v227 offset:1024
	ds_read_b128 v[174:177], v227 offset:2048
	ds_read_b128 v[178:181], v227 offset:3072
	s_add_u32 s14, s14, 0x80000
	s_addc_u32 s15, s15, 0
	s_mov_b32 m0, s56
	ds_read_b128 v[202:205], v200 offset:32768
	ds_read_b128 v[206:209], v200 offset:33792
	ds_read_b128 v[210:213], v200 offset:34816
	ds_read_b128 v[214:217], v200 offset:35840
	ds_read_b128 v[228:231], v200 offset:36864
	ds_read_b128 v[232:235], v200 offset:37888
	ds_read_b128 v[236:239], v200 offset:38912
	ds_read_b128 v[240:243], v200 offset:39936
	global_load_lds_dwordx4 v162, s[14:15]
	s_mov_b32 m0, s57
	s_nop 0
	global_load_lds_dwordx4 v164, s[14:15]
	s_waitcnt vmcnt(8)
	s_waitcnt lgkmcnt(0)
	s_barrier
	v_mfma_f32_16x16x32_bf16 v[150:153], v[64:67], v[202:205], v[150:153]
	v_mfma_f32_16x16x32_bf16 v[146:149], v[82:85], v[202:205], v[146:149]
	v_mfma_f32_16x16x32_bf16 v[134:137], v[64:67], v[210:213], v[134:137]
	v_mfma_f32_16x16x32_bf16 v[130:133], v[82:85], v[210:213], v[130:133]
	v_mfma_f32_16x16x32_bf16 v[118:121], v[64:67], v[228:231], v[118:121]
	v_mfma_f32_16x16x32_bf16 v[114:117], v[82:85], v[228:231], v[114:117]
	v_mfma_f32_16x16x32_bf16 v[102:105], v[64:67], v[236:239], v[102:105]
	v_mfma_f32_16x16x32_bf16 v[98:101], v[82:85], v[236:239], v[98:101]
	v_mfma_f32_16x16x32_bf16 v[150:153], v[74:77], v[206:209], v[150:153]
	v_mfma_f32_16x16x32_bf16 v[146:149], v[86:89], v[206:209], v[146:149]
	v_mfma_f32_16x16x32_bf16 v[134:137], v[74:77], v[214:217], v[134:137]
	v_mfma_f32_16x16x32_bf16 v[130:133], v[86:89], v[214:217], v[130:133]
	v_mfma_f32_16x16x32_bf16 v[118:121], v[74:77], v[232:235], v[118:121]
	v_mfma_f32_16x16x32_bf16 v[114:117], v[86:89], v[232:235], v[114:117]
	v_mfma_f32_16x16x32_bf16 v[102:105], v[74:77], v[240:243], v[102:105]
	v_mfma_f32_16x16x32_bf16 v[98:101], v[86:89], v[240:243], v[98:101]
	v_mfma_f32_16x16x32_bf16 v[142:145], v[154:157], v[202:205], v[142:145]
	v_mfma_f32_16x16x32_bf16 v[138:141], v[174:177], v[202:205], v[138:141]
	v_mfma_f32_16x16x32_bf16 v[126:129], v[154:157], v[210:213], v[126:129]
	v_mfma_f32_16x16x32_bf16 v[122:125], v[174:177], v[210:213], v[122:125]
	v_mfma_f32_16x16x32_bf16 v[110:113], v[154:157], v[228:231], v[110:113]
	v_mfma_f32_16x16x32_bf16 v[106:109], v[174:177], v[228:231], v[106:109]
	v_mfma_f32_16x16x32_bf16 v[94:97], v[154:157], v[236:239], v[94:97]
	v_mfma_f32_16x16x32_bf16 v[90:93], v[174:177], v[236:239], v[90:93]
	v_mfma_f32_16x16x32_bf16 v[142:145], v[158:161], v[206:209], v[142:145]
	v_mfma_f32_16x16x32_bf16 v[138:141], v[178:181], v[206:209], v[138:141]
	v_mfma_f32_16x16x32_bf16 v[126:129], v[158:161], v[214:217], v[126:129]
	v_mfma_f32_16x16x32_bf16 v[122:125], v[178:181], v[214:217], v[122:125]
	v_mfma_f32_16x16x32_bf16 v[110:113], v[158:161], v[232:235], v[110:113]
	v_mfma_f32_16x16x32_bf16 v[106:109], v[178:181], v[232:235], v[106:109]
	v_mfma_f32_16x16x32_bf16 v[94:97], v[158:161], v[240:243], v[94:97]
	v_mfma_f32_16x16x32_bf16 v[90:93], v[178:181], v[240:243], v[90:93]
	s_barrier
; #define PG8_STAGE(bufoff, gbase, voff) do { _Pragma("unroll") for (int _i = 0; _i < 2; ++_i) \
;         __builtin_amdgcn_global_load_lds((const unsigned*)((const char*)(gbase) + (voff)[_i]), (PG8_LAS unsigned*)(lds + (bufoff) + ldsw + _i * 8192), 16, 0, 0); } while (0)
; #define PG8_LDA(dst, b, h) do { _Pragma("unroll") for (int m = 0; m < 4; ++m) _Pragma("unroll") for (int k = 0; k < 2; ++k) dst[m][k] = *(const PG8_LAS bf16x8*)(lds + PG8_SA(b, h) + aoff + m * 2048 + k * 1024); } while (0)
; #define PG8_MMA(ai, bj, At, Bt) do { __builtin_amdgcn_s_setprio(1); _Pragma("unroll") for (int m = 0; m < 4; ++m) _Pragma("unroll") for (int n = 0; n < 2; ++n) _Pragma("unroll") for (int k = 0; k < 2; ++k) \
;         acc[ai][bj][m][n] = __builtin_amdgcn_mfma_f32_16x16x32_bf16(Bt[n][k], At[m][k], acc[ai][bj][m][n], 0, 0, 0); __builtin_amdgcn_s_setprio(0); } while (0)
; #define PG8_WAIT_V(n) asm volatile("s_waitcnt vmcnt(" #n ")" ::: "memory")
; #define PG8_WAIT_L(n) asm volatile("s_waitcnt lgkmcnt(" #n ")" ::: "memory")
; #define PG8_BAR __builtin_amdgcn_s_barrier()
; #define PG8_SCHED __builtin_amdgcn_sched_barrier(0)
; template <class Epi, class Sched, bool ALIGN_EPI = false, bool SP2 = false>
; __device__ __forceinline__ void gemm_phase(PG8_LAS unsigned char* lds, const Gemm g, const Sched& S, const Epi& E, const int wv) {
;     ...
;         for (int t = 0; t < nt; t += 2) {
;     ...
;             PG8_LDA(At, 1, 1); PG8_STAGE(PG8_SB(1, 0), b3, voffB); PG8_STAGE(PG8_SB(1, 1), b3 + hstepB, voffB); PG8_STAGE(PG8_SA(1, 0), a3, voffA);
;             PG8_WAIT_V(8); PG8_WAIT_L(0); PG8_BAR; PG8_MMA(1, 0, At, B0); PG8_MMA(1, 1, At, B1); PG8_BAR; PG8_SCHED;
	s_add_i32 s14, s68, s53
	s_add_i32 m0, s14, 0xffffff80
	ds_read_b128 v[202:205], v200 offset:49152
	ds_read_b128 v[206:209], v200 offset:50176
	ds_read_b128 v[210:213], v200 offset:51200
	ds_read_b128 v[214:217], v200 offset:52224
	ds_read_b128 v[228:231], v200 offset:53248
	ds_read_b128 v[232:235], v200 offset:54272
	ds_read_b128 v[236:239], v200 offset:55296
	ds_read_b128 v[240:243], v200 offset:56320
	global_load_lds_dwordx4 v[218:219], off offset:128
	s_add_i32 m0, s14, 0x1f80
	s_add_i32 s14, s69, s53
	global_load_lds_dwordx4 v[244:245], off offset:128
	s_add_i32 m0, s14, 0xffffff80
	s_nop 0
	global_load_lds_dwordx4 v[246:247], off offset:128
	s_add_i32 m0, s14, 0x1f80
	s_nop 0
	global_load_lds_dwordx4 v[248:249], off offset:128
	s_add_i32 m0, s58, 0xffffff80
	s_nop 0
	global_load_lds_dwordx4 v[250:251], off offset:128
	s_add_i32 m0, s59, 0xffffff80
	s_nop 0
	global_load_lds_dwordx4 v[252:253], off offset:128
	s_waitcnt vmcnt(8)
	s_waitcnt lgkmcnt(0)
	s_barrier
	v_mfma_f32_16x16x32_bf16 v[78:81], v[64:67], v[202:205], v[78:81]
	v_mfma_f32_16x16x32_bf16 v[68:71], v[82:85], v[202:205], v[70:73]
	v_mfma_f32_16x16x32_bf16 v[46:49], v[64:67], v[210:213], v[46:49]
	v_mfma_f32_16x16x32_bf16 v[42:45], v[82:85], v[210:213], v[42:45]
	v_mfma_f32_16x16x32_bf16 v[30:33], v[64:67], v[228:231], v[30:33]
	v_mfma_f32_16x16x32_bf16 v[26:29], v[82:85], v[228:231], v[26:29]
	v_mfma_f32_16x16x32_bf16 v[14:17], v[64:67], v[236:239], v[14:17]
	v_mfma_f32_16x16x32_bf16 v[10:13], v[82:85], v[236:239], v[10:13]
	v_mfma_f32_16x16x32_bf16 v[78:81], v[74:77], v[206:209], v[78:81]
	v_mfma_f32_16x16x32_bf16 v[70:73], v[86:89], v[206:209], v[68:71]
	v_mfma_f32_16x16x32_bf16 v[46:49], v[74:77], v[214:217], v[46:49]
	v_mfma_f32_16x16x32_bf16 v[42:45], v[86:89], v[214:217], v[42:45]
	v_mfma_f32_16x16x32_bf16 v[30:33], v[74:77], v[232:235], v[30:33]
	v_mfma_f32_16x16x32_bf16 v[26:29], v[86:89], v[232:235], v[26:29]
	v_mfma_f32_16x16x32_bf16 v[14:17], v[74:77], v[240:243], v[14:17]
	v_mfma_f32_16x16x32_bf16 v[10:13], v[86:89], v[240:243], v[10:13]
	v_mfma_f32_16x16x32_bf16 v[60:63], v[154:157], v[202:205], v[60:63]
	v_mfma_f32_16x16x32_bf16 v[54:57], v[174:177], v[202:205], v[54:57]
	v_mfma_f32_16x16x32_bf16 v[38:41], v[154:157], v[210:213], v[38:41]
	v_mfma_f32_16x16x32_bf16 v[34:37], v[174:177], v[210:213], v[34:37]
	v_mfma_f32_16x16x32_bf16 v[22:25], v[154:157], v[228:231], v[22:25]
	v_mfma_f32_16x16x32_bf16 v[18:21], v[174:177], v[228:231], v[18:21]
	v_mfma_f32_16x16x32_bf16 v[6:9], v[154:157], v[236:239], v[6:9]
	v_mfma_f32_16x16x32_bf16 v[2:5], v[174:177], v[236:239], v[2:5]
	v_mfma_f32_16x16x32_bf16 v[62:65], v[158:161], v[206:209], v[60:63]
	v_mfma_f32_16x16x32_bf16 v[54:57], v[178:181], v[206:209], v[54:57]
	v_mfma_f32_16x16x32_bf16 v[38:41], v[158:161], v[214:217], v[38:41]
	v_mfma_f32_16x16x32_bf16 v[34:37], v[178:181], v[214:217], v[34:37]
	v_mfma_f32_16x16x32_bf16 v[22:25], v[158:161], v[232:235], v[22:25]
	v_mfma_f32_16x16x32_bf16 v[18:21], v[178:181], v[232:235], v[18:21]
	v_mfma_f32_16x16x32_bf16 v[6:9], v[158:161], v[240:243], v[6:9]
	v_mfma_f32_16x16x32_bf16 v[2:5], v[178:181], v[240:243], v[2:5]
	s_barrier
	s_add_u32 s12, s12, 0x100
	s_addc_u32 s13, s13, 0
	s_add_u32 s42, s42, 0x100
	s_addc_u32 s43, s43, 0
	s_cmp_ge_i32 s67, s60
	s_mov_b32 s14, s67
	s_cbranch_scc0 .LBB0_176
	s_movk_i32 s68, 0x4000
	s_movk_i32 s69, 0x6000
	s_mov_b32 s70, 0x18000
	s_mov_b32 s71, 0x3f317217

; template <class Epi, class Sched, bool ALIGN_EPI = false, bool SP2 = false>
; __device__ __forceinline__ void gemm_phase(PG8_LAS unsigned char* lds, const Gemm g, const Sched& S, const Epi& E, const int wv) {
;     ...
; #pragma unroll
;     for (int a = 0; a < 2; ++a)
; #pragma unroll
;         for (int b = 0; b < 2; ++b)
; #pragma unroll
;             for (int m = 0; m < 4; ++m)
; #pragma unroll
;                 for (int n = 0; n < 2; ++n) acc[a][b][m][n] = (f32x4){0.f, 0.f, 0.f, 0.f};
;     ...
;         const char* nA = has_next ? (const char*)g.A + (size_t)nxt.pm * tstepA + (g.amod ? (size_t)(nxt.pn % g.amod) * K * 2 : (size_t)0) : cA; const char* nB = has_next ? (const char*)g.Bt + (size_t)nxt.pn * tstepB : cB;
;         for (int t = 0; t < nt; t += 2) {
;             const bool last = (t == nt - 2);
;             const char* a1 = cA + (size_t)(t + 1) * kstep;
;             const char* a2 = last ? nA : cA + (size_t)(t + 2) * kstep; const char* b2 = last ? nB : cB + (size_t)(t + 2) * kstep;
.LBB0_334:
	v_mov_b32_e32 v141, 0
	s_andn2_b64 vcc, exec, s[34:35]
	v_mov_b32_e32 v140, v141
	v_pk_mov_b32 v[138:139], v[140:141], v[140:141]
	v_pk_mov_b32 v[144:145], v[140:141], v[140:141]
	v_pk_mov_b32 v[142:143], v[140:141], v[140:141]
	v_pk_mov_b32 v[128:129], v[140:141], v[140:141]
	v_pk_mov_b32 v[126:127], v[140:141], v[140:141]
	v_pk_mov_b32 v[124:125], v[140:141], v[140:141]
	v_pk_mov_b32 v[122:123], v[140:141], v[140:141]
	v_pk_mov_b32 v[112:113], v[140:141], v[140:141]
	v_pk_mov_b32 v[110:111], v[140:141], v[140:141]
	v_pk_mov_b32 v[108:109], v[140:141], v[140:141]
	v_pk_mov_b32 v[106:107], v[140:141], v[140:141]
	v_pk_mov_b32 v[96:97], v[140:141], v[140:141]
	v_pk_mov_b32 v[94:95], v[140:141], v[140:141]
	v_pk_mov_b32 v[92:93], v[140:141], v[140:141]
	v_pk_mov_b32 v[90:91], v[140:141], v[140:141]
	v_pk_mov_b32 v[136:137], v[140:141], v[140:141]
	v_pk_mov_b32 v[134:135], v[140:141], v[140:141]
	v_pk_mov_b32 v[132:133], v[140:141], v[140:141]
	v_pk_mov_b32 v[130:131], v[140:141], v[140:141]
	v_pk_mov_b32 v[120:121], v[140:141], v[140:141]
	v_pk_mov_b32 v[118:119], v[140:141], v[140:141]
	v_pk_mov_b32 v[116:117], v[140:141], v[140:141]
	v_pk_mov_b32 v[114:115], v[140:141], v[140:141]
	v_pk_mov_b32 v[104:105], v[140:141], v[140:141]
	v_pk_mov_b32 v[102:103], v[140:141], v[140:141]
	v_pk_mov_b32 v[100:101], v[140:141], v[140:141]
	v_pk_mov_b32 v[98:99], v[140:141], v[140:141]
	v_pk_mov_b32 v[88:89], v[140:141], v[140:141]
	v_pk_mov_b32 v[86:87], v[140:141], v[140:141]
	v_pk_mov_b32 v[84:85], v[140:141], v[140:141]
	v_pk_mov_b32 v[82:83], v[140:141], v[140:141]
	v_pk_mov_b32 v[80:81], v[140:141], v[140:141]
	v_pk_mov_b32 v[78:79], v[140:141], v[140:141]
	v_pk_mov_b32 v[76:77], v[140:141], v[140:141]
	v_pk_mov_b32 v[74:75], v[140:141], v[140:141]
	v_pk_mov_b32 v[64:65], v[140:141], v[140:141]
	v_pk_mov_b32 v[62:63], v[140:141], v[140:141]
	v_pk_mov_b32 v[60:61], v[140:141], v[140:141]
	v_pk_mov_b32 v[58:59], v[140:141], v[140:141]
	s_nop 0
	v_pk_mov_b32 v[40:41], v[140:141], v[140:141]
	v_pk_mov_b32 v[38:39], v[140:141], v[140:141]
	v_pk_mov_b32 v[36:37], v[140:141], v[140:141]
	v_pk_mov_b32 v[34:35], v[140:141], v[140:141]
	v_pk_mov_b32 v[16:17], v[140:141], v[140:141]
	v_pk_mov_b32 v[14:15], v[140:141], v[140:141]
	v_pk_mov_b32 v[12:13], v[140:141], v[140:141]
	v_pk_mov_b32 v[10:11], v[140:141], v[140:141]
	v_pk_mov_b32 v[72:73], v[140:141], v[140:141]
	v_pk_mov_b32 v[70:71], v[140:141], v[140:141]
	v_pk_mov_b32 v[68:69], v[140:141], v[140:141]
	v_pk_mov_b32 v[66:67], v[140:141], v[140:141]
	v_pk_mov_b32 v[56:57], v[140:141], v[140:141]
	v_pk_mov_b32 v[54:55], v[140:141], v[140:141]
	v_pk_mov_b32 v[52:53], v[140:141], v[140:141]
	v_pk_mov_b32 v[50:51], v[140:141], v[140:141]
	v_pk_mov_b32 v[24:25], v[140:141], v[140:141]
	v_pk_mov_b32 v[22:23], v[140:141], v[140:141]
	v_pk_mov_b32 v[20:21], v[140:141], v[140:141]
	v_pk_mov_b32 v[18:19], v[140:141], v[140:141]
	v_pk_mov_b32 v[8:9], v[140:141], v[140:141]
	v_pk_mov_b32 v[6:7], v[140:141], v[140:141]
	v_pk_mov_b32 v[4:5], v[140:141], v[140:141]
	v_pk_mov_b32 v[2:3], v[140:141], v[140:141]
	s_cbranch_vccnz .LBB0_337
	s_add_u32 s12, s40, 0x80080
	s_addc_u32 s13, s41, 0
	s_add_u32 s11, s14, 0x100
	v_mov_b32_e32 v2, 0
	s_addc_u32 s17, s15, 0
	s_mov_b32 s14, 0
	v_mov_b32_e32 v3, v2
	v_pk_mov_b32 v[4:5], v[2:3], v[2:3]
	v_pk_mov_b32 v[6:7], v[2:3], v[2:3]
	v_pk_mov_b32 v[8:9], v[2:3], v[2:3]
	v_pk_mov_b32 v[18:19], v[2:3], v[2:3]
	v_pk_mov_b32 v[20:21], v[2:3], v[2:3]
	v_pk_mov_b32 v[22:23], v[2:3], v[2:3]
	v_pk_mov_b32 v[24:25], v[2:3], v[2:3]
	v_pk_mov_b32 v[50:51], v[2:3], v[2:3]
	v_pk_mov_b32 v[52:53], v[2:3], v[2:3]
	v_pk_mov_b32 v[54:55], v[2:3], v[2:3]
	v_pk_mov_b32 v[56:57], v[2:3], v[2:3]
	v_pk_mov_b32 v[66:67], v[2:3], v[2:3]
	v_pk_mov_b32 v[68:69], v[2:3], v[2:3]
	v_pk_mov_b32 v[70:71], v[2:3], v[2:3]
	v_pk_mov_b32 v[72:73], v[2:3], v[2:3]
	v_pk_mov_b32 v[10:11], v[2:3], v[2:3]
	v_pk_mov_b32 v[12:13], v[2:3], v[2:3]
	v_pk_mov_b32 v[14:15], v[2:3], v[2:3]
	v_pk_mov_b32 v[16:17], v[2:3], v[2:3]
	v_pk_mov_b32 v[34:35], v[2:3], v[2:3]
	v_pk_mov_b32 v[36:37], v[2:3], v[2:3]
	v_pk_mov_b32 v[38:39], v[2:3], v[2:3]
	v_pk_mov_b32 v[40:41], v[2:3], v[2:3]
	v_pk_mov_b32 v[58:59], v[2:3], v[2:3]
	v_pk_mov_b32 v[60:61], v[2:3], v[2:3]
	v_pk_mov_b32 v[62:63], v[2:3], v[2:3]
	v_pk_mov_b32 v[64:65], v[2:3], v[2:3]
	v_pk_mov_b32 v[74:75], v[2:3], v[2:3]
	v_pk_mov_b32 v[76:77], v[2:3], v[2:3]
	v_pk_mov_b32 v[78:79], v[2:3], v[2:3]
	v_pk_mov_b32 v[80:81], v[2:3], v[2:3]
	v_pk_mov_b32 v[82:83], v[2:3], v[2:3]
	v_pk_mov_b32 v[84:85], v[2:3], v[2:3]
	v_pk_mov_b32 v[86:87], v[2:3], v[2:3]
	v_pk_mov_b32 v[88:89], v[2:3], v[2:3]
	v_pk_mov_b32 v[98:99], v[2:3], v[2:3]
	v_pk_mov_b32 v[100:101], v[2:3], v[2:3]
	v_pk_mov_b32 v[102:103], v[2:3], v[2:3]
	v_pk_mov_b32 v[104:105], v[2:3], v[2:3]
	v_pk_mov_b32 v[114:115], v[2:3], v[2:3]
	v_pk_mov_b32 v[116:117], v[2:3], v[2:3]
	v_pk_mov_b32 v[118:119], v[2:3], v[2:3]
	v_pk_mov_b32 v[120:121], v[2:3], v[2:3]
	v_pk_mov_b32 v[130:131], v[2:3], v[2:3]
	v_pk_mov_b32 v[132:133], v[2:3], v[2:3]
	v_pk_mov_b32 v[134:135], v[2:3], v[2:3]
	v_pk_mov_b32 v[136:137], v[2:3], v[2:3]
	v_pk_mov_b32 v[90:91], v[2:3], v[2:3]
	v_pk_mov_b32 v[92:93], v[2:3], v[2:3]
	v_pk_mov_b32 v[94:95], v[2:3], v[2:3]
	v_pk_mov_b32 v[96:97], v[2:3], v[2:3]
	v_pk_mov_b32 v[106:107], v[2:3], v[2:3]
	v_pk_mov_b32 v[108:109], v[2:3], v[2:3]
	v_pk_mov_b32 v[110:111], v[2:3], v[2:3]
	v_pk_mov_b32 v[112:113], v[2:3], v[2:3]
	v_pk_mov_b32 v[122:123], v[2:3], v[2:3]
	v_pk_mov_b32 v[124:125], v[2:3], v[2:3]
	v_pk_mov_b32 v[126:127], v[2:3], v[2:3]
	v_pk_mov_b32 v[128:129], v[2:3], v[2:3]
	v_pk_mov_b32 v[142:143], v[2:3], v[2:3]
	v_pk_mov_b32 v[144:145], v[2:3], v[2:3]
	v_pk_mov_b32 v[138:139], v[2:3], v[2:3]
	v_pk_mov_b32 v[140:141], v[2:3], v[2:3]
	v_add_u32_e32 v171, 0x10000, v197
	v_add_u32_e32 v227, 0x14000, v197
	v_add_u32_e32 v244, 0x18000, v197
	v_add_u32_e32 v245, 0x1c000, v197
; #define PG8_STAGE(bufoff, gbase, voff) do { _Pragma("unroll") for (int _i = 0; _i < 2; ++_i) \
;         __builtin_amdgcn_global_load_lds((const unsigned*)((const char*)(gbase) + (voff)[_i]), (PG8_LAS unsigned*)(lds + (bufoff) + ldsw + _i * 8192), 16, 0, 0); } while (0)
; #define PG8_LDA(dst, b, h) do { _Pragma("unroll") for (int m = 0; m < 4; ++m) _Pragma("unroll") for (int k = 0; k < 2; ++k) dst[m][k] = *(const PG8_LAS bf16x8*)(lds + PG8_SA(b, h) + aoff + m * 2048 + k * 1024); } while (0)
; #define PG8_LDB(dst, b, h) do { _Pragma("unroll") for (int n = 0; n < 2; ++n) _Pragma("unroll") for (int k = 0; k < 2; ++k) dst[n][k] = *(const PG8_LAS bf16x8*)(lds + PG8_SB(b, h) + boff + n * 2048 + k * 1024); } while (0)
; #define PG8_MMA(ai, bj, At, Bt) do { __builtin_amdgcn_s_setprio(1); _Pragma("unroll") for (int m = 0; m < 4; ++m) _Pragma("unroll") for (int n = 0; n < 2; ++n) _Pragma("unroll") for (int k = 0; k < 2; ++k) \
;         acc[ai][bj][m][n] = __builtin_amdgcn_mfma_f32_16x16x32_bf16(Bt[n][k], At[m][k], acc[ai][bj][m][n], 0, 0, 0); __builtin_amdgcn_s_setprio(0); } while (0)
; #define PG8_WAIT_V(n) asm volatile("s_waitcnt vmcnt(" #n ")" ::: "memory")
; #define PG8_WAIT_L(n) asm volatile("s_waitcnt lgkmcnt(" #n ")" ::: "memory")
; template <class Epi, class Sched, bool ALIGN_EPI = false, bool SP2 = false>
; __device__ __forceinline__ void gemm_phase(PG8_LAS unsigned char* lds, const Gemm g, const Sched& S, const Epi& E, const int wv) {
;     ...
;             const bool last = (t == nt - 2);
;             const char* a1 = cA + (size_t)(t + 1) * kstep;
;             const char* a2 = last ? nA : cA + (size_t)(t + 2) * kstep; const char* b2 = last ? nB : cB + (size_t)(t + 2) * kstep;
;             const char* a3 = a2 + kstep; const char* b3 = b2 + kstep;
;             if (last && has_next) S.a_ready(nxt);
;             if constexpr (SP2) {
;             PG8_LDB(B0, 0, 0); PG8_LDB(B1, 0, 1); PG8_SCHED; PG8_LDA(At, 0, 0); PG8_STAGE(PG8_SA(1, 1), a1 + hstepA, voffA);
;             PG8_WAIT_V(8); PG8_WAIT_L(0); PG8_BAR; PG8_MMA(0, 0, At, B0); PG8_MMA(0, 1, At, B1); PG8_BAR; PG8_SCHED;
;             PG8_LDA(At, 0, 1); PG8_STAGE(PG8_SB(0, 0), b2, voffB); PG8_STAGE(PG8_SB(0, 1), b2 + hstepB, voffB); PG8_STAGE(PG8_SA(0, 0), a2, voffA);
;             PG8_WAIT_V(8); PG8_WAIT_L(0); PG8_BAR; PG8_MMA(1, 0, At, B0); PG8_MMA(1, 1, At, B1); PG8_BAR; PG8_SCHED;
.LBB0_336:
	s_add_i32 s40, s14, 2
	s_add_u32 s41, s12, 0xfff80080
	s_addc_u32 s15, s13, -1
	s_add_i32 s65, 0, 0x10000
	s_cmp_eq_u32 s62, s14
	s_cselect_b32 s15, s93, s15
	s_cselect_b32 s14, s92, s41
	s_cselect_b32 s45, s25, s17
	s_cselect_b32 s44, s24, s11
	s_add_i32 s41, 0, 0x14000
	ds_read_b128 v[26:29], v171
	ds_read_b128 v[30:33], v171 offset:1024
	ds_read_b128 v[42:45], v171 offset:2048
	ds_read_b128 v[46:49], v171 offset:3072
	ds_read_b128 v[146:149], v227
	ds_read_b128 v[150:153], v227 offset:1024
	ds_read_b128 v[154:157], v227 offset:2048
	ds_read_b128 v[158:161], v227 offset:3072
	s_add_i32 m0, s55, 0xc000
	ds_read_b128 v[172:175], v199
	ds_read_b128 v[176:179], v199 offset:1024
	ds_read_b128 v[180:183], v199 offset:2048
	ds_read_b128 v[200:203], v199 offset:3072
	ds_read_b128 v[204:207], v199 offset:4096
	ds_read_b128 v[208:211], v199 offset:5120
	ds_read_b128 v[212:215], v199 offset:6144
	ds_read_b128 v[216:219], v199 offset:7168
	global_load_lds_dwordx4 v168, s[12:13]
	s_add_i32 m0, s55, 0xe000
	s_nop 0
	global_load_lds_dwordx4 v170, s[12:13]
	s_waitcnt vmcnt(8)
	s_waitcnt lgkmcnt(0)
	s_barrier
	v_mfma_f32_16x16x32_bf16 v[138:141], v[26:29], v[172:175], v[138:141]
	v_mfma_f32_16x16x32_bf16 v[142:145], v[42:45], v[172:175], v[142:145]
	v_mfma_f32_16x16x32_bf16 v[126:129], v[26:29], v[180:183], v[126:129]
	v_mfma_f32_16x16x32_bf16 v[122:125], v[42:45], v[180:183], v[122:125]
	v_mfma_f32_16x16x32_bf16 v[110:113], v[26:29], v[204:207], v[110:113]
	v_mfma_f32_16x16x32_bf16 v[106:109], v[42:45], v[204:207], v[106:109]
	v_mfma_f32_16x16x32_bf16 v[94:97], v[26:29], v[212:215], v[94:97]
	v_mfma_f32_16x16x32_bf16 v[90:93], v[42:45], v[212:215], v[90:93]
	v_mfma_f32_16x16x32_bf16 v[138:141], v[30:33], v[176:179], v[138:141]
	v_mfma_f32_16x16x32_bf16 v[142:145], v[46:49], v[176:179], v[142:145]
	v_mfma_f32_16x16x32_bf16 v[126:129], v[30:33], v[200:203], v[126:129]
	v_mfma_f32_16x16x32_bf16 v[122:125], v[46:49], v[200:203], v[122:125]
	v_mfma_f32_16x16x32_bf16 v[110:113], v[30:33], v[208:211], v[110:113]
	v_mfma_f32_16x16x32_bf16 v[106:109], v[46:49], v[208:211], v[106:109]
	v_mfma_f32_16x16x32_bf16 v[94:97], v[30:33], v[216:219], v[94:97]
	v_mfma_f32_16x16x32_bf16 v[90:93], v[46:49], v[216:219], v[90:93]
	v_mfma_f32_16x16x32_bf16 v[134:137], v[146:149], v[172:175], v[134:137]
	v_mfma_f32_16x16x32_bf16 v[130:133], v[154:157], v[172:175], v[130:133]
	v_mfma_f32_16x16x32_bf16 v[118:121], v[146:149], v[180:183], v[118:121]
	v_mfma_f32_16x16x32_bf16 v[114:117], v[154:157], v[180:183], v[114:117]
	v_mfma_f32_16x16x32_bf16 v[102:105], v[146:149], v[204:207], v[102:105]
	v_mfma_f32_16x16x32_bf16 v[98:101], v[154:157], v[204:207], v[98:101]
	v_mfma_f32_16x16x32_bf16 v[86:89], v[146:149], v[212:215], v[86:89]
	v_mfma_f32_16x16x32_bf16 v[82:85], v[154:157], v[212:215], v[82:85]
	v_mfma_f32_16x16x32_bf16 v[134:137], v[150:153], v[176:179], v[134:137]
	v_mfma_f32_16x16x32_bf16 v[130:133], v[158:161], v[176:179], v[130:133]
	v_mfma_f32_16x16x32_bf16 v[118:121], v[150:153], v[200:203], v[118:121]
	v_mfma_f32_16x16x32_bf16 v[114:117], v[158:161], v[200:203], v[114:117]
	v_mfma_f32_16x16x32_bf16 v[102:105], v[150:153], v[208:211], v[102:105]
	v_mfma_f32_16x16x32_bf16 v[98:101], v[158:161], v[208:211], v[98:101]
	v_mfma_f32_16x16x32_bf16 v[86:89], v[150:153], v[216:219], v[86:89]
	v_mfma_f32_16x16x32_bf16 v[82:85], v[158:161], v[216:219], v[82:85]
	s_barrier
	s_add_i32 s65, s65, s54
	v_lshl_add_u64 v[184:185], s[44:45], 0, v[0:1]
	s_mov_b32 m0, s65
	ds_read_b128 v[172:175], v199 offset:16384
	ds_read_b128 v[176:179], v199 offset:17408
	ds_read_b128 v[180:183], v199 offset:18432
	ds_read_b128 v[200:203], v199 offset:19456
	ds_read_b128 v[204:207], v199 offset:20480
	ds_read_b128 v[208:211], v199 offset:21504
	ds_read_b128 v[212:215], v199 offset:22528
	ds_read_b128 v[216:219], v199 offset:23552
	global_load_lds_dwordx4 v[184:185], off
	s_add_i32 m0, s65, 0x2000
	v_lshl_add_u64 v[194:195], s[44:45], 0, v[162:163]
	s_add_u32 s44, s44, s28
	s_addc_u32 s45, s45, s29
	s_add_i32 s41, s41, s54
	global_load_lds_dwordx4 v[194:195], off
	v_lshl_add_u64 v[228:229], s[44:45], 0, v[0:1]
	s_mov_b32 m0, s41
	v_lshl_add_u64 v[230:231], s[44:45], 0, v[162:163]
	global_load_lds_dwordx4 v[228:229], off
	s_add_i32 m0, s41, 0x2000
	v_lshl_add_u64 v[232:233], s[14:15], 0, v[166:167]
	global_load_lds_dwordx4 v[230:231], off
	s_mov_b32 m0, s55
	v_lshl_add_u64 v[234:235], s[14:15], 0, v[164:165]
	global_load_lds_dwordx4 v[232:233], off
	s_mov_b32 m0, s56
	s_nop 0
	global_load_lds_dwordx4 v[234:235], off
	s_waitcnt vmcnt(8)
	s_waitcnt lgkmcnt(0)
	s_barrier
; #define PG8_STAGE(bufoff, gbase, voff) do { _Pragma("unroll") for (int _i = 0; _i < 2; ++_i) \
;         __builtin_amdgcn_global_load_lds((const unsigned*)((const char*)(gbase) + (voff)[_i]), (PG8_LAS unsigned*)(lds + (bufoff) + ldsw + _i * 8192), 16, 0, 0); } while (0)
; #define PG8_LDA(dst, b, h) do { _Pragma("unroll") for (int m = 0; m < 4; ++m) _Pragma("unroll") for (int k = 0; k < 2; ++k) dst[m][k] = *(const PG8_LAS bf16x8*)(lds + PG8_SA(b, h) + aoff + m * 2048 + k * 1024); } while (0)
; #define PG8_LDB(dst, b, h) do { _Pragma("unroll") for (int n = 0; n < 2; ++n) _Pragma("unroll") for (int k = 0; k < 2; ++k) dst[n][k] = *(const PG8_LAS bf16x8*)(lds + PG8_SB(b, h) + boff + n * 2048 + k * 1024); } while (0)
; #define PG8_MMA(ai, bj, At, Bt) do { __builtin_amdgcn_s_setprio(1); _Pragma("unroll") for (int m = 0; m < 4; ++m) _Pragma("unroll") for (int n = 0; n < 2; ++n) _Pragma("unroll") for (int k = 0; k < 2; ++k) \
;         acc[ai][bj][m][n] = __builtin_amdgcn_mfma_f32_16x16x32_bf16(Bt[n][k], At[m][k], acc[ai][bj][m][n], 0, 0, 0); __builtin_amdgcn_s_setprio(0); } while (0)
; #define PG8_WAIT_V(n) asm volatile("s_waitcnt vmcnt(" #n ")" ::: "memory")
; #define PG8_WAIT_L(n) asm volatile("s_waitcnt lgkmcnt(" #n ")" ::: "memory")
; #define PG8_BAR __builtin_amdgcn_s_barrier()
; #define PG8_SCHED __builtin_amdgcn_sched_barrier(0)
; template <class Epi, class Sched, bool ALIGN_EPI = false, bool SP2 = false>
; __device__ __forceinline__ void gemm_phase(PG8_LAS unsigned char* lds, const Gemm g, const Sched& S, const Epi& E, const int wv) {
;     ...
;             PG8_WAIT_V(8); PG8_WAIT_L(0); PG8_BAR; PG8_MMA(1, 0, At, B0); PG8_MMA(1, 1, At, B1); PG8_BAR; PG8_SCHED;
;             PG8_LDB(B0, 1, 0); PG8_LDB(B1, 1, 1); PG8_SCHED; PG8_LDA(At, 1, 0); PG8_STAGE(PG8_SA(0, 1), a2 + hstepA, voffA);
;             PG8_WAIT_V(8); PG8_WAIT_L(0); PG8_BAR; PG8_MMA(0, 0, At, B0); PG8_MMA(0, 1, At, B1); PG8_BAR; PG8_SCHED;
	v_mfma_f32_16x16x32_bf16 v[78:81], v[26:29], v[172:175], v[78:81]
	v_mfma_f32_16x16x32_bf16 v[74:77], v[42:45], v[172:175], v[74:77]
	v_mfma_f32_16x16x32_bf16 v[62:65], v[26:29], v[180:183], v[62:65]
	v_mfma_f32_16x16x32_bf16 v[58:61], v[42:45], v[180:183], v[58:61]
	v_mfma_f32_16x16x32_bf16 v[38:41], v[26:29], v[204:207], v[38:41]
	v_mfma_f32_16x16x32_bf16 v[34:37], v[42:45], v[204:207], v[34:37]
	v_mfma_f32_16x16x32_bf16 v[14:17], v[26:29], v[212:215], v[14:17]
	v_mfma_f32_16x16x32_bf16 v[10:13], v[42:45], v[212:215], v[10:13]
	v_mfma_f32_16x16x32_bf16 v[78:81], v[30:33], v[176:179], v[78:81]
	v_mfma_f32_16x16x32_bf16 v[74:77], v[46:49], v[176:179], v[74:77]
	v_mfma_f32_16x16x32_bf16 v[62:65], v[30:33], v[200:203], v[62:65]
	v_mfma_f32_16x16x32_bf16 v[58:61], v[46:49], v[200:203], v[58:61]
	v_mfma_f32_16x16x32_bf16 v[38:41], v[30:33], v[208:211], v[38:41]
	v_mfma_f32_16x16x32_bf16 v[34:37], v[46:49], v[208:211], v[34:37]
	v_mfma_f32_16x16x32_bf16 v[14:17], v[30:33], v[216:219], v[14:17]
	v_mfma_f32_16x16x32_bf16 v[10:13], v[46:49], v[216:219], v[10:13]
	v_mfma_f32_16x16x32_bf16 v[22:25], v[146:149], v[204:207], v[22:25]
	v_mfma_f32_16x16x32_bf16 v[18:21], v[154:157], v[204:207], v[18:21]
	v_mfma_f32_16x16x32_bf16 v[6:9], v[146:149], v[212:215], v[6:9]
	v_mfma_f32_16x16x32_bf16 v[2:5], v[154:157], v[212:215], v[2:5]
	v_mfma_f32_16x16x32_bf16 v[26:29], v[146:149], v[172:175], v[70:73]
	v_mfma_f32_16x16x32_bf16 v[30:33], v[154:157], v[172:175], v[66:69]
	v_mfma_f32_16x16x32_bf16 v[42:45], v[146:149], v[180:183], v[54:57]
	v_mfma_f32_16x16x32_bf16 v[46:49], v[154:157], v[180:183], v[50:53]
	v_mfma_f32_16x16x32_bf16 v[22:25], v[150:153], v[208:211], v[22:25]
	v_mfma_f32_16x16x32_bf16 v[18:21], v[158:161], v[208:211], v[18:21]
	v_mfma_f32_16x16x32_bf16 v[6:9], v[150:153], v[216:219], v[6:9]
	v_mfma_f32_16x16x32_bf16 v[2:5], v[158:161], v[216:219], v[2:5]
	v_mfma_f32_16x16x32_bf16 v[26:29], v[150:153], v[176:179], v[26:29]
	v_mfma_f32_16x16x32_bf16 v[30:33], v[158:161], v[176:179], v[30:33]
	v_mfma_f32_16x16x32_bf16 v[42:45], v[150:153], v[200:203], v[42:45]
	v_mfma_f32_16x16x32_bf16 v[46:49], v[158:161], v[200:203], v[46:49]
	s_barrier
	s_add_i32 s41, 0, 0x18000
	s_add_i32 s44, 0, 0x1c000
	ds_read_b128 v[50:53], v244
	ds_read_b128 v[54:57], v244 offset:1024
	ds_read_b128 v[66:69], v244 offset:2048
	ds_read_b128 v[70:73], v244 offset:3072
	ds_read_b128 v[146:149], v245
	ds_read_b128 v[150:153], v245 offset:1024
	ds_read_b128 v[154:157], v245 offset:2048
	ds_read_b128 v[158:161], v245 offset:3072
	s_add_u32 s14, s14, 0x80000
	s_addc_u32 s15, s15, 0
	s_mov_b32 m0, s57
	ds_read_b128 v[172:175], v199 offset:32768
	ds_read_b128 v[176:179], v199 offset:33792
	ds_read_b128 v[180:183], v199 offset:34816
	ds_read_b128 v[200:203], v199 offset:35840
	ds_read_b128 v[204:207], v199 offset:36864
	ds_read_b128 v[208:211], v199 offset:37888
	ds_read_b128 v[212:215], v199 offset:38912
	ds_read_b128 v[216:219], v199 offset:39936
	global_load_lds_dwordx4 v166, s[14:15]
	s_mov_b32 m0, s58
	s_nop 0
	global_load_lds_dwordx4 v164, s[14:15]
	s_waitcnt vmcnt(8)
	s_waitcnt lgkmcnt(0)
	s_barrier
	v_mfma_f32_16x16x32_bf16 v[138:141], v[50:53], v[172:175], v[138:141]
	v_mfma_f32_16x16x32_bf16 v[142:145], v[66:69], v[172:175], v[142:145]
	v_mfma_f32_16x16x32_bf16 v[126:129], v[50:53], v[180:183], v[126:129]
	v_mfma_f32_16x16x32_bf16 v[122:125], v[66:69], v[180:183], v[122:125]
	v_mfma_f32_16x16x32_bf16 v[110:113], v[50:53], v[204:207], v[110:113]
	v_mfma_f32_16x16x32_bf16 v[106:109], v[66:69], v[204:207], v[106:109]
	v_mfma_f32_16x16x32_bf16 v[94:97], v[50:53], v[212:215], v[94:97]
	v_mfma_f32_16x16x32_bf16 v[90:93], v[66:69], v[212:215], v[90:93]
	v_mfma_f32_16x16x32_bf16 v[138:141], v[54:57], v[176:179], v[138:141]
	v_mfma_f32_16x16x32_bf16 v[142:145], v[70:73], v[176:179], v[142:145]
	v_mfma_f32_16x16x32_bf16 v[126:129], v[54:57], v[200:203], v[126:129]
	v_mfma_f32_16x16x32_bf16 v[122:125], v[70:73], v[200:203], v[122:125]
	v_mfma_f32_16x16x32_bf16 v[110:113], v[54:57], v[208:211], v[110:113]
	v_mfma_f32_16x16x32_bf16 v[106:109], v[70:73], v[208:211], v[106:109]
	v_mfma_f32_16x16x32_bf16 v[94:97], v[54:57], v[216:219], v[94:97]
	v_mfma_f32_16x16x32_bf16 v[90:93], v[70:73], v[216:219], v[90:93]
	v_mfma_f32_16x16x32_bf16 v[134:137], v[146:149], v[172:175], v[134:137]
	v_mfma_f32_16x16x32_bf16 v[130:133], v[154:157], v[172:175], v[130:133]
	v_mfma_f32_16x16x32_bf16 v[118:121], v[146:149], v[180:183], v[118:121]
	v_mfma_f32_16x16x32_bf16 v[114:117], v[154:157], v[180:183], v[114:117]
	v_mfma_f32_16x16x32_bf16 v[102:105], v[146:149], v[204:207], v[102:105]
	v_mfma_f32_16x16x32_bf16 v[98:101], v[154:157], v[204:207], v[98:101]
	v_mfma_f32_16x16x32_bf16 v[86:89], v[146:149], v[212:215], v[86:89]
	v_mfma_f32_16x16x32_bf16 v[82:85], v[154:157], v[212:215], v[82:85]
	v_mfma_f32_16x16x32_bf16 v[134:137], v[150:153], v[176:179], v[134:137]
	v_mfma_f32_16x16x32_bf16 v[130:133], v[158:161], v[176:179], v[130:133]
	v_mfma_f32_16x16x32_bf16 v[118:121], v[150:153], v[200:203], v[118:121]
	v_mfma_f32_16x16x32_bf16 v[114:117], v[158:161], v[200:203], v[114:117]
	v_mfma_f32_16x16x32_bf16 v[102:105], v[150:153], v[208:211], v[102:105]
	v_mfma_f32_16x16x32_bf16 v[98:101], v[158:161], v[208:211], v[98:101]
	v_mfma_f32_16x16x32_bf16 v[86:89], v[150:153], v[216:219], v[86:89]
	v_mfma_f32_16x16x32_bf16 v[82:85], v[158:161], v[216:219], v[82:85]
	s_barrier
; #define PG8_STAGE(bufoff, gbase, voff) do { _Pragma("unroll") for (int _i = 0; _i < 2; ++_i) \
;         __builtin_amdgcn_global_load_lds((const unsigned*)((const char*)(gbase) + (voff)[_i]), (PG8_LAS unsigned*)(lds + (bufoff) + ldsw + _i * 8192), 16, 0, 0); } while (0)
; #define PG8_LDA(dst, b, h) do { _Pragma("unroll") for (int m = 0; m < 4; ++m) _Pragma("unroll") for (int k = 0; k < 2; ++k) dst[m][k] = *(const PG8_LAS bf16x8*)(lds + PG8_SA(b, h) + aoff + m * 2048 + k * 1024); } while (0)
; #define PG8_MMA(ai, bj, At, Bt) do { __builtin_amdgcn_s_setprio(1); _Pragma("unroll") for (int m = 0; m < 4; ++m) _Pragma("unroll") for (int n = 0; n < 2; ++n) _Pragma("unroll") for (int k = 0; k < 2; ++k) \
;         acc[ai][bj][m][n] = __builtin_amdgcn_mfma_f32_16x16x32_bf16(Bt[n][k], At[m][k], acc[ai][bj][m][n], 0, 0, 0); __builtin_amdgcn_s_setprio(0); } while (0)
; #define PG8_WAIT_V(n) asm volatile("s_waitcnt vmcnt(" #n ")" ::: "memory")
; #define PG8_WAIT_L(n) asm volatile("s_waitcnt lgkmcnt(" #n ")" ::: "memory")
; #define PG8_BAR __builtin_amdgcn_s_barrier()
; #define PG8_SCHED __builtin_amdgcn_sched_barrier(0)
; template <class Epi, class Sched, bool ALIGN_EPI = false, bool SP2 = false>
; __device__ __forceinline__ void gemm_phase(PG8_LAS unsigned char* lds, const Gemm g, const Sched& S, const Epi& E, const int wv) {
;     ...
;         for (int t = 0; t < nt; t += 2) {
;     ...
;             PG8_LDA(At, 1, 1); PG8_STAGE(PG8_SB(1, 0), b3, voffB); PG8_STAGE(PG8_SB(1, 1), b3 + hstepB, voffB); PG8_STAGE(PG8_SA(1, 0), a3, voffA);
;             PG8_WAIT_V(8); PG8_WAIT_L(0); PG8_BAR; PG8_MMA(1, 0, At, B0); PG8_MMA(1, 1, At, B1); PG8_BAR; PG8_SCHED;
	s_add_i32 s14, s41, s54
	s_add_i32 m0, s14, 0xffffff80
	ds_read_b128 v[172:175], v199 offset:49152
	ds_read_b128 v[176:179], v199 offset:50176
	ds_read_b128 v[180:183], v199 offset:51200
	ds_read_b128 v[200:203], v199 offset:52224
	ds_read_b128 v[204:207], v199 offset:53248
	ds_read_b128 v[208:211], v199 offset:54272
	ds_read_b128 v[212:215], v199 offset:55296
	ds_read_b128 v[216:219], v199 offset:56320
	global_load_lds_dwordx4 v[184:185], off offset:128
	s_add_i32 m0, s14, 0x1f80
	s_add_i32 s14, s44, s54
	global_load_lds_dwordx4 v[194:195], off offset:128
	s_add_i32 m0, s14, 0xffffff80
	s_nop 0
	global_load_lds_dwordx4 v[228:229], off offset:128
	s_add_i32 m0, s14, 0x1f80
	s_nop 0
	global_load_lds_dwordx4 v[230:231], off offset:128
	s_add_i32 m0, s60, 0xffffff80
	s_nop 0
	global_load_lds_dwordx4 v[232:233], off offset:128
	s_add_i32 m0, s61, 0xffffff80
	s_nop 0
	global_load_lds_dwordx4 v[234:235], off offset:128
	s_waitcnt vmcnt(8)
	s_waitcnt lgkmcnt(0)
	s_barrier
	v_mfma_f32_16x16x32_bf16 v[78:81], v[50:53], v[172:175], v[78:81]
	v_mfma_f32_16x16x32_bf16 v[74:77], v[66:69], v[172:175], v[74:77]
	v_mfma_f32_16x16x32_bf16 v[62:65], v[50:53], v[180:183], v[62:65]
	v_mfma_f32_16x16x32_bf16 v[58:61], v[66:69], v[180:183], v[58:61]
	v_mfma_f32_16x16x32_bf16 v[38:41], v[50:53], v[204:207], v[38:41]
	v_mfma_f32_16x16x32_bf16 v[34:37], v[66:69], v[204:207], v[34:37]
	v_mfma_f32_16x16x32_bf16 v[14:17], v[50:53], v[212:215], v[14:17]
	v_mfma_f32_16x16x32_bf16 v[10:13], v[66:69], v[212:215], v[10:13]
	v_mfma_f32_16x16x32_bf16 v[78:81], v[54:57], v[176:179], v[78:81]
	v_mfma_f32_16x16x32_bf16 v[74:77], v[70:73], v[176:179], v[74:77]
	v_mfma_f32_16x16x32_bf16 v[62:65], v[54:57], v[200:203], v[62:65]
	v_mfma_f32_16x16x32_bf16 v[58:61], v[70:73], v[200:203], v[58:61]
	v_mfma_f32_16x16x32_bf16 v[38:41], v[54:57], v[208:211], v[38:41]
	v_mfma_f32_16x16x32_bf16 v[34:37], v[70:73], v[208:211], v[34:37]
	v_mfma_f32_16x16x32_bf16 v[14:17], v[54:57], v[216:219], v[14:17]
	v_mfma_f32_16x16x32_bf16 v[10:13], v[70:73], v[216:219], v[10:13]
	v_mfma_f32_16x16x32_bf16 v[26:29], v[146:149], v[172:175], v[26:29]
	v_mfma_f32_16x16x32_bf16 v[70:73], v[150:153], v[176:179], v[26:29]
	v_mfma_f32_16x16x32_bf16 v[26:29], v[154:157], v[172:175], v[30:33]
	v_mfma_f32_16x16x32_bf16 v[66:69], v[158:161], v[176:179], v[26:29]
	v_mfma_f32_16x16x32_bf16 v[26:29], v[146:149], v[180:183], v[42:45]
	v_mfma_f32_16x16x32_bf16 v[54:57], v[150:153], v[200:203], v[26:29]
	v_mfma_f32_16x16x32_bf16 v[26:29], v[154:157], v[180:183], v[46:49]
	v_mfma_f32_16x16x32_bf16 v[22:25], v[146:149], v[204:207], v[22:25]
	v_mfma_f32_16x16x32_bf16 v[18:21], v[154:157], v[204:207], v[18:21]
	v_mfma_f32_16x16x32_bf16 v[6:9], v[146:149], v[212:215], v[6:9]
	v_mfma_f32_16x16x32_bf16 v[2:5], v[154:157], v[212:215], v[2:5]
	v_mfma_f32_16x16x32_bf16 v[50:53], v[158:161], v[200:203], v[26:29]
	v_mfma_f32_16x16x32_bf16 v[22:25], v[150:153], v[208:211], v[22:25]
	v_mfma_f32_16x16x32_bf16 v[18:21], v[158:161], v[208:211], v[18:21]
	v_mfma_f32_16x16x32_bf16 v[6:9], v[150:153], v[216:219], v[6:9]
	v_mfma_f32_16x16x32_bf16 v[2:5], v[158:161], v[216:219], v[2:5]
	s_barrier
	s_add_u32 s12, s12, 0x100
	s_addc_u32 s13, s13, 0
	s_add_u32 s11, s11, 0x100
	s_addc_u32 s17, s17, 0
	s_cmp_ge_i32 s40, s59
	s_mov_b32 s14, s40
	s_cbranch_scc0 .LBB0_336

; #define PG8_STAGE(bufoff, gbase, voff) do { _Pragma("unroll") for (int _i = 0; _i < 2; ++_i) \
;         __builtin_amdgcn_global_load_lds((const unsigned*)((const char*)(gbase) + (voff)[_i]), (PG8_LAS unsigned*)(lds + (bufoff) + ldsw + _i * 8192), 16, 0, 0); } while (0)
; #define PG8_LDA(dst, b, h) do { _Pragma("unroll") for (int m = 0; m < 4; ++m) _Pragma("unroll") for (int k = 0; k < 2; ++k) dst[m][k] = *(const PG8_LAS bf16x8*)(lds + PG8_SA(b, h) + aoff + m * 2048 + k * 1024); } while (0)
; #define PG8_LDB(dst, b, h) do { _Pragma("unroll") for (int n = 0; n < 2; ++n) _Pragma("unroll") for (int k = 0; k < 2; ++k) dst[n][k] = *(const PG8_LAS bf16x8*)(lds + PG8_SB(b, h) + boff + n * 2048 + k * 1024); } while (0)
; #define PG8_MMA(ai, bj, At, Bt) do { __builtin_amdgcn_s_setprio(1); _Pragma("unroll") for (int m = 0; m < 4; ++m) _Pragma("unroll") for (int n = 0; n < 2; ++n) _Pragma("unroll") for (int k = 0; k < 2; ++k) \
;         acc[ai][bj][m][n] = __builtin_amdgcn_mfma_f32_16x16x32_bf16(Bt[n][k], At[m][k], acc[ai][bj][m][n], 0, 0, 0); __builtin_amdgcn_s_setprio(0); } while (0)
; #define PG8_WAIT_V(n) asm volatile("s_waitcnt vmcnt(" #n ")" ::: "memory")
; #define PG8_WAIT_L(n) asm volatile("s_waitcnt lgkmcnt(" #n ")" ::: "memory")
; template <class Epi, class Sched, bool ALIGN_EPI = false, bool SP2 = false>
; __device__ __forceinline__ void gemm_phase(PG8_LAS unsigned char* lds, const Gemm g, const Sched& S, const Epi& E, const int wv) {
;     ...
; #pragma unroll
;     for (int a = 0; a < 2; ++a)
; #pragma unroll
;         for (int b = 0; b < 2; ++b)
; #pragma unroll
;             for (int m = 0; m < 4; ++m)
; #pragma unroll
;                 for (int n = 0; n < 2; ++n) acc[a][b][m][n] = (f32x4){0.f, 0.f, 0.f, 0.f};
;     ...
;             const bool last = (t == nt - 2);
;             const char* a1 = cA + (size_t)(t + 1) * kstep;
;             const char* a2 = last ? nA : cA + (size_t)(t + 2) * kstep; const char* b2 = last ? nB : cB + (size_t)(t + 2) * kstep;
;             const char* a3 = a2 + kstep; const char* b3 = b2 + kstep;
;             if (last && has_next) S.a_ready(nxt);
;             if constexpr (SP2) {
;             PG8_LDB(B0, 0, 0); PG8_LDB(B1, 0, 1); PG8_SCHED; PG8_LDA(At, 0, 0); PG8_STAGE(PG8_SA(1, 1), a1 + hstepA, voffA);
;             PG8_WAIT_V(8); PG8_WAIT_L(0); PG8_BAR; PG8_MMA(0, 0, At, B0); PG8_MMA(0, 1, At, B1); PG8_BAR; PG8_SCHED;
.LBB0_698:
	s_and_b64 s[44:45], s[44:45], exec
	s_cselect_b32 s31, s15, s55
	s_cselect_b32 s71, s14, s54
	s_add_u32 s44, s54, 0x80080
	s_addc_u32 s45, s55, 0
	s_add_u32 s56, s56, 0x100
	v_mov_b32_e32 v2, 0
	s_addc_u32 s57, s57, 0
	s_mov_b32 s54, 0
	v_mov_b32_e32 v3, v2
	v_pk_mov_b32 v[4:5], v[2:3], v[2:3]
	v_pk_mov_b32 v[6:7], v[2:3], v[2:3]
	v_pk_mov_b32 v[8:9], v[2:3], v[2:3]
	v_pk_mov_b32 v[18:19], v[2:3], v[2:3]
	v_pk_mov_b32 v[20:21], v[2:3], v[2:3]
	v_pk_mov_b32 v[22:23], v[2:3], v[2:3]
	v_pk_mov_b32 v[24:25], v[2:3], v[2:3]
	v_pk_mov_b32 v[34:35], v[2:3], v[2:3]
	v_pk_mov_b32 v[36:37], v[2:3], v[2:3]
	v_pk_mov_b32 v[38:39], v[2:3], v[2:3]
	v_pk_mov_b32 v[40:41], v[2:3], v[2:3]
	v_pk_mov_b32 v[50:51], v[2:3], v[2:3]
	v_pk_mov_b32 v[52:53], v[2:3], v[2:3]
	v_pk_mov_b32 v[54:55], v[2:3], v[2:3]
	v_pk_mov_b32 v[56:57], v[2:3], v[2:3]
	v_pk_mov_b32 v[10:11], v[2:3], v[2:3]
	v_pk_mov_b32 v[12:13], v[2:3], v[2:3]
	v_pk_mov_b32 v[14:15], v[2:3], v[2:3]
	v_pk_mov_b32 v[16:17], v[2:3], v[2:3]
	v_pk_mov_b32 v[26:27], v[2:3], v[2:3]
	v_pk_mov_b32 v[28:29], v[2:3], v[2:3]
	v_pk_mov_b32 v[30:31], v[2:3], v[2:3]
	v_pk_mov_b32 v[32:33], v[2:3], v[2:3]
	v_pk_mov_b32 v[42:43], v[2:3], v[2:3]
	v_pk_mov_b32 v[44:45], v[2:3], v[2:3]
	v_pk_mov_b32 v[46:47], v[2:3], v[2:3]
	v_pk_mov_b32 v[48:49], v[2:3], v[2:3]
	v_pk_mov_b32 v[58:59], v[2:3], v[2:3]
	v_pk_mov_b32 v[60:61], v[2:3], v[2:3]
	v_pk_mov_b32 v[62:63], v[2:3], v[2:3]
	v_pk_mov_b32 v[64:65], v[2:3], v[2:3]
	v_pk_mov_b32 v[66:67], v[2:3], v[2:3]
	v_pk_mov_b32 v[68:69], v[2:3], v[2:3]
	v_pk_mov_b32 v[70:71], v[2:3], v[2:3]
	v_pk_mov_b32 v[72:73], v[2:3], v[2:3]
	v_pk_mov_b32 v[82:83], v[2:3], v[2:3]
	v_pk_mov_b32 v[84:85], v[2:3], v[2:3]
	v_pk_mov_b32 v[86:87], v[2:3], v[2:3]
	v_pk_mov_b32 v[88:89], v[2:3], v[2:3]
	v_pk_mov_b32 v[98:99], v[2:3], v[2:3]
	v_pk_mov_b32 v[100:101], v[2:3], v[2:3]
	v_pk_mov_b32 v[102:103], v[2:3], v[2:3]
	v_pk_mov_b32 v[104:105], v[2:3], v[2:3]
	v_pk_mov_b32 v[118:119], v[2:3], v[2:3]
	v_pk_mov_b32 v[120:121], v[2:3], v[2:3]
	v_pk_mov_b32 v[122:123], v[2:3], v[2:3]
	v_pk_mov_b32 v[124:125], v[2:3], v[2:3]
	v_pk_mov_b32 v[74:75], v[2:3], v[2:3]
	v_pk_mov_b32 v[76:77], v[2:3], v[2:3]
	v_pk_mov_b32 v[78:79], v[2:3], v[2:3]
	v_pk_mov_b32 v[80:81], v[2:3], v[2:3]
	v_pk_mov_b32 v[90:91], v[2:3], v[2:3]
	v_pk_mov_b32 v[92:93], v[2:3], v[2:3]
	v_pk_mov_b32 v[94:95], v[2:3], v[2:3]
	v_pk_mov_b32 v[96:97], v[2:3], v[2:3]
	v_pk_mov_b32 v[106:107], v[2:3], v[2:3]
	v_pk_mov_b32 v[108:109], v[2:3], v[2:3]
	v_pk_mov_b32 v[110:111], v[2:3], v[2:3]
	v_pk_mov_b32 v[112:113], v[2:3], v[2:3]
	v_pk_mov_b32 v[130:131], v[2:3], v[2:3]
	v_pk_mov_b32 v[132:133], v[2:3], v[2:3]
	v_pk_mov_b32 v[134:135], v[2:3], v[2:3]
	v_pk_mov_b32 v[136:137], v[2:3], v[2:3]
	v_add_u32_e32 v190, 0x10000, v230
	v_add_u32_e32 v191, 0x14000, v230
	v_add_u32_e32 v192, 0x18000, v230
	v_add_u32_e32 v193, 0x1c000, v230
.LBB0_699:
	s_add_i32 s72, s54, 2
	s_add_u32 s73, s44, 0xfff80080
	s_addc_u32 s55, s45, -1
	s_add_i32 s76, 0, 0x10000
	s_cmp_eq_u32 s66, s54
	s_cselect_b32 s55, s31, s55
	s_cselect_b32 s54, s71, s73
	s_cselect_b32 s75, s13, s57
	s_cselect_b32 s74, s12, s56
	s_add_i32 s73, 0, 0x14000
	ds_read_b128 v[126:129], v190
	ds_read_b128 v[138:141], v190 offset:1024
	ds_read_b128 v[142:145], v190 offset:2048
	ds_read_b128 v[146:149], v190 offset:3072
	ds_read_b128 v[150:153], v191
	ds_read_b128 v[154:157], v191 offset:1024
	ds_read_b128 v[158:161], v191 offset:2048
	ds_read_b128 v[162:165], v191 offset:3072
	s_add_i32 m0, s59, 0xc000
	ds_read_b128 v[166:169], v235
	ds_read_b128 v[170:173], v235 offset:1024
	ds_read_b128 v[174:177], v235 offset:2048
	ds_read_b128 v[178:181], v235 offset:3072
	ds_read_b128 v[182:185], v235 offset:4096
	ds_read_b128 v[204:207], v235 offset:5120
	ds_read_b128 v[208:211], v235 offset:6144
	ds_read_b128 v[212:215], v235 offset:7168
	global_load_lds_dwordx4 v200, s[44:45]
	s_add_i32 m0, s59, 0xe000
	s_nop 0
	global_load_lds_dwordx4 v202, s[44:45]
	s_waitcnt vmcnt(8)
	s_waitcnt lgkmcnt(0)
	s_barrier
	v_mfma_f32_16x16x32_bf16 v[134:137], v[126:129], v[166:169], v[134:137]
	v_mfma_f32_16x16x32_bf16 v[130:133], v[142:145], v[166:169], v[130:133]
	v_mfma_f32_16x16x32_bf16 v[110:113], v[126:129], v[174:177], v[110:113]
	v_mfma_f32_16x16x32_bf16 v[106:109], v[142:145], v[174:177], v[106:109]
	v_mfma_f32_16x16x32_bf16 v[94:97], v[126:129], v[182:185], v[94:97]
	v_mfma_f32_16x16x32_bf16 v[90:93], v[142:145], v[182:185], v[90:93]
	v_mfma_f32_16x16x32_bf16 v[78:81], v[126:129], v[208:211], v[78:81]
	v_mfma_f32_16x16x32_bf16 v[74:77], v[142:145], v[208:211], v[74:77]
	v_mfma_f32_16x16x32_bf16 v[134:137], v[138:141], v[170:173], v[134:137]
	v_mfma_f32_16x16x32_bf16 v[130:133], v[146:149], v[170:173], v[130:133]
	v_mfma_f32_16x16x32_bf16 v[110:113], v[138:141], v[178:181], v[110:113]
	v_mfma_f32_16x16x32_bf16 v[106:109], v[146:149], v[178:181], v[106:109]
	v_mfma_f32_16x16x32_bf16 v[94:97], v[138:141], v[204:207], v[94:97]
	v_mfma_f32_16x16x32_bf16 v[90:93], v[146:149], v[204:207], v[90:93]
	v_mfma_f32_16x16x32_bf16 v[78:81], v[138:141], v[212:215], v[78:81]
	v_mfma_f32_16x16x32_bf16 v[74:77], v[146:149], v[212:215], v[74:77]
	v_mfma_f32_16x16x32_bf16 v[122:125], v[150:153], v[166:169], v[122:125]
	v_mfma_f32_16x16x32_bf16 v[116:119], v[158:161], v[166:169], v[118:121]
	v_mfma_f32_16x16x32_bf16 v[102:105], v[150:153], v[174:177], v[102:105]
	v_mfma_f32_16x16x32_bf16 v[98:101], v[158:161], v[174:177], v[98:101]
	v_mfma_f32_16x16x32_bf16 v[86:89], v[150:153], v[182:185], v[86:89]
	v_mfma_f32_16x16x32_bf16 v[82:85], v[158:161], v[182:185], v[82:85]
	v_mfma_f32_16x16x32_bf16 v[70:73], v[150:153], v[208:211], v[70:73]
	v_mfma_f32_16x16x32_bf16 v[66:69], v[158:161], v[208:211], v[66:69]
	v_mfma_f32_16x16x32_bf16 v[122:125], v[154:157], v[170:173], v[122:125]
	v_mfma_f32_16x16x32_bf16 v[116:119], v[162:165], v[170:173], v[116:119]
	v_mfma_f32_16x16x32_bf16 v[102:105], v[154:157], v[178:181], v[102:105]
	v_mfma_f32_16x16x32_bf16 v[98:101], v[162:165], v[178:181], v[98:101]
	v_mfma_f32_16x16x32_bf16 v[86:89], v[154:157], v[204:207], v[86:89]
	v_mfma_f32_16x16x32_bf16 v[82:85], v[162:165], v[204:207], v[82:85]
	v_mfma_f32_16x16x32_bf16 v[70:73], v[154:157], v[212:215], v[70:73]
	v_mfma_f32_16x16x32_bf16 v[66:69], v[162:165], v[212:215], v[66:69]
	s_barrier
; #define PG8_STAGE(bufoff, gbase, voff) do { _Pragma("unroll") for (int _i = 0; _i < 2; ++_i) \
;         __builtin_amdgcn_global_load_lds((const unsigned*)((const char*)(gbase) + (voff)[_i]), (PG8_LAS unsigned*)(lds + (bufoff) + ldsw + _i * 8192), 16, 0, 0); } while (0)
; #define PG8_LDA(dst, b, h) do { _Pragma("unroll") for (int m = 0; m < 4; ++m) _Pragma("unroll") for (int k = 0; k < 2; ++k) dst[m][k] = *(const PG8_LAS bf16x8*)(lds + PG8_SA(b, h) + aoff + m * 2048 + k * 1024); } while (0)
; #define PG8_LDB(dst, b, h) do { _Pragma("unroll") for (int n = 0; n < 2; ++n) _Pragma("unroll") for (int k = 0; k < 2; ++k) dst[n][k] = *(const PG8_LAS bf16x8*)(lds + PG8_SB(b, h) + boff + n * 2048 + k * 1024); } while (0)
; #define PG8_MMA(ai, bj, At, Bt) do { __builtin_amdgcn_s_setprio(1); _Pragma("unroll") for (int m = 0; m < 4; ++m) _Pragma("unroll") for (int n = 0; n < 2; ++n) _Pragma("unroll") for (int k = 0; k < 2; ++k) \
;         acc[ai][bj][m][n] = __builtin_amdgcn_mfma_f32_16x16x32_bf16(Bt[n][k], At[m][k], acc[ai][bj][m][n], 0, 0, 0); __builtin_amdgcn_s_setprio(0); } while (0)
; #define PG8_WAIT_V(n) asm volatile("s_waitcnt vmcnt(" #n ")" ::: "memory")
; #define PG8_WAIT_L(n) asm volatile("s_waitcnt lgkmcnt(" #n ")" ::: "memory")
; #define PG8_BAR __builtin_amdgcn_s_barrier()
; #define PG8_SCHED __builtin_amdgcn_sched_barrier(0)
; template <class Epi, class Sched, bool ALIGN_EPI = false, bool SP2 = false>
; __device__ __forceinline__ void gemm_phase(PG8_LAS unsigned char* lds, const Gemm g, const Sched& S, const Epi& E, const int wv) {
;     ...
;             PG8_LDA(At, 0, 1); PG8_STAGE(PG8_SB(0, 0), b2, voffB); PG8_STAGE(PG8_SB(0, 1), b2 + hstepB, voffB); PG8_STAGE(PG8_SA(0, 0), a2, voffA);
;             PG8_WAIT_V(8); PG8_WAIT_L(0); PG8_BAR; PG8_MMA(1, 0, At, B0); PG8_MMA(1, 1, At, B1); PG8_BAR; PG8_SCHED;
;             PG8_LDB(B0, 1, 0); PG8_LDB(B1, 1, 1); PG8_SCHED; PG8_LDA(At, 1, 0); PG8_STAGE(PG8_SA(0, 1), a2 + hstepA, voffA);
;             PG8_WAIT_V(8); PG8_WAIT_L(0); PG8_BAR; PG8_MMA(0, 0, At, B0); PG8_MMA(0, 1, At, B1); PG8_BAR; PG8_SCHED;
	s_add_i32 s76, s76, s53
	v_lshl_add_u64 v[216:217], s[74:75], 0, v[0:1]
	s_mov_b32 m0, s76
	ds_read_b128 v[166:169], v235 offset:16384
	ds_read_b128 v[170:173], v235 offset:17408
	ds_read_b128 v[174:177], v235 offset:18432
	ds_read_b128 v[178:181], v235 offset:19456
	ds_read_b128 v[182:185], v235 offset:20480
	ds_read_b128 v[204:207], v235 offset:21504
	ds_read_b128 v[208:211], v235 offset:22528
	ds_read_b128 v[212:215], v235 offset:23552
	global_load_lds_dwordx4 v[216:217], off
	s_add_i32 m0, s76, 0x2000
	v_lshl_add_u64 v[218:219], s[74:75], 0, v[198:199]
	s_add_u32 s74, s74, s34
	s_addc_u32 s75, s75, s35
	s_add_i32 s73, s73, s53
	global_load_lds_dwordx4 v[218:219], off
	v_lshl_add_u64 v[236:237], s[74:75], 0, v[0:1]
	s_mov_b32 m0, s73
	v_lshl_add_u64 v[238:239], s[74:75], 0, v[198:199]
	global_load_lds_dwordx4 v[236:237], off
	s_add_i32 m0, s73, 0x2000
	v_lshl_add_u64 v[240:241], s[54:55], 0, v[194:195]
	global_load_lds_dwordx4 v[238:239], off
	s_mov_b32 m0, s59
	v_lshl_add_u64 v[242:243], s[54:55], 0, v[196:197]
	global_load_lds_dwordx4 v[240:241], off
	s_mov_b32 m0, s60
	s_nop 0
	global_load_lds_dwordx4 v[242:243], off
	s_waitcnt vmcnt(8)
	s_waitcnt lgkmcnt(0)
	s_barrier
	v_mfma_f32_16x16x32_bf16 v[62:65], v[126:129], v[166:169], v[62:65]
	v_mfma_f32_16x16x32_bf16 v[58:61], v[142:145], v[166:169], v[58:61]
	v_mfma_f32_16x16x32_bf16 v[46:49], v[126:129], v[174:177], v[46:49]
	v_mfma_f32_16x16x32_bf16 v[42:45], v[142:145], v[174:177], v[42:45]
	v_mfma_f32_16x16x32_bf16 v[30:33], v[126:129], v[182:185], v[30:33]
	v_mfma_f32_16x16x32_bf16 v[26:29], v[142:145], v[182:185], v[26:29]
	v_mfma_f32_16x16x32_bf16 v[14:17], v[126:129], v[208:211], v[14:17]
	v_mfma_f32_16x16x32_bf16 v[10:13], v[142:145], v[208:211], v[10:13]
	v_mfma_f32_16x16x32_bf16 v[62:65], v[138:141], v[170:173], v[62:65]
	v_mfma_f32_16x16x32_bf16 v[58:61], v[146:149], v[170:173], v[58:61]
	v_mfma_f32_16x16x32_bf16 v[46:49], v[138:141], v[178:181], v[46:49]
	v_mfma_f32_16x16x32_bf16 v[42:45], v[146:149], v[178:181], v[42:45]
	v_mfma_f32_16x16x32_bf16 v[30:33], v[138:141], v[204:207], v[30:33]
	v_mfma_f32_16x16x32_bf16 v[26:29], v[146:149], v[204:207], v[26:29]
	v_mfma_f32_16x16x32_bf16 v[14:17], v[138:141], v[212:215], v[14:17]
	v_mfma_f32_16x16x32_bf16 v[10:13], v[146:149], v[212:215], v[10:13]
	v_mfma_f32_16x16x32_bf16 v[54:57], v[150:153], v[166:169], v[54:57]
	v_mfma_f32_16x16x32_bf16 v[50:53], v[158:161], v[166:169], v[50:53]
	v_mfma_f32_16x16x32_bf16 v[38:41], v[150:153], v[174:177], v[38:41]
	v_mfma_f32_16x16x32_bf16 v[34:37], v[158:161], v[174:177], v[34:37]
	v_mfma_f32_16x16x32_bf16 v[22:25], v[150:153], v[182:185], v[22:25]
	v_mfma_f32_16x16x32_bf16 v[18:21], v[158:161], v[182:185], v[18:21]
	v_mfma_f32_16x16x32_bf16 v[6:9], v[150:153], v[208:211], v[6:9]
	v_mfma_f32_16x16x32_bf16 v[2:5], v[158:161], v[208:211], v[2:5]
	v_mfma_f32_16x16x32_bf16 v[54:57], v[154:157], v[170:173], v[54:57]
	v_mfma_f32_16x16x32_bf16 v[50:53], v[162:165], v[170:173], v[50:53]
	v_mfma_f32_16x16x32_bf16 v[38:41], v[154:157], v[178:181], v[38:41]
	v_mfma_f32_16x16x32_bf16 v[34:37], v[162:165], v[178:181], v[34:37]
	v_mfma_f32_16x16x32_bf16 v[22:25], v[154:157], v[204:207], v[22:25]
	v_mfma_f32_16x16x32_bf16 v[18:21], v[162:165], v[204:207], v[18:21]
	v_mfma_f32_16x16x32_bf16 v[6:9], v[154:157], v[212:215], v[6:9]
	v_mfma_f32_16x16x32_bf16 v[2:5], v[162:165], v[212:215], v[2:5]
	s_barrier
	s_add_i32 s73, 0, 0x18000
	s_add_i32 s74, 0, 0x1c000
	ds_read_b128 v[126:129], v192
	ds_read_b128 v[138:141], v192 offset:1024
	ds_read_b128 v[142:145], v192 offset:2048
	ds_read_b128 v[146:149], v192 offset:3072
	ds_read_b128 v[150:153], v193
	ds_read_b128 v[154:157], v193 offset:1024
	ds_read_b128 v[158:161], v193 offset:2048
	ds_read_b128 v[162:165], v193 offset:3072
	s_add_u32 s54, s54, 0x80000
	s_addc_u32 s55, s55, 0
	s_mov_b32 m0, s61
	ds_read_b128 v[166:169], v235 offset:32768
	ds_read_b128 v[170:173], v235 offset:33792
	ds_read_b128 v[174:177], v235 offset:34816
	ds_read_b128 v[178:181], v235 offset:35840
	ds_read_b128 v[182:185], v235 offset:36864
	ds_read_b128 v[204:207], v235 offset:37888
	ds_read_b128 v[208:211], v235 offset:38912
	ds_read_b128 v[212:215], v235 offset:39936
	global_load_lds_dwordx4 v194, s[54:55]
	s_mov_b32 m0, s62
	s_nop 0
	global_load_lds_dwordx4 v196, s[54:55]
	s_waitcnt vmcnt(8)
	s_waitcnt lgkmcnt(0)
	s_barrier
; #define PG8_STAGE(bufoff, gbase, voff) do { _Pragma("unroll") for (int _i = 0; _i < 2; ++_i) \
;         __builtin_amdgcn_global_load_lds((const unsigned*)((const char*)(gbase) + (voff)[_i]), (PG8_LAS unsigned*)(lds + (bufoff) + ldsw + _i * 8192), 16, 0, 0); } while (0)
; #define PG8_LDA(dst, b, h) do { _Pragma("unroll") for (int m = 0; m < 4; ++m) _Pragma("unroll") for (int k = 0; k < 2; ++k) dst[m][k] = *(const PG8_LAS bf16x8*)(lds + PG8_SA(b, h) + aoff + m * 2048 + k * 1024); } while (0)
; #define PG8_MMA(ai, bj, At, Bt) do { __builtin_amdgcn_s_setprio(1); _Pragma("unroll") for (int m = 0; m < 4; ++m) _Pragma("unroll") for (int n = 0; n < 2; ++n) _Pragma("unroll") for (int k = 0; k < 2; ++k) \
;         acc[ai][bj][m][n] = __builtin_amdgcn_mfma_f32_16x16x32_bf16(Bt[n][k], At[m][k], acc[ai][bj][m][n], 0, 0, 0); __builtin_amdgcn_s_setprio(0); } while (0)
; #define PG8_WAIT_V(n) asm volatile("s_waitcnt vmcnt(" #n ")" ::: "memory")
; #define PG8_WAIT_L(n) asm volatile("s_waitcnt lgkmcnt(" #n ")" ::: "memory")
; #define PG8_BAR __builtin_amdgcn_s_barrier()
; #define PG8_SCHED __builtin_amdgcn_sched_barrier(0)
; template <class Epi, class Sched, bool ALIGN_EPI = false, bool SP2 = false>
; __device__ __forceinline__ void gemm_phase(PG8_LAS unsigned char* lds, const Gemm g, const Sched& S, const Epi& E, const int wv) {
;     ...
;         for (int t = 0; t < nt; t += 2) {
;     ...
;             PG8_WAIT_V(8); PG8_WAIT_L(0); PG8_BAR; PG8_MMA(0, 0, At, B0); PG8_MMA(0, 1, At, B1); PG8_BAR; PG8_SCHED;
;             PG8_LDA(At, 1, 1); PG8_STAGE(PG8_SB(1, 0), b3, voffB); PG8_STAGE(PG8_SB(1, 1), b3 + hstepB, voffB); PG8_STAGE(PG8_SA(1, 0), a3, voffA);
;             PG8_WAIT_V(8); PG8_WAIT_L(0); PG8_BAR; PG8_MMA(1, 0, At, B0); PG8_MMA(1, 1, At, B1); PG8_BAR; PG8_SCHED;
	v_mfma_f32_16x16x32_bf16 v[134:137], v[126:129], v[166:169], v[134:137]
	v_mfma_f32_16x16x32_bf16 v[130:133], v[142:145], v[166:169], v[130:133]
	v_mfma_f32_16x16x32_bf16 v[110:113], v[126:129], v[174:177], v[110:113]
	v_mfma_f32_16x16x32_bf16 v[106:109], v[142:145], v[174:177], v[106:109]
	v_mfma_f32_16x16x32_bf16 v[94:97], v[126:129], v[182:185], v[94:97]
	v_mfma_f32_16x16x32_bf16 v[90:93], v[142:145], v[182:185], v[90:93]
	v_mfma_f32_16x16x32_bf16 v[78:81], v[126:129], v[208:211], v[78:81]
	v_mfma_f32_16x16x32_bf16 v[74:77], v[142:145], v[208:211], v[74:77]
	v_mfma_f32_16x16x32_bf16 v[134:137], v[138:141], v[170:173], v[134:137]
	v_mfma_f32_16x16x32_bf16 v[130:133], v[146:149], v[170:173], v[130:133]
	v_mfma_f32_16x16x32_bf16 v[110:113], v[138:141], v[178:181], v[110:113]
	v_mfma_f32_16x16x32_bf16 v[106:109], v[146:149], v[178:181], v[106:109]
	v_mfma_f32_16x16x32_bf16 v[94:97], v[138:141], v[204:207], v[94:97]
	v_mfma_f32_16x16x32_bf16 v[90:93], v[146:149], v[204:207], v[90:93]
	v_mfma_f32_16x16x32_bf16 v[78:81], v[138:141], v[212:215], v[78:81]
	v_mfma_f32_16x16x32_bf16 v[74:77], v[146:149], v[212:215], v[74:77]
	v_mfma_f32_16x16x32_bf16 v[120:123], v[150:153], v[166:169], v[122:125]
	v_mfma_f32_16x16x32_bf16 v[116:119], v[158:161], v[166:169], v[116:119]
	v_mfma_f32_16x16x32_bf16 v[102:105], v[150:153], v[174:177], v[102:105]
	v_mfma_f32_16x16x32_bf16 v[98:101], v[158:161], v[174:177], v[98:101]
	v_mfma_f32_16x16x32_bf16 v[86:89], v[150:153], v[182:185], v[86:89]
	v_mfma_f32_16x16x32_bf16 v[82:85], v[158:161], v[182:185], v[82:85]
	v_mfma_f32_16x16x32_bf16 v[70:73], v[150:153], v[208:211], v[70:73]
	v_mfma_f32_16x16x32_bf16 v[66:69], v[158:161], v[208:211], v[66:69]
	v_mfma_f32_16x16x32_bf16 v[122:125], v[154:157], v[170:173], v[120:123]
	v_mfma_f32_16x16x32_bf16 v[118:121], v[162:165], v[170:173], v[116:119]
	v_mfma_f32_16x16x32_bf16 v[102:105], v[154:157], v[178:181], v[102:105]
	v_mfma_f32_16x16x32_bf16 v[98:101], v[162:165], v[178:181], v[98:101]
	v_mfma_f32_16x16x32_bf16 v[86:89], v[154:157], v[204:207], v[86:89]
	v_mfma_f32_16x16x32_bf16 v[82:85], v[162:165], v[204:207], v[82:85]
	v_mfma_f32_16x16x32_bf16 v[70:73], v[154:157], v[212:215], v[70:73]
	v_mfma_f32_16x16x32_bf16 v[66:69], v[162:165], v[212:215], v[66:69]
	s_barrier
	s_add_i32 s54, s73, s53
	s_add_i32 m0, s54, 0xffffff80
	ds_read_b128 v[166:169], v235 offset:49152
	ds_read_b128 v[170:173], v235 offset:50176
	ds_read_b128 v[174:177], v235 offset:51200
	ds_read_b128 v[178:181], v235 offset:52224
	ds_read_b128 v[182:185], v235 offset:53248
	ds_read_b128 v[204:207], v235 offset:54272
	ds_read_b128 v[208:211], v235 offset:55296
	ds_read_b128 v[212:215], v235 offset:56320
	global_load_lds_dwordx4 v[216:217], off offset:128
	s_add_i32 m0, s54, 0x1f80
	s_add_i32 s54, s74, s53
	global_load_lds_dwordx4 v[218:219], off offset:128
	s_add_i32 m0, s54, 0xffffff80
	s_nop 0
	global_load_lds_dwordx4 v[236:237], off offset:128
	s_add_i32 m0, s54, 0x1f80
	s_nop 0
	global_load_lds_dwordx4 v[238:239], off offset:128
	s_add_i32 m0, s64, 0xffffff80
	s_nop 0
	global_load_lds_dwordx4 v[240:241], off offset:128
	s_add_i32 m0, s65, 0xffffff80
	s_nop 0
	global_load_lds_dwordx4 v[242:243], off offset:128
	s_waitcnt vmcnt(8)
	s_waitcnt lgkmcnt(0)
	s_barrier
	v_mfma_f32_16x16x32_bf16 v[62:65], v[126:129], v[166:169], v[62:65]
	v_mfma_f32_16x16x32_bf16 v[58:61], v[142:145], v[166:169], v[58:61]
	v_mfma_f32_16x16x32_bf16 v[46:49], v[126:129], v[174:177], v[46:49]
	v_mfma_f32_16x16x32_bf16 v[42:45], v[142:145], v[174:177], v[42:45]
	v_mfma_f32_16x16x32_bf16 v[30:33], v[126:129], v[182:185], v[30:33]
	v_mfma_f32_16x16x32_bf16 v[26:29], v[142:145], v[182:185], v[26:29]
	v_mfma_f32_16x16x32_bf16 v[14:17], v[126:129], v[208:211], v[14:17]
	v_mfma_f32_16x16x32_bf16 v[10:13], v[142:145], v[208:211], v[10:13]
	v_mfma_f32_16x16x32_bf16 v[62:65], v[138:141], v[170:173], v[62:65]
	v_mfma_f32_16x16x32_bf16 v[58:61], v[146:149], v[170:173], v[58:61]
	v_mfma_f32_16x16x32_bf16 v[46:49], v[138:141], v[178:181], v[46:49]
	v_mfma_f32_16x16x32_bf16 v[42:45], v[146:149], v[178:181], v[42:45]
	v_mfma_f32_16x16x32_bf16 v[30:33], v[138:141], v[204:207], v[30:33]
	v_mfma_f32_16x16x32_bf16 v[26:29], v[146:149], v[204:207], v[26:29]
	v_mfma_f32_16x16x32_bf16 v[14:17], v[138:141], v[212:215], v[14:17]
	v_mfma_f32_16x16x32_bf16 v[10:13], v[146:149], v[212:215], v[10:13]
	v_mfma_f32_16x16x32_bf16 v[54:57], v[150:153], v[166:169], v[54:57]
	v_mfma_f32_16x16x32_bf16 v[50:53], v[158:161], v[166:169], v[50:53]
	v_mfma_f32_16x16x32_bf16 v[38:41], v[150:153], v[174:177], v[38:41]
	v_mfma_f32_16x16x32_bf16 v[34:37], v[158:161], v[174:177], v[34:37]
	v_mfma_f32_16x16x32_bf16 v[22:25], v[150:153], v[182:185], v[22:25]
	v_mfma_f32_16x16x32_bf16 v[18:21], v[158:161], v[182:185], v[18:21]
	v_mfma_f32_16x16x32_bf16 v[6:9], v[150:153], v[208:211], v[6:9]
	v_mfma_f32_16x16x32_bf16 v[2:5], v[158:161], v[208:211], v[2:5]
	v_mfma_f32_16x16x32_bf16 v[54:57], v[154:157], v[170:173], v[54:57]
	v_mfma_f32_16x16x32_bf16 v[50:53], v[162:165], v[170:173], v[50:53]
	v_mfma_f32_16x16x32_bf16 v[38:41], v[154:157], v[178:181], v[38:41]
	v_mfma_f32_16x16x32_bf16 v[34:37], v[162:165], v[178:181], v[34:37]
	v_mfma_f32_16x16x32_bf16 v[22:25], v[154:157], v[204:207], v[22:25]
	v_mfma_f32_16x16x32_bf16 v[18:21], v[162:165], v[204:207], v[18:21]
	v_mfma_f32_16x16x32_bf16 v[6:9], v[154:157], v[212:215], v[6:9]
	v_mfma_f32_16x16x32_bf16 v[2:5], v[162:165], v[212:215], v[2:5]
	s_barrier
	s_add_u32 s44, s44, 0x100
	s_addc_u32 s45, s45, 0
	s_add_u32 s56, s56, 0x100
	s_addc_u32 s57, s57, 0
	s_cmp_ge_i32 s72, s63
	s_mov_b32 s54, s72
	s_cbranch_scc0 .LBB0_699
	s_movk_i32 s75, 0x2000
	s_mov_b32 s72, 0x10000
	s_mov_b32 s73, 0x12000
	s_mov_b32 s74, 0x14000
	s_mov_b32 s71, 0x3f317217
	s_and_b64 vcc, exec, s[48:49]
	s_cbranch_vccz .LBB0_673

; #define PG8_STAGE(bufoff, gbase, voff) do { _Pragma("unroll") for (int _i = 0; _i < 2; ++_i) \
;         __builtin_amdgcn_global_load_lds((const unsigned*)((const char*)(gbase) + (voff)[_i]), (PG8_LAS unsigned*)(lds + (bufoff) + ldsw + _i * 8192), 16, 0, 0); } while (0)
; #define PG8_LDA(dst, b, h) do { _Pragma("unroll") for (int m = 0; m < 4; ++m) _Pragma("unroll") for (int k = 0; k < 2; ++k) dst[m][k] = *(const PG8_LAS bf16x8*)(lds + PG8_SA(b, h) + aoff + m * 2048 + k * 1024); } while (0)
; #define PG8_LDB(dst, b, h) do { _Pragma("unroll") for (int n = 0; n < 2; ++n) _Pragma("unroll") for (int k = 0; k < 2; ++k) dst[n][k] = *(const PG8_LAS bf16x8*)(lds + PG8_SB(b, h) + boff + n * 2048 + k * 1024); } while (0)
; #define PG8_MMA(ai, bj, At, Bt) do { __builtin_amdgcn_s_setprio(1); _Pragma("unroll") for (int m = 0; m < 4; ++m) _Pragma("unroll") for (int n = 0; n < 2; ++n) _Pragma("unroll") for (int k = 0; k < 2; ++k) \
;         acc[ai][bj][m][n] = __builtin_amdgcn_mfma_f32_16x16x32_bf16(Bt[n][k], At[m][k], acc[ai][bj][m][n], 0, 0, 0); __builtin_amdgcn_s_setprio(0); } while (0)
; #define PG8_WAIT_V(n) asm volatile("s_waitcnt vmcnt(" #n ")" ::: "memory")
; #define PG8_WAIT_L(n) asm volatile("s_waitcnt lgkmcnt(" #n ")" ::: "memory")
; template <class Epi, class Sched, bool ALIGN_EPI = false, bool SP2 = false>
; __device__ __forceinline__ void gemm_phase(PG8_LAS unsigned char* lds, const Gemm g, const Sched& S, const Epi& E, const int wv) {
;     ...
; #pragma unroll
;     for (int a = 0; a < 2; ++a)
; #pragma unroll
;         for (int b = 0; b < 2; ++b)
; #pragma unroll
;             for (int m = 0; m < 4; ++m)
; #pragma unroll
;                 for (int n = 0; n < 2; ++n) acc[a][b][m][n] = (f32x4){0.f, 0.f, 0.f, 0.f};
;     ...
;             const bool last = (t == nt - 2);
;             const char* a1 = cA + (size_t)(t + 1) * kstep;
;             const char* a2 = last ? nA : cA + (size_t)(t + 2) * kstep; const char* b2 = last ? nB : cB + (size_t)(t + 2) * kstep;
;             const char* a3 = a2 + kstep; const char* b3 = b2 + kstep;
;             if (last && has_next) S.a_ready(nxt);
;             if constexpr (SP2) {
;             PG8_LDB(B0, 0, 0); PG8_LDB(B1, 0, 1); PG8_SCHED; PG8_LDA(At, 0, 0); PG8_STAGE(PG8_SA(1, 1), a1 + hstepA, voffA);
;             PG8_WAIT_V(8); PG8_WAIT_L(0); PG8_BAR; PG8_MMA(0, 0, At, B0); PG8_MMA(0, 1, At, B1); PG8_BAR; PG8_SCHED;
.LBB0_808:
	s_and_b64 s[14:15], s[46:47], exec
	s_cselect_b32 s11, s91, s49
	s_cselect_b32 s13, s90, s48
	s_add_u32 s35, s52, 0x100
	v_mov_b32_e32 v18, 0
	s_addc_u32 s51, s53, 0
	s_mov_b32 s46, 0
	v_mov_b32_e32 v19, v18
	v_pk_mov_b32 v[20:21], v[18:19], v[18:19]
	v_pk_mov_b32 v[90:91], v[18:19], v[18:19]
	v_pk_mov_b32 v[92:93], v[18:19], v[18:19]
	v_pk_mov_b32 v[22:23], v[18:19], v[18:19]
	v_pk_mov_b32 v[24:25], v[18:19], v[18:19]
	v_pk_mov_b32 v[94:95], v[18:19], v[18:19]
	v_pk_mov_b32 v[96:97], v[18:19], v[18:19]
	v_pk_mov_b32 v[2:3], v[18:19], v[18:19]
	v_pk_mov_b32 v[4:5], v[18:19], v[18:19]
	v_pk_mov_b32 v[66:67], v[18:19], v[18:19]
	v_pk_mov_b32 v[68:69], v[18:19], v[18:19]
	v_pk_mov_b32 v[10:11], v[18:19], v[18:19]
	v_pk_mov_b32 v[12:13], v[18:19], v[18:19]
	v_pk_mov_b32 v[82:83], v[18:19], v[18:19]
	v_pk_mov_b32 v[84:85], v[18:19], v[18:19]
	v_pk_mov_b32 v[26:27], v[18:19], v[18:19]
	v_pk_mov_b32 v[28:29], v[18:19], v[18:19]
	v_pk_mov_b32 v[98:99], v[18:19], v[18:19]
	v_pk_mov_b32 v[100:101], v[18:19], v[18:19]
	v_pk_mov_b32 v[30:31], v[18:19], v[18:19]
	v_pk_mov_b32 v[32:33], v[18:19], v[18:19]
	v_pk_mov_b32 v[102:103], v[18:19], v[18:19]
	v_pk_mov_b32 v[104:105], v[18:19], v[18:19]
	v_pk_mov_b32 v[6:7], v[18:19], v[18:19]
	v_pk_mov_b32 v[8:9], v[18:19], v[18:19]
	v_pk_mov_b32 v[70:71], v[18:19], v[18:19]
	v_pk_mov_b32 v[72:73], v[18:19], v[18:19]
	v_pk_mov_b32 v[14:15], v[18:19], v[18:19]
	v_pk_mov_b32 v[16:17], v[18:19], v[18:19]
	v_pk_mov_b32 v[86:87], v[18:19], v[18:19]
	v_pk_mov_b32 v[88:89], v[18:19], v[18:19]
	v_pk_mov_b32 v[50:51], v[18:19], v[18:19]
	v_pk_mov_b32 v[52:53], v[18:19], v[18:19]
	v_pk_mov_b32 v[122:123], v[18:19], v[18:19]
	v_pk_mov_b32 v[124:125], v[18:19], v[18:19]
	v_pk_mov_b32 v[54:55], v[18:19], v[18:19]
	v_pk_mov_b32 v[56:57], v[18:19], v[18:19]
	v_pk_mov_b32 v[126:127], v[18:19], v[18:19]
	v_pk_mov_b32 v[128:129], v[18:19], v[18:19]
	v_pk_mov_b32 v[34:35], v[18:19], v[18:19]
	v_pk_mov_b32 v[36:37], v[18:19], v[18:19]
	v_pk_mov_b32 v[106:107], v[18:19], v[18:19]
	v_pk_mov_b32 v[108:109], v[18:19], v[18:19]
	v_pk_mov_b32 v[42:43], v[18:19], v[18:19]
	v_pk_mov_b32 v[44:45], v[18:19], v[18:19]
	v_pk_mov_b32 v[114:115], v[18:19], v[18:19]
	v_pk_mov_b32 v[116:117], v[18:19], v[18:19]
	v_pk_mov_b32 v[58:59], v[18:19], v[18:19]
	v_pk_mov_b32 v[60:61], v[18:19], v[18:19]
	v_pk_mov_b32 v[130:131], v[18:19], v[18:19]
	v_pk_mov_b32 v[132:133], v[18:19], v[18:19]
	v_pk_mov_b32 v[62:63], v[18:19], v[18:19]
	v_pk_mov_b32 v[64:65], v[18:19], v[18:19]
	v_pk_mov_b32 v[134:135], v[18:19], v[18:19]
	v_pk_mov_b32 v[136:137], v[18:19], v[18:19]
	v_pk_mov_b32 v[38:39], v[18:19], v[18:19]
	v_pk_mov_b32 v[40:41], v[18:19], v[18:19]
	v_pk_mov_b32 v[110:111], v[18:19], v[18:19]
	v_pk_mov_b32 v[112:113], v[18:19], v[18:19]
	v_pk_mov_b32 v[46:47], v[18:19], v[18:19]
	v_pk_mov_b32 v[48:49], v[18:19], v[18:19]
	v_pk_mov_b32 v[118:119], v[18:19], v[18:19]
	v_pk_mov_b32 v[120:121], v[18:19], v[18:19]
	v_add_u32_e32 v192, 0x10000, v208
	v_add_u32_e32 v193, 0x14000, v208
	v_add_u32_e32 v213, 0x18000, v208
	v_add_u32_e32 v227, 0x1c000, v208
.LBB0_809:
	s_add_i32 s52, s46, 2
	s_add_u32 s14, s48, 0x100
	s_addc_u32 s15, s49, 0
	s_add_i32 s53, 0, 0x10000
	s_cmp_eq_u32 s71, s46
	s_cselect_b32 s47, s11, s15
	s_cselect_b32 s46, s13, s14
	s_cselect_b32 s77, s87, s51
	s_cselect_b32 s76, s86, s35
	s_add_i32 s75, 0, 0x14000
	ds_read_b128 v[138:141], v192
	ds_read_b128 v[142:145], v192 offset:1024
	ds_read_b128 v[146:149], v192 offset:2048
	ds_read_b128 v[150:153], v192 offset:3072
	ds_read_b128 v[154:157], v193
	ds_read_b128 v[158:161], v193 offset:1024
	ds_read_b128 v[162:165], v193 offset:2048
	ds_read_b128 v[166:169], v193 offset:3072
	s_add_i32 m0, s63, 0xc000
	ds_read_b128 v[194:197], v211
	ds_read_b128 v[198:201], v211 offset:1024
	ds_read_b128 v[202:205], v211 offset:2048
	ds_read_b128 v[214:217], v211 offset:3072
	ds_read_b128 v[228:231], v211 offset:4096
	ds_read_b128 v[232:235], v211 offset:5120
	ds_read_b128 v[236:239], v211 offset:6144
	ds_read_b128 v[240:243], v211 offset:7168
	global_load_lds_dwordx4 v182, s[48:49]
	v_lshl_add_u64 v[190:191], s[48:49], 0, v[184:185]
	s_add_i32 m0, s63, 0xe000
	s_nop 0
	global_load_lds_dwordx4 v[190:191], off
	s_waitcnt vmcnt(8)
	s_waitcnt lgkmcnt(0)
	s_barrier
	v_mfma_f32_16x16x32_bf16 v[118:121], v[138:141], v[194:197], v[118:121]
	v_mfma_f32_16x16x32_bf16 v[46:49], v[146:149], v[194:197], v[46:49]
	v_mfma_f32_16x16x32_bf16 v[110:113], v[138:141], v[202:205], v[110:113]
	v_mfma_f32_16x16x32_bf16 v[38:41], v[146:149], v[202:205], v[38:41]
	v_mfma_f32_16x16x32_bf16 v[134:137], v[138:141], v[228:231], v[134:137]
	v_mfma_f32_16x16x32_bf16 v[62:65], v[146:149], v[228:231], v[62:65]
	v_mfma_f32_16x16x32_bf16 v[130:133], v[138:141], v[236:239], v[130:133]
	v_mfma_f32_16x16x32_bf16 v[58:61], v[146:149], v[236:239], v[58:61]
	v_mfma_f32_16x16x32_bf16 v[118:121], v[142:145], v[198:201], v[118:121]
	v_mfma_f32_16x16x32_bf16 v[46:49], v[150:153], v[198:201], v[46:49]
	v_mfma_f32_16x16x32_bf16 v[110:113], v[142:145], v[214:217], v[110:113]
	v_mfma_f32_16x16x32_bf16 v[38:41], v[150:153], v[214:217], v[38:41]
	v_mfma_f32_16x16x32_bf16 v[134:137], v[142:145], v[232:235], v[134:137]
	v_mfma_f32_16x16x32_bf16 v[62:65], v[150:153], v[232:235], v[62:65]
	v_mfma_f32_16x16x32_bf16 v[130:133], v[142:145], v[240:243], v[130:133]
	v_mfma_f32_16x16x32_bf16 v[58:61], v[150:153], v[240:243], v[58:61]
	v_mfma_f32_16x16x32_bf16 v[114:117], v[154:157], v[194:197], v[114:117]
	v_mfma_f32_16x16x32_bf16 v[42:45], v[162:165], v[194:197], v[42:45]
	v_mfma_f32_16x16x32_bf16 v[106:109], v[154:157], v[202:205], v[106:109]
	v_mfma_f32_16x16x32_bf16 v[34:37], v[162:165], v[202:205], v[34:37]
	v_mfma_f32_16x16x32_bf16 v[126:129], v[154:157], v[228:231], v[126:129]
	v_mfma_f32_16x16x32_bf16 v[54:57], v[162:165], v[228:231], v[54:57]
	v_mfma_f32_16x16x32_bf16 v[122:125], v[154:157], v[236:239], v[122:125]
	v_mfma_f32_16x16x32_bf16 v[50:53], v[162:165], v[236:239], v[50:53]
	v_mfma_f32_16x16x32_bf16 v[114:117], v[158:161], v[198:201], v[114:117]
	v_mfma_f32_16x16x32_bf16 v[42:45], v[166:169], v[198:201], v[42:45]
	v_mfma_f32_16x16x32_bf16 v[106:109], v[158:161], v[214:217], v[106:109]
	v_mfma_f32_16x16x32_bf16 v[34:37], v[166:169], v[214:217], v[34:37]
	v_mfma_f32_16x16x32_bf16 v[126:129], v[158:161], v[232:235], v[126:129]
	v_mfma_f32_16x16x32_bf16 v[54:57], v[166:169], v[232:235], v[54:57]
	v_mfma_f32_16x16x32_bf16 v[122:125], v[158:161], v[240:243], v[122:125]
	v_mfma_f32_16x16x32_bf16 v[50:53], v[166:169], v[240:243], v[50:53]
	s_barrier
; #define PG8_STAGE(bufoff, gbase, voff) do { _Pragma("unroll") for (int _i = 0; _i < 2; ++_i) \
;         __builtin_amdgcn_global_load_lds((const unsigned*)((const char*)(gbase) + (voff)[_i]), (PG8_LAS unsigned*)(lds + (bufoff) + ldsw + _i * 8192), 16, 0, 0); } while (0)
; #define PG8_LDA(dst, b, h) do { _Pragma("unroll") for (int m = 0; m < 4; ++m) _Pragma("unroll") for (int k = 0; k < 2; ++k) dst[m][k] = *(const PG8_LAS bf16x8*)(lds + PG8_SA(b, h) + aoff + m * 2048 + k * 1024); } while (0)
; #define PG8_LDB(dst, b, h) do { _Pragma("unroll") for (int n = 0; n < 2; ++n) _Pragma("unroll") for (int k = 0; k < 2; ++k) dst[n][k] = *(const PG8_LAS bf16x8*)(lds + PG8_SB(b, h) + boff + n * 2048 + k * 1024); } while (0)
; #define PG8_MMA(ai, bj, At, Bt) do { __builtin_amdgcn_s_setprio(1); _Pragma("unroll") for (int m = 0; m < 4; ++m) _Pragma("unroll") for (int n = 0; n < 2; ++n) _Pragma("unroll") for (int k = 0; k < 2; ++k) \
;         acc[ai][bj][m][n] = __builtin_amdgcn_mfma_f32_16x16x32_bf16(Bt[n][k], At[m][k], acc[ai][bj][m][n], 0, 0, 0); __builtin_amdgcn_s_setprio(0); } while (0)
; #define PG8_WAIT_V(n) asm volatile("s_waitcnt vmcnt(" #n ")" ::: "memory")
; #define PG8_WAIT_L(n) asm volatile("s_waitcnt lgkmcnt(" #n ")" ::: "memory")
; #define PG8_BAR __builtin_amdgcn_s_barrier()
; #define PG8_SCHED __builtin_amdgcn_sched_barrier(0)
; template <class Epi, class Sched, bool ALIGN_EPI = false, bool SP2 = false>
; __device__ __forceinline__ void gemm_phase(PG8_LAS unsigned char* lds, const Gemm g, const Sched& S, const Epi& E, const int wv) {
;     ...
;             PG8_LDA(At, 0, 1); PG8_STAGE(PG8_SB(0, 0), b2, voffB); PG8_STAGE(PG8_SB(0, 1), b2 + hstepB, voffB); PG8_STAGE(PG8_SA(0, 0), a2, voffA);
;             PG8_WAIT_V(8); PG8_WAIT_L(0); PG8_BAR; PG8_MMA(1, 0, At, B0); PG8_MMA(1, 1, At, B1); PG8_BAR; PG8_SCHED;
;             PG8_LDB(B0, 1, 0); PG8_LDB(B1, 1, 1); PG8_SCHED; PG8_LDA(At, 1, 0); PG8_STAGE(PG8_SA(0, 1), a2 + hstepA, voffA);
;             PG8_WAIT_V(8); PG8_WAIT_L(0); PG8_BAR; PG8_MMA(0, 0, At, B0); PG8_MMA(0, 1, At, B1); PG8_BAR; PG8_SCHED;
	s_add_i32 s48, s53, s62
	s_mov_b32 m0, s48
	ds_read_b128 v[194:197], v211 offset:16384
	ds_read_b128 v[198:201], v211 offset:17408
	ds_read_b128 v[202:205], v211 offset:18432
	ds_read_b128 v[214:217], v211 offset:19456
	ds_read_b128 v[228:231], v211 offset:20480
	ds_read_b128 v[232:235], v211 offset:21504
	ds_read_b128 v[236:239], v211 offset:22528
	ds_read_b128 v[240:243], v211 offset:23552
	global_load_lds_dwordx4 v0, s[76:77]
	s_add_i32 m0, s48, 0x2000
	s_add_u32 s48, s76, s16
	s_addc_u32 s49, s77, s17
	s_add_i32 s53, s75, s62
	global_load_lds_dwordx4 v174, s[76:77]
	v_lshl_add_u64 v[218:219], s[48:49], 0, v[0:1]
	s_mov_b32 m0, s53
	v_lshl_add_u64 v[244:245], s[48:49], 0, v[174:175]
	global_load_lds_dwordx4 v[218:219], off
	s_add_i32 m0, s53, 0x2000
	v_lshl_add_u64 v[246:247], s[46:47], 0, v[170:171]
	global_load_lds_dwordx4 v[244:245], off
	s_mov_b32 m0, s63
	v_lshl_add_u64 v[248:249], s[46:47], 0, v[172:173]
	global_load_lds_dwordx4 v[246:247], off
	s_mov_b32 m0, s64
	s_nop 0
	global_load_lds_dwordx4 v[248:249], off
	s_waitcnt vmcnt(8)
	s_waitcnt lgkmcnt(0)
	s_barrier
	v_mfma_f32_16x16x32_bf16 v[86:89], v[138:141], v[194:197], v[86:89]
	v_mfma_f32_16x16x32_bf16 v[14:17], v[146:149], v[194:197], v[14:17]
	v_mfma_f32_16x16x32_bf16 v[70:73], v[138:141], v[202:205], v[70:73]
	v_mfma_f32_16x16x32_bf16 v[6:9], v[146:149], v[202:205], v[6:9]
	v_mfma_f32_16x16x32_bf16 v[102:105], v[138:141], v[228:231], v[102:105]
	v_mfma_f32_16x16x32_bf16 v[30:33], v[146:149], v[228:231], v[30:33]
	v_mfma_f32_16x16x32_bf16 v[98:101], v[138:141], v[236:239], v[98:101]
	v_mfma_f32_16x16x32_bf16 v[26:29], v[146:149], v[236:239], v[26:29]
	v_mfma_f32_16x16x32_bf16 v[86:89], v[142:145], v[198:201], v[86:89]
	v_mfma_f32_16x16x32_bf16 v[14:17], v[150:153], v[198:201], v[14:17]
	v_mfma_f32_16x16x32_bf16 v[70:73], v[142:145], v[214:217], v[70:73]
	v_mfma_f32_16x16x32_bf16 v[6:9], v[150:153], v[214:217], v[6:9]
	v_mfma_f32_16x16x32_bf16 v[102:105], v[142:145], v[232:235], v[102:105]
	v_mfma_f32_16x16x32_bf16 v[30:33], v[150:153], v[232:235], v[30:33]
	v_mfma_f32_16x16x32_bf16 v[98:101], v[142:145], v[240:243], v[98:101]
	v_mfma_f32_16x16x32_bf16 v[26:29], v[150:153], v[240:243], v[26:29]
	v_mfma_f32_16x16x32_bf16 v[82:85], v[154:157], v[194:197], v[82:85]
	v_mfma_f32_16x16x32_bf16 v[10:13], v[162:165], v[194:197], v[10:13]
	v_mfma_f32_16x16x32_bf16 v[66:69], v[154:157], v[202:205], v[66:69]
	v_mfma_f32_16x16x32_bf16 v[2:5], v[162:165], v[202:205], v[2:5]
	v_mfma_f32_16x16x32_bf16 v[94:97], v[154:157], v[228:231], v[94:97]
	v_mfma_f32_16x16x32_bf16 v[22:25], v[162:165], v[228:231], v[22:25]
	v_mfma_f32_16x16x32_bf16 v[90:93], v[154:157], v[236:239], v[90:93]
	v_mfma_f32_16x16x32_bf16 v[18:21], v[162:165], v[236:239], v[18:21]
	v_mfma_f32_16x16x32_bf16 v[82:85], v[158:161], v[198:201], v[82:85]
	v_mfma_f32_16x16x32_bf16 v[10:13], v[166:169], v[198:201], v[10:13]
	v_mfma_f32_16x16x32_bf16 v[66:69], v[158:161], v[214:217], v[66:69]
	v_mfma_f32_16x16x32_bf16 v[2:5], v[166:169], v[214:217], v[2:5]
	v_mfma_f32_16x16x32_bf16 v[94:97], v[158:161], v[232:235], v[94:97]
	v_mfma_f32_16x16x32_bf16 v[22:25], v[166:169], v[232:235], v[22:25]
	v_mfma_f32_16x16x32_bf16 v[90:93], v[158:161], v[240:243], v[90:93]
	v_mfma_f32_16x16x32_bf16 v[18:21], v[166:169], v[240:243], v[18:21]
	s_barrier
	s_add_i32 s48, 0, 0x18000
	s_add_i32 s49, 0, 0x1c000
	ds_read_b128 v[138:141], v213
	ds_read_b128 v[142:145], v213 offset:1024
	ds_read_b128 v[146:149], v213 offset:2048
	ds_read_b128 v[150:153], v213 offset:3072
	ds_read_b128 v[154:157], v227
	ds_read_b128 v[158:161], v227 offset:1024
	ds_read_b128 v[162:165], v227 offset:2048
	ds_read_b128 v[166:169], v227 offset:3072
	s_add_u32 s46, s46, 0x80000
	s_addc_u32 s47, s47, 0
	s_mov_b32 m0, s65
	ds_read_b128 v[194:197], v211 offset:32768
	ds_read_b128 v[198:201], v211 offset:33792
	ds_read_b128 v[202:205], v211 offset:34816
	ds_read_b128 v[214:217], v211 offset:35840
	ds_read_b128 v[228:231], v211 offset:36864
	ds_read_b128 v[232:235], v211 offset:37888
	ds_read_b128 v[236:239], v211 offset:38912
	ds_read_b128 v[240:243], v211 offset:39936
	global_load_lds_dwordx4 v170, s[46:47]
	s_mov_b32 m0, s66
	s_nop 0
	global_load_lds_dwordx4 v172, s[46:47]
	s_waitcnt vmcnt(8)
	s_waitcnt lgkmcnt(0)
	s_barrier
; #define PG8_STAGE(bufoff, gbase, voff) do { _Pragma("unroll") for (int _i = 0; _i < 2; ++_i) \
;         __builtin_amdgcn_global_load_lds((const unsigned*)((const char*)(gbase) + (voff)[_i]), (PG8_LAS unsigned*)(lds + (bufoff) + ldsw + _i * 8192), 16, 0, 0); } while (0)
; #define PG8_LDA(dst, b, h) do { _Pragma("unroll") for (int m = 0; m < 4; ++m) _Pragma("unroll") for (int k = 0; k < 2; ++k) dst[m][k] = *(const PG8_LAS bf16x8*)(lds + PG8_SA(b, h) + aoff + m * 2048 + k * 1024); } while (0)
; #define PG8_MMA(ai, bj, At, Bt) do { __builtin_amdgcn_s_setprio(1); _Pragma("unroll") for (int m = 0; m < 4; ++m) _Pragma("unroll") for (int n = 0; n < 2; ++n) _Pragma("unroll") for (int k = 0; k < 2; ++k) \
;         acc[ai][bj][m][n] = __builtin_amdgcn_mfma_f32_16x16x32_bf16(Bt[n][k], At[m][k], acc[ai][bj][m][n], 0, 0, 0); __builtin_amdgcn_s_setprio(0); } while (0)
; #define PG8_WAIT_V(n) asm volatile("s_waitcnt vmcnt(" #n ")" ::: "memory")
; #define PG8_WAIT_L(n) asm volatile("s_waitcnt lgkmcnt(" #n ")" ::: "memory")
; #define PG8_BAR __builtin_amdgcn_s_barrier()
; #define PG8_SCHED __builtin_amdgcn_sched_barrier(0)
; template <class Epi, class Sched, bool ALIGN_EPI = false, bool SP2 = false>
; __device__ __forceinline__ void gemm_phase(PG8_LAS unsigned char* lds, const Gemm g, const Sched& S, const Epi& E, const int wv) {
;     ...
;         for (int t = 0; t < nt; t += 2) {
;     ...
;             PG8_WAIT_V(8); PG8_WAIT_L(0); PG8_BAR; PG8_MMA(0, 0, At, B0); PG8_MMA(0, 1, At, B1); PG8_BAR; PG8_SCHED;
;             PG8_LDA(At, 1, 1); PG8_STAGE(PG8_SB(1, 0), b3, voffB); PG8_STAGE(PG8_SB(1, 1), b3 + hstepB, voffB); PG8_STAGE(PG8_SA(1, 0), a3, voffA);
;             PG8_WAIT_V(8); PG8_WAIT_L(0); PG8_BAR; PG8_MMA(1, 0, At, B0); PG8_MMA(1, 1, At, B1); PG8_BAR; PG8_SCHED;
	v_mfma_f32_16x16x32_bf16 v[118:121], v[138:141], v[194:197], v[118:121]
	v_mfma_f32_16x16x32_bf16 v[46:49], v[146:149], v[194:197], v[46:49]
	v_mfma_f32_16x16x32_bf16 v[110:113], v[138:141], v[202:205], v[110:113]
	v_mfma_f32_16x16x32_bf16 v[38:41], v[146:149], v[202:205], v[38:41]
	v_mfma_f32_16x16x32_bf16 v[134:137], v[138:141], v[228:231], v[134:137]
	v_mfma_f32_16x16x32_bf16 v[62:65], v[146:149], v[228:231], v[62:65]
	v_mfma_f32_16x16x32_bf16 v[130:133], v[138:141], v[236:239], v[130:133]
	v_mfma_f32_16x16x32_bf16 v[58:61], v[146:149], v[236:239], v[58:61]
	v_mfma_f32_16x16x32_bf16 v[118:121], v[142:145], v[198:201], v[118:121]
	v_mfma_f32_16x16x32_bf16 v[46:49], v[150:153], v[198:201], v[46:49]
	v_mfma_f32_16x16x32_bf16 v[110:113], v[142:145], v[214:217], v[110:113]
	v_mfma_f32_16x16x32_bf16 v[38:41], v[150:153], v[214:217], v[38:41]
	v_mfma_f32_16x16x32_bf16 v[134:137], v[142:145], v[232:235], v[134:137]
	v_mfma_f32_16x16x32_bf16 v[62:65], v[150:153], v[232:235], v[62:65]
	v_mfma_f32_16x16x32_bf16 v[130:133], v[142:145], v[240:243], v[130:133]
	v_mfma_f32_16x16x32_bf16 v[58:61], v[150:153], v[240:243], v[58:61]
	v_mfma_f32_16x16x32_bf16 v[114:117], v[154:157], v[194:197], v[114:117]
	v_mfma_f32_16x16x32_bf16 v[42:45], v[162:165], v[194:197], v[42:45]
	v_mfma_f32_16x16x32_bf16 v[106:109], v[154:157], v[202:205], v[106:109]
	v_mfma_f32_16x16x32_bf16 v[34:37], v[162:165], v[202:205], v[34:37]
	v_mfma_f32_16x16x32_bf16 v[126:129], v[154:157], v[228:231], v[126:129]
	v_mfma_f32_16x16x32_bf16 v[54:57], v[162:165], v[228:231], v[54:57]
	v_mfma_f32_16x16x32_bf16 v[122:125], v[154:157], v[236:239], v[122:125]
	v_mfma_f32_16x16x32_bf16 v[50:53], v[162:165], v[236:239], v[50:53]
	v_mfma_f32_16x16x32_bf16 v[114:117], v[158:161], v[198:201], v[114:117]
	v_mfma_f32_16x16x32_bf16 v[42:45], v[166:169], v[198:201], v[42:45]
	v_mfma_f32_16x16x32_bf16 v[106:109], v[158:161], v[214:217], v[106:109]
	v_mfma_f32_16x16x32_bf16 v[34:37], v[166:169], v[214:217], v[34:37]
	v_mfma_f32_16x16x32_bf16 v[126:129], v[158:161], v[232:235], v[126:129]
	v_mfma_f32_16x16x32_bf16 v[54:57], v[166:169], v[232:235], v[54:57]
	v_mfma_f32_16x16x32_bf16 v[122:125], v[158:161], v[240:243], v[122:125]
	v_mfma_f32_16x16x32_bf16 v[50:53], v[166:169], v[240:243], v[50:53]
	s_barrier
	s_add_i32 s46, s48, s62
	s_add_i32 m0, s46, 0xffffff80
	ds_read_b128 v[194:197], v211 offset:49152
	ds_read_b128 v[198:201], v211 offset:50176
	ds_read_b128 v[202:205], v211 offset:51200
	ds_read_b128 v[214:217], v211 offset:52224
	ds_read_b128 v[228:231], v211 offset:53248
	ds_read_b128 v[232:235], v211 offset:54272
	ds_read_b128 v[236:239], v211 offset:55296
	ds_read_b128 v[240:243], v211 offset:56320
	global_load_lds_dwordx4 v0, s[76:77] offset:128
	s_add_i32 m0, s46, 0x1f80
	s_add_i32 s46, s49, s62
	global_load_lds_dwordx4 v174, s[76:77] offset:128
	s_add_i32 m0, s46, 0xffffff80
	s_nop 0
	global_load_lds_dwordx4 v[218:219], off offset:128
	s_add_i32 m0, s46, 0x1f80
	s_nop 0
	global_load_lds_dwordx4 v[244:245], off offset:128
	s_add_i32 m0, s69, 0xffffff80
	s_nop 0
	global_load_lds_dwordx4 v[246:247], off offset:128
	s_add_i32 m0, s70, 0xffffff80
	s_nop 0
	global_load_lds_dwordx4 v[248:249], off offset:128
	s_waitcnt vmcnt(8)
	s_waitcnt lgkmcnt(0)
	s_barrier
	v_mfma_f32_16x16x32_bf16 v[86:89], v[138:141], v[194:197], v[86:89]
	v_mfma_f32_16x16x32_bf16 v[14:17], v[146:149], v[194:197], v[14:17]
	v_mfma_f32_16x16x32_bf16 v[70:73], v[138:141], v[202:205], v[70:73]
	v_mfma_f32_16x16x32_bf16 v[6:9], v[146:149], v[202:205], v[6:9]
	v_mfma_f32_16x16x32_bf16 v[102:105], v[138:141], v[228:231], v[102:105]
	v_mfma_f32_16x16x32_bf16 v[30:33], v[146:149], v[228:231], v[30:33]
	v_mfma_f32_16x16x32_bf16 v[98:101], v[138:141], v[236:239], v[98:101]
	v_mfma_f32_16x16x32_bf16 v[26:29], v[146:149], v[236:239], v[26:29]
	v_mfma_f32_16x16x32_bf16 v[86:89], v[142:145], v[198:201], v[86:89]
	v_mfma_f32_16x16x32_bf16 v[14:17], v[150:153], v[198:201], v[14:17]
	v_mfma_f32_16x16x32_bf16 v[70:73], v[142:145], v[214:217], v[70:73]
	v_mfma_f32_16x16x32_bf16 v[6:9], v[150:153], v[214:217], v[6:9]
	v_mfma_f32_16x16x32_bf16 v[102:105], v[142:145], v[232:235], v[102:105]
	v_mfma_f32_16x16x32_bf16 v[30:33], v[150:153], v[232:235], v[30:33]
	v_mfma_f32_16x16x32_bf16 v[98:101], v[142:145], v[240:243], v[98:101]
	v_mfma_f32_16x16x32_bf16 v[26:29], v[150:153], v[240:243], v[26:29]
	v_mfma_f32_16x16x32_bf16 v[82:85], v[154:157], v[194:197], v[82:85]
	v_mfma_f32_16x16x32_bf16 v[10:13], v[162:165], v[194:197], v[10:13]
	v_mfma_f32_16x16x32_bf16 v[66:69], v[154:157], v[202:205], v[66:69]
	v_mfma_f32_16x16x32_bf16 v[2:5], v[162:165], v[202:205], v[2:5]
	v_mfma_f32_16x16x32_bf16 v[94:97], v[154:157], v[228:231], v[94:97]
	v_mfma_f32_16x16x32_bf16 v[22:25], v[162:165], v[228:231], v[22:25]
	v_mfma_f32_16x16x32_bf16 v[90:93], v[154:157], v[236:239], v[90:93]
	v_mfma_f32_16x16x32_bf16 v[18:21], v[162:165], v[236:239], v[18:21]
	v_mfma_f32_16x16x32_bf16 v[82:85], v[158:161], v[198:201], v[82:85]
	v_mfma_f32_16x16x32_bf16 v[10:13], v[166:169], v[198:201], v[10:13]
	v_mfma_f32_16x16x32_bf16 v[66:69], v[158:161], v[214:217], v[66:69]
	v_mfma_f32_16x16x32_bf16 v[2:5], v[166:169], v[214:217], v[2:5]
	v_mfma_f32_16x16x32_bf16 v[94:97], v[158:161], v[232:235], v[94:97]
	v_mfma_f32_16x16x32_bf16 v[22:25], v[166:169], v[232:235], v[22:25]
	v_mfma_f32_16x16x32_bf16 v[90:93], v[158:161], v[240:243], v[90:93]
	v_mfma_f32_16x16x32_bf16 v[18:21], v[166:169], v[240:243], v[18:21]
	s_barrier
	s_add_u32 s35, s35, 0x100
	s_addc_u32 s51, s51, 0
	s_cmp_ge_i32 s52, s67
	s_mov_b64 s[48:49], s[14:15]
	s_mov_b32 s46, s52
	s_cbranch_scc0 .LBB0_809
	s_movk_i32 s75, 0x2000
	s_movk_i32 s76, 0x3000
	s_and_b64 vcc, exec, s[30:31]
	s_cbranch_vccz .LBB0_784

; #define PG8_STAGE(bufoff, gbase, voff) do { _Pragma("unroll") for (int _i = 0; _i < 2; ++_i) \
;         __builtin_amdgcn_global_load_lds((const unsigned*)((const char*)(gbase) + (voff)[_i]), (PG8_LAS unsigned*)(lds + (bufoff) + ldsw + _i * 8192), 16, 0, 0); } while (0)
; #define PG8_LDA(dst, b, h) do { _Pragma("unroll") for (int m = 0; m < 4; ++m) _Pragma("unroll") for (int k = 0; k < 2; ++k) dst[m][k] = *(const PG8_LAS bf16x8*)(lds + PG8_SA(b, h) + aoff + m * 2048 + k * 1024); } while (0)
; #define PG8_LDB(dst, b, h) do { _Pragma("unroll") for (int n = 0; n < 2; ++n) _Pragma("unroll") for (int k = 0; k < 2; ++k) dst[n][k] = *(const PG8_LAS bf16x8*)(lds + PG8_SB(b, h) + boff + n * 2048 + k * 1024); } while (0)
; #define PG8_MMA(ai, bj, At, Bt) do { __builtin_amdgcn_s_setprio(1); _Pragma("unroll") for (int m = 0; m < 4; ++m) _Pragma("unroll") for (int n = 0; n < 2; ++n) _Pragma("unroll") for (int k = 0; k < 2; ++k) \
;         acc[ai][bj][m][n] = __builtin_amdgcn_mfma_f32_16x16x32_bf16(Bt[n][k], At[m][k], acc[ai][bj][m][n], 0, 0, 0); __builtin_amdgcn_s_setprio(0); } while (0)
; #define PG8_WAIT_V(n) asm volatile("s_waitcnt vmcnt(" #n ")" ::: "memory")
; #define PG8_WAIT_L(n) asm volatile("s_waitcnt lgkmcnt(" #n ")" ::: "memory")
; template <class Epi, class Sched, bool ALIGN_EPI = false, bool SP2 = false>
; __device__ __forceinline__ void gemm_phase(PG8_LAS unsigned char* lds, const Gemm g, const Sched& S, const Epi& E, const int wv) {
;     ...
; #pragma unroll
;     for (int a = 0; a < 2; ++a)
; #pragma unroll
;         for (int b = 0; b < 2; ++b)
; #pragma unroll
;             for (int m = 0; m < 4; ++m)
; #pragma unroll
;                 for (int n = 0; n < 2; ++n) acc[a][b][m][n] = (f32x4){0.f, 0.f, 0.f, 0.f};
;     ...
;             const bool last = (t == nt - 2);
;             const char* a1 = cA + (size_t)(t + 1) * kstep;
;             const char* a2 = last ? nA : cA + (size_t)(t + 2) * kstep; const char* b2 = last ? nB : cB + (size_t)(t + 2) * kstep;
;             const char* a3 = a2 + kstep; const char* b3 = b2 + kstep;
;             if (last && has_next) S.a_ready(nxt);
;             if constexpr (SP2) {
;             PG8_LDB(B0, 0, 0); PG8_LDB(B1, 0, 1); PG8_SCHED; PG8_LDA(At, 0, 0); PG8_STAGE(PG8_SA(1, 1), a1 + hstepA, voffA);
;             PG8_WAIT_V(8); PG8_WAIT_L(0); PG8_BAR; PG8_MMA(0, 0, At, B0); PG8_MMA(0, 1, At, B1); PG8_BAR; PG8_SCHED;
.LBB0_989:
	s_add_u32 s65, s34, 0x100
	v_mov_b32_e32 v2, 0
	s_addc_u32 s66, s35, 0
	s_mov_b32 s44, 0
	v_mov_b32_e32 v3, v2
	v_pk_mov_b32 v[4:5], v[2:3], v[2:3]
	v_pk_mov_b32 v[6:7], v[2:3], v[2:3]
	v_pk_mov_b32 v[8:9], v[2:3], v[2:3]
	v_pk_mov_b32 v[18:19], v[2:3], v[2:3]
	v_pk_mov_b32 v[20:21], v[2:3], v[2:3]
	v_pk_mov_b32 v[22:23], v[2:3], v[2:3]
	v_pk_mov_b32 v[24:25], v[2:3], v[2:3]
	v_pk_mov_b32 v[34:35], v[2:3], v[2:3]
	v_pk_mov_b32 v[36:37], v[2:3], v[2:3]
	v_pk_mov_b32 v[38:39], v[2:3], v[2:3]
	v_pk_mov_b32 v[40:41], v[2:3], v[2:3]
	v_pk_mov_b32 v[50:51], v[2:3], v[2:3]
	v_pk_mov_b32 v[52:53], v[2:3], v[2:3]
	v_pk_mov_b32 v[54:55], v[2:3], v[2:3]
	v_pk_mov_b32 v[56:57], v[2:3], v[2:3]
	v_pk_mov_b32 v[10:11], v[2:3], v[2:3]
	v_pk_mov_b32 v[12:13], v[2:3], v[2:3]
	v_pk_mov_b32 v[14:15], v[2:3], v[2:3]
	v_pk_mov_b32 v[16:17], v[2:3], v[2:3]
	v_pk_mov_b32 v[26:27], v[2:3], v[2:3]
	v_pk_mov_b32 v[28:29], v[2:3], v[2:3]
	v_pk_mov_b32 v[30:31], v[2:3], v[2:3]
	v_pk_mov_b32 v[32:33], v[2:3], v[2:3]
	v_pk_mov_b32 v[42:43], v[2:3], v[2:3]
	v_pk_mov_b32 v[44:45], v[2:3], v[2:3]
	v_pk_mov_b32 v[46:47], v[2:3], v[2:3]
	v_pk_mov_b32 v[48:49], v[2:3], v[2:3]
	v_pk_mov_b32 v[58:59], v[2:3], v[2:3]
	v_pk_mov_b32 v[60:61], v[2:3], v[2:3]
	v_pk_mov_b32 v[62:63], v[2:3], v[2:3]
	v_pk_mov_b32 v[64:65], v[2:3], v[2:3]
	v_pk_mov_b32 v[66:67], v[2:3], v[2:3]
	v_pk_mov_b32 v[68:69], v[2:3], v[2:3]
	v_pk_mov_b32 v[70:71], v[2:3], v[2:3]
	v_pk_mov_b32 v[72:73], v[2:3], v[2:3]
	v_pk_mov_b32 v[82:83], v[2:3], v[2:3]
	v_pk_mov_b32 v[84:85], v[2:3], v[2:3]
	v_pk_mov_b32 v[86:87], v[2:3], v[2:3]
	v_pk_mov_b32 v[88:89], v[2:3], v[2:3]
	v_pk_mov_b32 v[98:99], v[2:3], v[2:3]
	v_pk_mov_b32 v[100:101], v[2:3], v[2:3]
	v_pk_mov_b32 v[102:103], v[2:3], v[2:3]
	v_pk_mov_b32 v[104:105], v[2:3], v[2:3]
	v_pk_mov_b32 v[118:119], v[2:3], v[2:3]
	v_pk_mov_b32 v[120:121], v[2:3], v[2:3]
	v_pk_mov_b32 v[122:123], v[2:3], v[2:3]
	v_pk_mov_b32 v[124:125], v[2:3], v[2:3]
	v_pk_mov_b32 v[74:75], v[2:3], v[2:3]
	v_pk_mov_b32 v[76:77], v[2:3], v[2:3]
	v_pk_mov_b32 v[78:79], v[2:3], v[2:3]
	v_pk_mov_b32 v[80:81], v[2:3], v[2:3]
	v_pk_mov_b32 v[90:91], v[2:3], v[2:3]
	v_pk_mov_b32 v[92:93], v[2:3], v[2:3]
	v_pk_mov_b32 v[94:95], v[2:3], v[2:3]
	v_pk_mov_b32 v[96:97], v[2:3], v[2:3]
	v_pk_mov_b32 v[106:107], v[2:3], v[2:3]
	v_pk_mov_b32 v[108:109], v[2:3], v[2:3]
	v_pk_mov_b32 v[110:111], v[2:3], v[2:3]
	v_pk_mov_b32 v[112:113], v[2:3], v[2:3]
	v_pk_mov_b32 v[130:131], v[2:3], v[2:3]
	v_pk_mov_b32 v[132:133], v[2:3], v[2:3]
	v_pk_mov_b32 v[134:135], v[2:3], v[2:3]
	v_pk_mov_b32 v[136:137], v[2:3], v[2:3]
	v_add_u32_e32 v197, 0x10000, v230
	v_add_u32_e32 v201, 0x14000, v230
	v_add_u32_e32 v203, 0x18000, v230
	v_add_u32_e32 v216, 0x1c000, v230
.LBB0_990:
	s_add_i32 s67, s44, 2
	s_add_u32 s34, s30, 0x100
	s_addc_u32 s35, s31, 0
	s_add_i32 s70, 0, 0x10000
	s_cmp_eq_u32 s59, s44
	s_cselect_b32 s45, s13, s35
	s_cselect_b32 s44, s12, s34
	s_cselect_b32 s69, s15, s66
	s_cselect_b32 s68, s14, s65
	s_add_i32 s71, 0, 0x14000
	ds_read_b128 v[114:117], v197
	ds_read_b128 v[126:129], v197 offset:1024
	ds_read_b128 v[138:141], v197 offset:2048
	ds_read_b128 v[142:145], v197 offset:3072
	ds_read_b128 v[146:149], v201
	ds_read_b128 v[150:153], v201 offset:1024
	ds_read_b128 v[154:157], v201 offset:2048
	ds_read_b128 v[158:161], v201 offset:3072
	s_add_i32 m0, s52, 0xc000
	ds_read_b128 v[162:165], v235
	ds_read_b128 v[166:169], v235 offset:1024
	ds_read_b128 v[170:173], v235 offset:2048
	ds_read_b128 v[174:177], v235 offset:3072
	ds_read_b128 v[178:181], v235 offset:4096
	ds_read_b128 v[182:185], v235 offset:5120
	ds_read_b128 v[204:207], v235 offset:6144
	ds_read_b128 v[208:211], v235 offset:7168
	global_load_lds_dwordx4 v200, s[30:31]
	s_add_i32 m0, s52, 0xe000
	s_nop 0
	global_load_lds_dwordx4 v202, s[30:31]
	s_waitcnt vmcnt(8)
	s_waitcnt lgkmcnt(0)
	s_barrier
	v_mfma_f32_16x16x32_bf16 v[134:137], v[114:117], v[162:165], v[134:137]
	v_mfma_f32_16x16x32_bf16 v[130:133], v[138:141], v[162:165], v[130:133]
	v_mfma_f32_16x16x32_bf16 v[110:113], v[114:117], v[170:173], v[110:113]
	v_mfma_f32_16x16x32_bf16 v[106:109], v[138:141], v[170:173], v[106:109]
	v_mfma_f32_16x16x32_bf16 v[94:97], v[114:117], v[178:181], v[94:97]
	v_mfma_f32_16x16x32_bf16 v[90:93], v[138:141], v[178:181], v[90:93]
	v_mfma_f32_16x16x32_bf16 v[78:81], v[114:117], v[204:207], v[78:81]
	v_mfma_f32_16x16x32_bf16 v[74:77], v[138:141], v[204:207], v[74:77]
	v_mfma_f32_16x16x32_bf16 v[134:137], v[126:129], v[166:169], v[134:137]
	v_mfma_f32_16x16x32_bf16 v[130:133], v[142:145], v[166:169], v[130:133]
	v_mfma_f32_16x16x32_bf16 v[110:113], v[126:129], v[174:177], v[110:113]
	v_mfma_f32_16x16x32_bf16 v[106:109], v[142:145], v[174:177], v[106:109]
	v_mfma_f32_16x16x32_bf16 v[94:97], v[126:129], v[182:185], v[94:97]
	v_mfma_f32_16x16x32_bf16 v[90:93], v[142:145], v[182:185], v[90:93]
	v_mfma_f32_16x16x32_bf16 v[78:81], v[126:129], v[208:211], v[78:81]
	v_mfma_f32_16x16x32_bf16 v[74:77], v[142:145], v[208:211], v[74:77]
	v_mfma_f32_16x16x32_bf16 v[122:125], v[146:149], v[162:165], v[122:125]
	v_mfma_f32_16x16x32_bf16 v[118:121], v[154:157], v[162:165], v[118:121]
	v_mfma_f32_16x16x32_bf16 v[102:105], v[146:149], v[170:173], v[102:105]
	v_mfma_f32_16x16x32_bf16 v[98:101], v[154:157], v[170:173], v[98:101]
	v_mfma_f32_16x16x32_bf16 v[86:89], v[146:149], v[178:181], v[86:89]
	v_mfma_f32_16x16x32_bf16 v[82:85], v[154:157], v[178:181], v[82:85]
	v_mfma_f32_16x16x32_bf16 v[70:73], v[146:149], v[204:207], v[70:73]
	v_mfma_f32_16x16x32_bf16 v[66:69], v[154:157], v[204:207], v[66:69]
	v_mfma_f32_16x16x32_bf16 v[122:125], v[150:153], v[166:169], v[122:125]
	v_mfma_f32_16x16x32_bf16 v[118:121], v[158:161], v[166:169], v[118:121]
	v_mfma_f32_16x16x32_bf16 v[102:105], v[150:153], v[174:177], v[102:105]
	v_mfma_f32_16x16x32_bf16 v[98:101], v[158:161], v[174:177], v[98:101]
	v_mfma_f32_16x16x32_bf16 v[86:89], v[150:153], v[182:185], v[86:89]
	v_mfma_f32_16x16x32_bf16 v[82:85], v[158:161], v[182:185], v[82:85]
	v_mfma_f32_16x16x32_bf16 v[70:73], v[150:153], v[208:211], v[70:73]
	v_mfma_f32_16x16x32_bf16 v[66:69], v[158:161], v[208:211], v[66:69]
	s_barrier
; #define PG8_STAGE(bufoff, gbase, voff) do { _Pragma("unroll") for (int _i = 0; _i < 2; ++_i) \
;         __builtin_amdgcn_global_load_lds((const unsigned*)((const char*)(gbase) + (voff)[_i]), (PG8_LAS unsigned*)(lds + (bufoff) + ldsw + _i * 8192), 16, 0, 0); } while (0)
; #define PG8_LDA(dst, b, h) do { _Pragma("unroll") for (int m = 0; m < 4; ++m) _Pragma("unroll") for (int k = 0; k < 2; ++k) dst[m][k] = *(const PG8_LAS bf16x8*)(lds + PG8_SA(b, h) + aoff + m * 2048 + k * 1024); } while (0)
; #define PG8_LDB(dst, b, h) do { _Pragma("unroll") for (int n = 0; n < 2; ++n) _Pragma("unroll") for (int k = 0; k < 2; ++k) dst[n][k] = *(const PG8_LAS bf16x8*)(lds + PG8_SB(b, h) + boff + n * 2048 + k * 1024); } while (0)
; #define PG8_MMA(ai, bj, At, Bt) do { __builtin_amdgcn_s_setprio(1); _Pragma("unroll") for (int m = 0; m < 4; ++m) _Pragma("unroll") for (int n = 0; n < 2; ++n) _Pragma("unroll") for (int k = 0; k < 2; ++k) \
;         acc[ai][bj][m][n] = __builtin_amdgcn_mfma_f32_16x16x32_bf16(Bt[n][k], At[m][k], acc[ai][bj][m][n], 0, 0, 0); __builtin_amdgcn_s_setprio(0); } while (0)
; #define PG8_WAIT_V(n) asm volatile("s_waitcnt vmcnt(" #n ")" ::: "memory")
; #define PG8_WAIT_L(n) asm volatile("s_waitcnt lgkmcnt(" #n ")" ::: "memory")
; #define PG8_BAR __builtin_amdgcn_s_barrier()
; #define PG8_SCHED __builtin_amdgcn_sched_barrier(0)
; template <class Epi, class Sched, bool ALIGN_EPI = false, bool SP2 = false>
; __device__ __forceinline__ void gemm_phase(PG8_LAS unsigned char* lds, const Gemm g, const Sched& S, const Epi& E, const int wv) {
;     ...
;             PG8_LDA(At, 0, 1); PG8_STAGE(PG8_SB(0, 0), b2, voffB); PG8_STAGE(PG8_SB(0, 1), b2 + hstepB, voffB); PG8_STAGE(PG8_SA(0, 0), a2, voffA);
;             PG8_WAIT_V(8); PG8_WAIT_L(0); PG8_BAR; PG8_MMA(1, 0, At, B0); PG8_MMA(1, 1, At, B1); PG8_BAR; PG8_SCHED;
;             PG8_LDB(B0, 1, 0); PG8_LDB(B1, 1, 1); PG8_SCHED; PG8_LDA(At, 1, 0); PG8_STAGE(PG8_SA(0, 1), a2 + hstepA, voffA);
;             PG8_WAIT_V(8); PG8_WAIT_L(0); PG8_BAR; PG8_MMA(0, 0, At, B0); PG8_MMA(0, 1, At, B1); PG8_BAR; PG8_SCHED;
	s_add_i32 s30, s70, s47
	v_lshl_add_u64 v[190:191], s[68:69], 0, v[0:1]
	s_mov_b32 m0, s30
	ds_read_b128 v[162:165], v235 offset:16384
	ds_read_b128 v[166:169], v235 offset:17408
	ds_read_b128 v[170:173], v235 offset:18432
	ds_read_b128 v[174:177], v235 offset:19456
	ds_read_b128 v[178:181], v235 offset:20480
	ds_read_b128 v[182:185], v235 offset:21504
	ds_read_b128 v[204:207], v235 offset:22528
	ds_read_b128 v[208:211], v235 offset:23552
	global_load_lds_dwordx4 v[190:191], off
	s_add_i32 m0, s30, 0x2000
	s_add_u32 s30, s68, s2
	v_lshl_add_u64 v[192:193], s[68:69], 0, v[198:199]
	s_addc_u32 s31, s69, s3
	s_add_i32 s68, s71, s47
	global_load_lds_dwordx4 v[192:193], off
	v_lshl_add_u64 v[212:213], s[30:31], 0, v[0:1]
	s_mov_b32 m0, s68
	v_lshl_add_u64 v[214:215], s[30:31], 0, v[198:199]
	global_load_lds_dwordx4 v[212:213], off
	s_add_i32 m0, s68, 0x2000
	global_load_lds_dwordx4 v[214:215], off
	s_mov_b32 m0, s52
	global_load_lds_dwordx4 v194, s[44:45]
	s_mov_b32 m0, s53
	s_nop 0
	global_load_lds_dwordx4 v196, s[44:45]
	s_waitcnt vmcnt(8)
	s_waitcnt lgkmcnt(0)
	s_barrier
	v_mfma_f32_16x16x32_bf16 v[62:65], v[114:117], v[162:165], v[62:65]
	v_mfma_f32_16x16x32_bf16 v[58:61], v[138:141], v[162:165], v[58:61]
	v_mfma_f32_16x16x32_bf16 v[46:49], v[114:117], v[170:173], v[46:49]
	v_mfma_f32_16x16x32_bf16 v[42:45], v[138:141], v[170:173], v[42:45]
	v_mfma_f32_16x16x32_bf16 v[30:33], v[114:117], v[178:181], v[30:33]
	v_mfma_f32_16x16x32_bf16 v[26:29], v[138:141], v[178:181], v[26:29]
	v_mfma_f32_16x16x32_bf16 v[14:17], v[114:117], v[204:207], v[14:17]
	v_mfma_f32_16x16x32_bf16 v[10:13], v[138:141], v[204:207], v[10:13]
	v_mfma_f32_16x16x32_bf16 v[62:65], v[126:129], v[166:169], v[62:65]
	v_mfma_f32_16x16x32_bf16 v[58:61], v[142:145], v[166:169], v[58:61]
	v_mfma_f32_16x16x32_bf16 v[46:49], v[126:129], v[174:177], v[46:49]
	v_mfma_f32_16x16x32_bf16 v[42:45], v[142:145], v[174:177], v[42:45]
	v_mfma_f32_16x16x32_bf16 v[30:33], v[126:129], v[182:185], v[30:33]
	v_mfma_f32_16x16x32_bf16 v[26:29], v[142:145], v[182:185], v[26:29]
	v_mfma_f32_16x16x32_bf16 v[14:17], v[126:129], v[208:211], v[14:17]
	v_mfma_f32_16x16x32_bf16 v[10:13], v[142:145], v[208:211], v[10:13]
	v_mfma_f32_16x16x32_bf16 v[54:57], v[146:149], v[162:165], v[54:57]
	v_mfma_f32_16x16x32_bf16 v[50:53], v[154:157], v[162:165], v[50:53]
	v_mfma_f32_16x16x32_bf16 v[38:41], v[146:149], v[170:173], v[38:41]
	v_mfma_f32_16x16x32_bf16 v[34:37], v[154:157], v[170:173], v[34:37]
	v_mfma_f32_16x16x32_bf16 v[22:25], v[146:149], v[178:181], v[22:25]
	v_mfma_f32_16x16x32_bf16 v[18:21], v[154:157], v[178:181], v[18:21]
	v_mfma_f32_16x16x32_bf16 v[6:9], v[146:149], v[204:207], v[6:9]
	v_mfma_f32_16x16x32_bf16 v[2:5], v[154:157], v[204:207], v[2:5]
	v_mfma_f32_16x16x32_bf16 v[54:57], v[150:153], v[166:169], v[54:57]
	v_mfma_f32_16x16x32_bf16 v[50:53], v[158:161], v[166:169], v[50:53]
	v_mfma_f32_16x16x32_bf16 v[38:41], v[150:153], v[174:177], v[38:41]
	v_mfma_f32_16x16x32_bf16 v[34:37], v[158:161], v[174:177], v[34:37]
	v_mfma_f32_16x16x32_bf16 v[22:25], v[150:153], v[182:185], v[22:25]
	v_mfma_f32_16x16x32_bf16 v[18:21], v[158:161], v[182:185], v[18:21]
	v_mfma_f32_16x16x32_bf16 v[6:9], v[150:153], v[208:211], v[6:9]
	v_mfma_f32_16x16x32_bf16 v[2:5], v[158:161], v[208:211], v[2:5]
	s_barrier
	s_add_i32 s68, 0, 0x18000
	s_add_i32 s69, 0, 0x1c000
	ds_read_b128 v[114:117], v203
	ds_read_b128 v[126:129], v203 offset:1024
	ds_read_b128 v[138:141], v203 offset:2048
	ds_read_b128 v[142:145], v203 offset:3072
	ds_read_b128 v[146:149], v216
	ds_read_b128 v[150:153], v216 offset:1024
	ds_read_b128 v[154:157], v216 offset:2048
	ds_read_b128 v[158:161], v216 offset:3072
	s_add_u32 s30, s44, 0x180000
	s_addc_u32 s31, s45, 0
	s_mov_b32 m0, s54
	ds_read_b128 v[162:165], v235 offset:32768
	ds_read_b128 v[166:169], v235 offset:33792
	ds_read_b128 v[170:173], v235 offset:34816
	ds_read_b128 v[174:177], v235 offset:35840
	ds_read_b128 v[178:181], v235 offset:36864
	ds_read_b128 v[182:185], v235 offset:37888
	ds_read_b128 v[204:207], v235 offset:38912
	ds_read_b128 v[208:211], v235 offset:39936
	global_load_lds_dwordx4 v194, s[30:31]
	s_mov_b32 m0, s55
	s_nop 0
	global_load_lds_dwordx4 v196, s[30:31]
	s_waitcnt vmcnt(8)
	s_waitcnt lgkmcnt(0)
	s_barrier
; #define PG8_STAGE(bufoff, gbase, voff) do { _Pragma("unroll") for (int _i = 0; _i < 2; ++_i) \
;         __builtin_amdgcn_global_load_lds((const unsigned*)((const char*)(gbase) + (voff)[_i]), (PG8_LAS unsigned*)(lds + (bufoff) + ldsw + _i * 8192), 16, 0, 0); } while (0)
; #define PG8_LDA(dst, b, h) do { _Pragma("unroll") for (int m = 0; m < 4; ++m) _Pragma("unroll") for (int k = 0; k < 2; ++k) dst[m][k] = *(const PG8_LAS bf16x8*)(lds + PG8_SA(b, h) + aoff + m * 2048 + k * 1024); } while (0)
; #define PG8_MMA(ai, bj, At, Bt) do { __builtin_amdgcn_s_setprio(1); _Pragma("unroll") for (int m = 0; m < 4; ++m) _Pragma("unroll") for (int n = 0; n < 2; ++n) _Pragma("unroll") for (int k = 0; k < 2; ++k) \
;         acc[ai][bj][m][n] = __builtin_amdgcn_mfma_f32_16x16x32_bf16(Bt[n][k], At[m][k], acc[ai][bj][m][n], 0, 0, 0); __builtin_amdgcn_s_setprio(0); } while (0)
; #define PG8_WAIT_V(n) asm volatile("s_waitcnt vmcnt(" #n ")" ::: "memory")
; #define PG8_WAIT_L(n) asm volatile("s_waitcnt lgkmcnt(" #n ")" ::: "memory")
; #define PG8_BAR __builtin_amdgcn_s_barrier()
; #define PG8_SCHED __builtin_amdgcn_sched_barrier(0)
; template <class Epi, class Sched, bool ALIGN_EPI = false, bool SP2 = false>
; __device__ __forceinline__ void gemm_phase(PG8_LAS unsigned char* lds, const Gemm g, const Sched& S, const Epi& E, const int wv) {
;     ...
;         for (int t = 0; t < nt; t += 2) {
;     ...
;             PG8_WAIT_V(8); PG8_WAIT_L(0); PG8_BAR; PG8_MMA(0, 0, At, B0); PG8_MMA(0, 1, At, B1); PG8_BAR; PG8_SCHED;
;             PG8_LDA(At, 1, 1); PG8_STAGE(PG8_SB(1, 0), b3, voffB); PG8_STAGE(PG8_SB(1, 1), b3 + hstepB, voffB); PG8_STAGE(PG8_SA(1, 0), a3, voffA);
;             PG8_WAIT_V(8); PG8_WAIT_L(0); PG8_BAR; PG8_MMA(1, 0, At, B0); PG8_MMA(1, 1, At, B1); PG8_BAR; PG8_SCHED;
	v_mfma_f32_16x16x32_bf16 v[134:137], v[114:117], v[162:165], v[134:137]
	v_mfma_f32_16x16x32_bf16 v[130:133], v[138:141], v[162:165], v[130:133]
	v_mfma_f32_16x16x32_bf16 v[110:113], v[114:117], v[170:173], v[110:113]
	v_mfma_f32_16x16x32_bf16 v[106:109], v[138:141], v[170:173], v[106:109]
	v_mfma_f32_16x16x32_bf16 v[94:97], v[114:117], v[178:181], v[94:97]
	v_mfma_f32_16x16x32_bf16 v[90:93], v[138:141], v[178:181], v[90:93]
	v_mfma_f32_16x16x32_bf16 v[78:81], v[114:117], v[204:207], v[78:81]
	v_mfma_f32_16x16x32_bf16 v[74:77], v[138:141], v[204:207], v[74:77]
	v_mfma_f32_16x16x32_bf16 v[134:137], v[126:129], v[166:169], v[134:137]
	v_mfma_f32_16x16x32_bf16 v[130:133], v[142:145], v[166:169], v[130:133]
	v_mfma_f32_16x16x32_bf16 v[110:113], v[126:129], v[174:177], v[110:113]
	v_mfma_f32_16x16x32_bf16 v[106:109], v[142:145], v[174:177], v[106:109]
	v_mfma_f32_16x16x32_bf16 v[94:97], v[126:129], v[182:185], v[94:97]
	v_mfma_f32_16x16x32_bf16 v[90:93], v[142:145], v[182:185], v[90:93]
	v_mfma_f32_16x16x32_bf16 v[78:81], v[126:129], v[208:211], v[78:81]
	v_mfma_f32_16x16x32_bf16 v[74:77], v[142:145], v[208:211], v[74:77]
	v_mfma_f32_16x16x32_bf16 v[122:125], v[146:149], v[162:165], v[122:125]
	v_mfma_f32_16x16x32_bf16 v[118:121], v[154:157], v[162:165], v[118:121]
	v_mfma_f32_16x16x32_bf16 v[102:105], v[146:149], v[170:173], v[102:105]
	v_mfma_f32_16x16x32_bf16 v[98:101], v[154:157], v[170:173], v[98:101]
	v_mfma_f32_16x16x32_bf16 v[86:89], v[146:149], v[178:181], v[86:89]
	v_mfma_f32_16x16x32_bf16 v[82:85], v[154:157], v[178:181], v[82:85]
	v_mfma_f32_16x16x32_bf16 v[70:73], v[146:149], v[204:207], v[70:73]
	v_mfma_f32_16x16x32_bf16 v[66:69], v[154:157], v[204:207], v[66:69]
	v_mfma_f32_16x16x32_bf16 v[122:125], v[150:153], v[166:169], v[122:125]
	v_mfma_f32_16x16x32_bf16 v[118:121], v[158:161], v[166:169], v[118:121]
	v_mfma_f32_16x16x32_bf16 v[102:105], v[150:153], v[174:177], v[102:105]
	v_mfma_f32_16x16x32_bf16 v[98:101], v[158:161], v[174:177], v[98:101]
	v_mfma_f32_16x16x32_bf16 v[86:89], v[150:153], v[182:185], v[86:89]
	v_mfma_f32_16x16x32_bf16 v[82:85], v[158:161], v[182:185], v[82:85]
	v_mfma_f32_16x16x32_bf16 v[70:73], v[150:153], v[208:211], v[70:73]
	v_mfma_f32_16x16x32_bf16 v[66:69], v[158:161], v[208:211], v[66:69]
	s_barrier
	s_add_i32 s30, s68, s47
	s_add_i32 m0, s30, 0xffffff80
	ds_read_b128 v[162:165], v235 offset:49152
	ds_read_b128 v[166:169], v235 offset:50176
	ds_read_b128 v[170:173], v235 offset:51200
	ds_read_b128 v[174:177], v235 offset:52224
	ds_read_b128 v[178:181], v235 offset:53248
	ds_read_b128 v[182:185], v235 offset:54272
	ds_read_b128 v[204:207], v235 offset:55296
	ds_read_b128 v[208:211], v235 offset:56320
	global_load_lds_dwordx4 v[190:191], off offset:128
	s_add_i32 m0, s30, 0x1f80
	s_add_i32 s30, s69, s47
	global_load_lds_dwordx4 v[192:193], off offset:128
	s_add_i32 m0, s30, 0xffffff80
	s_nop 0
	global_load_lds_dwordx4 v[212:213], off offset:128
	s_add_i32 m0, s30, 0x1f80
	s_nop 0
	global_load_lds_dwordx4 v[214:215], off offset:128
	s_add_i32 m0, s57, 0xffffff80
	s_nop 0
	global_load_lds_dwordx4 v194, s[44:45] offset:128
	s_add_i32 m0, s58, 0xffffff80
	s_nop 0
	global_load_lds_dwordx4 v196, s[44:45] offset:128
	s_waitcnt vmcnt(8)
	s_waitcnt lgkmcnt(0)
	s_barrier
	v_mfma_f32_16x16x32_bf16 v[62:65], v[114:117], v[162:165], v[62:65]
	v_mfma_f32_16x16x32_bf16 v[58:61], v[138:141], v[162:165], v[58:61]
	v_mfma_f32_16x16x32_bf16 v[46:49], v[114:117], v[170:173], v[46:49]
	v_mfma_f32_16x16x32_bf16 v[42:45], v[138:141], v[170:173], v[42:45]
	v_mfma_f32_16x16x32_bf16 v[30:33], v[114:117], v[178:181], v[30:33]
	v_mfma_f32_16x16x32_bf16 v[26:29], v[138:141], v[178:181], v[26:29]
	v_mfma_f32_16x16x32_bf16 v[14:17], v[114:117], v[204:207], v[14:17]
	v_mfma_f32_16x16x32_bf16 v[10:13], v[138:141], v[204:207], v[10:13]
	v_mfma_f32_16x16x32_bf16 v[62:65], v[126:129], v[166:169], v[62:65]
	v_mfma_f32_16x16x32_bf16 v[58:61], v[142:145], v[166:169], v[58:61]
	v_mfma_f32_16x16x32_bf16 v[46:49], v[126:129], v[174:177], v[46:49]
	v_mfma_f32_16x16x32_bf16 v[42:45], v[142:145], v[174:177], v[42:45]
	v_mfma_f32_16x16x32_bf16 v[30:33], v[126:129], v[182:185], v[30:33]
	v_mfma_f32_16x16x32_bf16 v[26:29], v[142:145], v[182:185], v[26:29]
	v_mfma_f32_16x16x32_bf16 v[14:17], v[126:129], v[208:211], v[14:17]
	v_mfma_f32_16x16x32_bf16 v[10:13], v[142:145], v[208:211], v[10:13]
	v_mfma_f32_16x16x32_bf16 v[54:57], v[146:149], v[162:165], v[54:57]
	v_mfma_f32_16x16x32_bf16 v[50:53], v[154:157], v[162:165], v[50:53]
	v_mfma_f32_16x16x32_bf16 v[38:41], v[146:149], v[170:173], v[38:41]
	v_mfma_f32_16x16x32_bf16 v[34:37], v[154:157], v[170:173], v[34:37]
	v_mfma_f32_16x16x32_bf16 v[22:25], v[146:149], v[178:181], v[22:25]
	v_mfma_f32_16x16x32_bf16 v[18:21], v[154:157], v[178:181], v[18:21]
	v_mfma_f32_16x16x32_bf16 v[6:9], v[146:149], v[204:207], v[6:9]
	v_mfma_f32_16x16x32_bf16 v[2:5], v[154:157], v[204:207], v[2:5]
	v_mfma_f32_16x16x32_bf16 v[54:57], v[150:153], v[166:169], v[54:57]
	v_mfma_f32_16x16x32_bf16 v[50:53], v[158:161], v[166:169], v[50:53]
	v_mfma_f32_16x16x32_bf16 v[38:41], v[150:153], v[174:177], v[38:41]
	v_mfma_f32_16x16x32_bf16 v[34:37], v[158:161], v[174:177], v[34:37]
	v_mfma_f32_16x16x32_bf16 v[22:25], v[150:153], v[182:185], v[22:25]
	v_mfma_f32_16x16x32_bf16 v[18:21], v[158:161], v[182:185], v[18:21]
	v_mfma_f32_16x16x32_bf16 v[6:9], v[150:153], v[208:211], v[6:9]
	v_mfma_f32_16x16x32_bf16 v[2:5], v[158:161], v[208:211], v[2:5]
	s_barrier
	s_add_u32 s65, s65, 0x100
	s_addc_u32 s66, s66, 0
	s_cmp_ge_i32 s67, s56
	s_mov_b64 s[30:31], s[34:35]
	s_mov_b32 s44, s67
	s_cbranch_scc0 .LBB0_990
	s_movk_i32 s68, 0x4000
	s_movk_i32 s69, 0x6000
	s_mov_b32 s70, 0x18000
	s_mov_b32 s71, 0x3f317217
	v_readlane_b32 s67, v255, 30
	s_and_b64 vcc, exec, s[28:29]
	s_cbranch_vccz .LBB0_966

; template <class Epi, class Sched, bool ALIGN_EPI = false, bool SP2 = false>
; __device__ __forceinline__ void gemm_phase(PG8_LAS unsigned char* lds, const Gemm g, const Sched& S, const Epi& E, const int wv) {
;     ...
; #pragma unroll
;     for (int a = 0; a < 2; ++a)
; #pragma unroll
;         for (int b = 0; b < 2; ++b)
; #pragma unroll
;             for (int m = 0; m < 4; ++m)
; #pragma unroll
;                 for (int n = 0; n < 2; ++n) acc[a][b][m][n] = (f32x4){0.f, 0.f, 0.f, 0.f};
;     ...
;         const char* nA = has_next ? (const char*)g.A + (size_t)nxt.pm * tstepA + (g.amod ? (size_t)(nxt.pn % g.amod) * K * 2 : (size_t)0) : cA; const char* nB = has_next ? (const char*)g.Bt + (size_t)nxt.pn * tstepB : cB;
;         for (int t = 0; t < nt; t += 2) {
;             const bool last = (t == nt - 2);
;             const char* a1 = cA + (size_t)(t + 1) * kstep;
;             const char* a2 = last ? nA : cA + (size_t)(t + 2) * kstep; const char* b2 = last ? nB : cB + (size_t)(t + 2) * kstep;
.LBB0_1072:
	s_ashr_i32 s17, s16, 31
	s_lshl_b64 s[24:25], s[16:17], 20
	s_add_u32 s24, s43, s24
	v_mov_b32_e32 v133, 0
	s_addc_u32 s25, s44, s25
	s_andn2_b64 vcc, exec, s[12:13]
	v_mov_b32_e32 v132, v133
	v_pk_mov_b32 v[130:131], v[132:133], v[132:133]
	v_pk_mov_b32 v[128:129], v[132:133], v[132:133]
	v_pk_mov_b32 v[126:127], v[132:133], v[132:133]
	v_pk_mov_b32 v[116:117], v[132:133], v[132:133]
	v_pk_mov_b32 v[114:115], v[132:133], v[132:133]
	v_pk_mov_b32 v[112:113], v[132:133], v[132:133]
	v_pk_mov_b32 v[110:111], v[132:133], v[132:133]
	v_pk_mov_b32 v[100:101], v[132:133], v[132:133]
	v_pk_mov_b32 v[98:99], v[132:133], v[132:133]
	s_nop 0
	v_pk_mov_b32 v[96:97], v[132:133], v[132:133]
	v_pk_mov_b32 v[94:95], v[132:133], v[132:133]
	v_pk_mov_b32 v[84:85], v[132:133], v[132:133]
	v_pk_mov_b32 v[82:83], v[132:133], v[132:133]
	v_pk_mov_b32 v[80:81], v[132:133], v[132:133]
	v_pk_mov_b32 v[78:79], v[132:133], v[132:133]
	v_pk_mov_b32 v[124:125], v[132:133], v[132:133]
	v_pk_mov_b32 v[122:123], v[132:133], v[132:133]
	v_pk_mov_b32 v[120:121], v[132:133], v[132:133]
	v_pk_mov_b32 v[118:119], v[132:133], v[132:133]
	v_pk_mov_b32 v[108:109], v[132:133], v[132:133]
	v_pk_mov_b32 v[106:107], v[132:133], v[132:133]
	v_pk_mov_b32 v[104:105], v[132:133], v[132:133]
	v_pk_mov_b32 v[102:103], v[132:133], v[132:133]
	v_pk_mov_b32 v[92:93], v[132:133], v[132:133]
	v_pk_mov_b32 v[90:91], v[132:133], v[132:133]
	v_pk_mov_b32 v[88:89], v[132:133], v[132:133]
	v_pk_mov_b32 v[86:87], v[132:133], v[132:133]
	v_pk_mov_b32 v[76:77], v[132:133], v[132:133]
	v_pk_mov_b32 v[74:75], v[132:133], v[132:133]
	v_pk_mov_b32 v[72:73], v[132:133], v[132:133]
	v_pk_mov_b32 v[70:71], v[132:133], v[132:133]
	v_pk_mov_b32 v[68:69], v[132:133], v[132:133]
	v_pk_mov_b32 v[66:67], v[132:133], v[132:133]
	v_pk_mov_b32 v[64:65], v[132:133], v[132:133]
	v_pk_mov_b32 v[62:63], v[132:133], v[132:133]
	v_pk_mov_b32 v[52:53], v[132:133], v[132:133]
	v_pk_mov_b32 v[50:51], v[132:133], v[132:133]
	v_pk_mov_b32 v[48:49], v[132:133], v[132:133]
	v_pk_mov_b32 v[46:47], v[132:133], v[132:133]
	v_pk_mov_b32 v[36:37], v[132:133], v[132:133]
	v_pk_mov_b32 v[34:35], v[132:133], v[132:133]
	v_pk_mov_b32 v[32:33], v[132:133], v[132:133]
	v_pk_mov_b32 v[30:31], v[132:133], v[132:133]
	v_pk_mov_b32 v[20:21], v[132:133], v[132:133]
	v_pk_mov_b32 v[18:19], v[132:133], v[132:133]
	v_pk_mov_b32 v[16:17], v[132:133], v[132:133]
	v_pk_mov_b32 v[14:15], v[132:133], v[132:133]
	v_pk_mov_b32 v[60:61], v[132:133], v[132:133]
	v_pk_mov_b32 v[58:59], v[132:133], v[132:133]
	v_pk_mov_b32 v[56:57], v[132:133], v[132:133]
	v_pk_mov_b32 v[54:55], v[132:133], v[132:133]
	v_pk_mov_b32 v[44:45], v[132:133], v[132:133]
	v_pk_mov_b32 v[42:43], v[132:133], v[132:133]
	v_pk_mov_b32 v[40:41], v[132:133], v[132:133]
	v_pk_mov_b32 v[38:39], v[132:133], v[132:133]
	v_pk_mov_b32 v[28:29], v[132:133], v[132:133]
	v_pk_mov_b32 v[26:27], v[132:133], v[132:133]
	v_pk_mov_b32 v[24:25], v[132:133], v[132:133]
	v_pk_mov_b32 v[22:23], v[132:133], v[132:133]
	v_pk_mov_b32 v[12:13], v[132:133], v[132:133]
	v_pk_mov_b32 v[10:11], v[132:133], v[132:133]
	v_pk_mov_b32 v[8:9], v[132:133], v[132:133]
	v_pk_mov_b32 v[6:7], v[132:133], v[132:133]
	s_cbranch_vccnz .LBB0_1076
	s_and_b64 s[40:41], s[40:41], exec
	s_cselect_b32 s17, s25, s29
	s_cselect_b32 s40, s24, s28
	s_add_u32 s28, s28, 0x80080
	s_addc_u32 s29, s29, 0
	s_add_u32 s41, s30, 0x100
	v_mov_b32_e32 v6, 0
	s_addc_u32 s62, s31, 0
	s_mov_b32 s30, 0
	v_mov_b32_e32 v7, v6
	v_pk_mov_b32 v[8:9], v[6:7], v[6:7]
	v_pk_mov_b32 v[10:11], v[6:7], v[6:7]
	v_pk_mov_b32 v[12:13], v[6:7], v[6:7]
	v_pk_mov_b32 v[22:23], v[6:7], v[6:7]
	v_pk_mov_b32 v[24:25], v[6:7], v[6:7]
	v_pk_mov_b32 v[26:27], v[6:7], v[6:7]
	v_pk_mov_b32 v[28:29], v[6:7], v[6:7]
	v_pk_mov_b32 v[38:39], v[6:7], v[6:7]
	v_pk_mov_b32 v[40:41], v[6:7], v[6:7]
	v_pk_mov_b32 v[42:43], v[6:7], v[6:7]
	v_pk_mov_b32 v[44:45], v[6:7], v[6:7]
	v_pk_mov_b32 v[54:55], v[6:7], v[6:7]
	v_pk_mov_b32 v[56:57], v[6:7], v[6:7]
	v_pk_mov_b32 v[58:59], v[6:7], v[6:7]
	v_pk_mov_b32 v[60:61], v[6:7], v[6:7]
	v_pk_mov_b32 v[14:15], v[6:7], v[6:7]
	v_pk_mov_b32 v[16:17], v[6:7], v[6:7]
	v_pk_mov_b32 v[18:19], v[6:7], v[6:7]
	v_pk_mov_b32 v[20:21], v[6:7], v[6:7]
	v_pk_mov_b32 v[30:31], v[6:7], v[6:7]
	v_pk_mov_b32 v[32:33], v[6:7], v[6:7]
	v_pk_mov_b32 v[34:35], v[6:7], v[6:7]
	v_pk_mov_b32 v[36:37], v[6:7], v[6:7]
	v_pk_mov_b32 v[46:47], v[6:7], v[6:7]
	v_pk_mov_b32 v[48:49], v[6:7], v[6:7]
	v_pk_mov_b32 v[50:51], v[6:7], v[6:7]
	v_pk_mov_b32 v[52:53], v[6:7], v[6:7]
	v_pk_mov_b32 v[62:63], v[6:7], v[6:7]
	v_pk_mov_b32 v[64:65], v[6:7], v[6:7]
	v_pk_mov_b32 v[66:67], v[6:7], v[6:7]
	v_pk_mov_b32 v[68:69], v[6:7], v[6:7]
	v_pk_mov_b32 v[70:71], v[6:7], v[6:7]
	v_pk_mov_b32 v[72:73], v[6:7], v[6:7]
	v_pk_mov_b32 v[74:75], v[6:7], v[6:7]
	v_pk_mov_b32 v[76:77], v[6:7], v[6:7]
	v_pk_mov_b32 v[86:87], v[6:7], v[6:7]
	v_pk_mov_b32 v[88:89], v[6:7], v[6:7]
	v_pk_mov_b32 v[90:91], v[6:7], v[6:7]
	v_pk_mov_b32 v[92:93], v[6:7], v[6:7]
	v_pk_mov_b32 v[102:103], v[6:7], v[6:7]
	v_pk_mov_b32 v[104:105], v[6:7], v[6:7]
	v_pk_mov_b32 v[106:107], v[6:7], v[6:7]
	v_pk_mov_b32 v[108:109], v[6:7], v[6:7]
	v_pk_mov_b32 v[118:119], v[6:7], v[6:7]
	v_pk_mov_b32 v[120:121], v[6:7], v[6:7]
	v_pk_mov_b32 v[122:123], v[6:7], v[6:7]
	v_pk_mov_b32 v[124:125], v[6:7], v[6:7]
	v_pk_mov_b32 v[78:79], v[6:7], v[6:7]
	v_pk_mov_b32 v[80:81], v[6:7], v[6:7]
	v_pk_mov_b32 v[82:83], v[6:7], v[6:7]
	v_pk_mov_b32 v[84:85], v[6:7], v[6:7]
	v_pk_mov_b32 v[94:95], v[6:7], v[6:7]
	v_pk_mov_b32 v[96:97], v[6:7], v[6:7]
	v_pk_mov_b32 v[98:99], v[6:7], v[6:7]
	v_pk_mov_b32 v[100:101], v[6:7], v[6:7]
	v_pk_mov_b32 v[110:111], v[6:7], v[6:7]
	v_pk_mov_b32 v[112:113], v[6:7], v[6:7]
	v_pk_mov_b32 v[114:115], v[6:7], v[6:7]
	v_pk_mov_b32 v[116:117], v[6:7], v[6:7]
	v_pk_mov_b32 v[126:127], v[6:7], v[6:7]
	v_pk_mov_b32 v[128:129], v[6:7], v[6:7]
	v_pk_mov_b32 v[130:131], v[6:7], v[6:7]
	v_pk_mov_b32 v[132:133], v[6:7], v[6:7]
	v_add_u32_e32 v147, 0x10000, v157
	v_add_u32_e32 v149, 0x14000, v157
	v_add_u32_e32 v152, 0x18000, v157
	v_add_u32_e32 v154, 0x1c000, v157
; #define PG8_STAGE(bufoff, gbase, voff) do { _Pragma("unroll") for (int _i = 0; _i < 2; ++_i) \
;         __builtin_amdgcn_global_load_lds((const unsigned*)((const char*)(gbase) + (voff)[_i]), (PG8_LAS unsigned*)(lds + (bufoff) + ldsw + _i * 8192), 16, 0, 0); } while (0)
; #define PG8_LDA(dst, b, h) do { _Pragma("unroll") for (int m = 0; m < 4; ++m) _Pragma("unroll") for (int k = 0; k < 2; ++k) dst[m][k] = *(const PG8_LAS bf16x8*)(lds + PG8_SA(b, h) + aoff + m * 2048 + k * 1024); } while (0)
; #define PG8_LDB(dst, b, h) do { _Pragma("unroll") for (int n = 0; n < 2; ++n) _Pragma("unroll") for (int k = 0; k < 2; ++k) dst[n][k] = *(const PG8_LAS bf16x8*)(lds + PG8_SB(b, h) + boff + n * 2048 + k * 1024); } while (0)
; #define PG8_MMA(ai, bj, At, Bt) do { __builtin_amdgcn_s_setprio(1); _Pragma("unroll") for (int m = 0; m < 4; ++m) _Pragma("unroll") for (int n = 0; n < 2; ++n) _Pragma("unroll") for (int k = 0; k < 2; ++k) \
;         acc[ai][bj][m][n] = __builtin_amdgcn_mfma_f32_16x16x32_bf16(Bt[n][k], At[m][k], acc[ai][bj][m][n], 0, 0, 0); __builtin_amdgcn_s_setprio(0); } while (0)
; #define PG8_WAIT_V(n) asm volatile("s_waitcnt vmcnt(" #n ")" ::: "memory")
; #define PG8_WAIT_L(n) asm volatile("s_waitcnt lgkmcnt(" #n ")" ::: "memory")
; template <class Epi, class Sched, bool ALIGN_EPI = false, bool SP2 = false>
; __device__ __forceinline__ void gemm_phase(PG8_LAS unsigned char* lds, const Gemm g, const Sched& S, const Epi& E, const int wv) {
;     ...
;             const bool last = (t == nt - 2);
;             const char* a1 = cA + (size_t)(t + 1) * kstep;
;             const char* a2 = last ? nA : cA + (size_t)(t + 2) * kstep; const char* b2 = last ? nB : cB + (size_t)(t + 2) * kstep;
;             const char* a3 = a2 + kstep; const char* b3 = b2 + kstep;
;             if (last && has_next) S.a_ready(nxt);
;             if constexpr (SP2) {
;             PG8_LDB(B0, 0, 0); PG8_LDB(B1, 0, 1); PG8_SCHED; PG8_LDA(At, 0, 0); PG8_STAGE(PG8_SA(1, 1), a1 + hstepA, voffA);
;             PG8_WAIT_V(8); PG8_WAIT_L(0); PG8_BAR; PG8_MMA(0, 0, At, B0); PG8_MMA(0, 1, At, B1); PG8_BAR; PG8_SCHED;
;             PG8_LDA(At, 0, 1); PG8_STAGE(PG8_SB(0, 0), b2, voffB); PG8_STAGE(PG8_SB(0, 1), b2 + hstepB, voffB); PG8_STAGE(PG8_SA(0, 0), a2, voffA);
;             PG8_WAIT_V(8); PG8_WAIT_L(0); PG8_BAR; PG8_MMA(1, 0, At, B0); PG8_MMA(1, 1, At, B1); PG8_BAR; PG8_SCHED;
.LBB0_1074:
	s_add_i32 s63, s30, 2
	s_add_u32 s64, s28, 0xfff80080
	s_addc_u32 s31, s29, -1
	s_add_i32 s66, 0, 0x10000
	s_cmp_eq_u32 s57, s30
	s_cselect_b32 s31, s17, s31
	s_cselect_b32 s30, s40, s64
	s_cselect_b32 s65, s19, s62
	s_cselect_b32 s64, s18, s41
	s_add_i32 s67, 0, 0x14000
	ds_read_b128 v[164:167], v147
	ds_read_b128 v[168:171], v147 offset:1024
	ds_read_b128 v[172:175], v147 offset:2048
	ds_read_b128 v[176:179], v147 offset:3072
	ds_read_b128 v[180:183], v149
	ds_read_b128 v[194:197], v149 offset:1024
	ds_read_b128 v[198:201], v149 offset:2048
	ds_read_b128 v[202:205], v149 offset:3072
	s_add_i32 m0, s47, 0xc000
	ds_read_b128 v[206:209], v163
	ds_read_b128 v[210:213], v163 offset:1024
	ds_read_b128 v[214:217], v163 offset:2048
	ds_read_b128 v[228:231], v163 offset:3072
	ds_read_b128 v[232:235], v163 offset:4096
	ds_read_b128 v[236:239], v163 offset:5120
	ds_read_b128 v[240:243], v163 offset:6144
	ds_read_b128 v[244:247], v163 offset:7168
	global_load_lds_dwordx4 v146, s[28:29]
	s_add_i32 m0, s47, 0xe000
	s_nop 0
	global_load_lds_dwordx4 v148, s[28:29]
	s_waitcnt vmcnt(8)
	s_waitcnt lgkmcnt(0)
	s_barrier
	v_mfma_f32_16x16x32_bf16 v[130:133], v[164:167], v[206:209], v[130:133]
	v_mfma_f32_16x16x32_bf16 v[126:129], v[172:175], v[206:209], v[126:129]
	v_mfma_f32_16x16x32_bf16 v[114:117], v[164:167], v[214:217], v[114:117]
	v_mfma_f32_16x16x32_bf16 v[110:113], v[172:175], v[214:217], v[110:113]
	v_mfma_f32_16x16x32_bf16 v[98:101], v[164:167], v[232:235], v[98:101]
	v_mfma_f32_16x16x32_bf16 v[94:97], v[172:175], v[232:235], v[94:97]
	v_mfma_f32_16x16x32_bf16 v[82:85], v[164:167], v[240:243], v[82:85]
	v_mfma_f32_16x16x32_bf16 v[78:81], v[172:175], v[240:243], v[78:81]
	v_mfma_f32_16x16x32_bf16 v[130:133], v[168:171], v[210:213], v[130:133]
	v_mfma_f32_16x16x32_bf16 v[126:129], v[176:179], v[210:213], v[126:129]
	v_mfma_f32_16x16x32_bf16 v[114:117], v[168:171], v[228:231], v[114:117]
	v_mfma_f32_16x16x32_bf16 v[110:113], v[176:179], v[228:231], v[110:113]
	v_mfma_f32_16x16x32_bf16 v[98:101], v[168:171], v[236:239], v[98:101]
	v_mfma_f32_16x16x32_bf16 v[94:97], v[176:179], v[236:239], v[94:97]
	v_mfma_f32_16x16x32_bf16 v[82:85], v[168:171], v[244:247], v[82:85]
	v_mfma_f32_16x16x32_bf16 v[78:81], v[176:179], v[244:247], v[78:81]
	v_mfma_f32_16x16x32_bf16 v[122:125], v[180:183], v[206:209], v[122:125]
	v_mfma_f32_16x16x32_bf16 v[118:121], v[198:201], v[206:209], v[118:121]
	v_mfma_f32_16x16x32_bf16 v[106:109], v[180:183], v[214:217], v[106:109]
	v_mfma_f32_16x16x32_bf16 v[102:105], v[198:201], v[214:217], v[102:105]
	v_mfma_f32_16x16x32_bf16 v[90:93], v[180:183], v[232:235], v[90:93]
	v_mfma_f32_16x16x32_bf16 v[86:89], v[198:201], v[232:235], v[86:89]
	v_mfma_f32_16x16x32_bf16 v[74:77], v[180:183], v[240:243], v[74:77]
	v_mfma_f32_16x16x32_bf16 v[70:73], v[198:201], v[240:243], v[70:73]
	v_mfma_f32_16x16x32_bf16 v[122:125], v[194:197], v[210:213], v[122:125]
	v_mfma_f32_16x16x32_bf16 v[118:121], v[202:205], v[210:213], v[118:121]
	v_mfma_f32_16x16x32_bf16 v[106:109], v[194:197], v[228:231], v[106:109]
	v_mfma_f32_16x16x32_bf16 v[102:105], v[202:205], v[228:231], v[102:105]
	v_mfma_f32_16x16x32_bf16 v[90:93], v[194:197], v[236:239], v[90:93]
	v_mfma_f32_16x16x32_bf16 v[86:89], v[202:205], v[236:239], v[86:89]
	v_mfma_f32_16x16x32_bf16 v[74:77], v[194:197], v[244:247], v[74:77]
	v_mfma_f32_16x16x32_bf16 v[70:73], v[202:205], v[244:247], v[70:73]
	s_barrier
	s_add_i32 s66, s66, s45
	v_lshl_add_u64 v[150:151], s[64:65], 0, v[138:139]
	s_mov_b32 m0, s66
	ds_read_b128 v[206:209], v163 offset:16384
	ds_read_b128 v[210:213], v163 offset:17408
	ds_read_b128 v[214:217], v163 offset:18432
	ds_read_b128 v[228:231], v163 offset:19456
	ds_read_b128 v[232:235], v163 offset:20480
	ds_read_b128 v[236:239], v163 offset:21504
	ds_read_b128 v[240:243], v163 offset:22528
	ds_read_b128 v[244:247], v163 offset:23552
	global_load_lds_dwordx4 v[150:151], off
	s_add_i32 m0, s66, 0x2000
	v_lshl_add_u64 v[184:185], s[64:65], 0, v[134:135]
	s_add_u32 s64, s64, s0
	s_addc_u32 s65, s65, s1
	s_add_i32 s66, s67, s45
	global_load_lds_dwordx4 v[184:185], off
	v_lshl_add_u64 v[190:191], s[64:65], 0, v[138:139]
	s_mov_b32 m0, s66
	v_lshl_add_u64 v[192:193], s[64:65], 0, v[134:135]
	global_load_lds_dwordx4 v[190:191], off
	s_add_i32 m0, s66, 0x2000
	v_lshl_add_u64 v[218:219], s[30:31], 0, v[140:141]
	global_load_lds_dwordx4 v[192:193], off
	s_mov_b32 m0, s47
	v_lshl_add_u64 v[248:249], s[30:31], 0, v[136:137]
	global_load_lds_dwordx4 v[218:219], off
	s_mov_b32 m0, s48
	s_nop 0
	global_load_lds_dwordx4 v[248:249], off
	s_waitcnt vmcnt(8)
	s_waitcnt lgkmcnt(0)
	s_barrier
; #define PG8_STAGE(bufoff, gbase, voff) do { _Pragma("unroll") for (int _i = 0; _i < 2; ++_i) \
;         __builtin_amdgcn_global_load_lds((const unsigned*)((const char*)(gbase) + (voff)[_i]), (PG8_LAS unsigned*)(lds + (bufoff) + ldsw + _i * 8192), 16, 0, 0); } while (0)
; #define PG8_LDA(dst, b, h) do { _Pragma("unroll") for (int m = 0; m < 4; ++m) _Pragma("unroll") for (int k = 0; k < 2; ++k) dst[m][k] = *(const PG8_LAS bf16x8*)(lds + PG8_SA(b, h) + aoff + m * 2048 + k * 1024); } while (0)
; #define PG8_LDB(dst, b, h) do { _Pragma("unroll") for (int n = 0; n < 2; ++n) _Pragma("unroll") for (int k = 0; k < 2; ++k) dst[n][k] = *(const PG8_LAS bf16x8*)(lds + PG8_SB(b, h) + boff + n * 2048 + k * 1024); } while (0)
; #define PG8_MMA(ai, bj, At, Bt) do { __builtin_amdgcn_s_setprio(1); _Pragma("unroll") for (int m = 0; m < 4; ++m) _Pragma("unroll") for (int n = 0; n < 2; ++n) _Pragma("unroll") for (int k = 0; k < 2; ++k) \
;         acc[ai][bj][m][n] = __builtin_amdgcn_mfma_f32_16x16x32_bf16(Bt[n][k], At[m][k], acc[ai][bj][m][n], 0, 0, 0); __builtin_amdgcn_s_setprio(0); } while (0)
; #define PG8_WAIT_V(n) asm volatile("s_waitcnt vmcnt(" #n ")" ::: "memory")
; #define PG8_WAIT_L(n) asm volatile("s_waitcnt lgkmcnt(" #n ")" ::: "memory")
; #define PG8_BAR __builtin_amdgcn_s_barrier()
; #define PG8_SCHED __builtin_amdgcn_sched_barrier(0)
; template <class Epi, class Sched, bool ALIGN_EPI = false, bool SP2 = false>
; __device__ __forceinline__ void gemm_phase(PG8_LAS unsigned char* lds, const Gemm g, const Sched& S, const Epi& E, const int wv) {
;     ...
;             PG8_WAIT_V(8); PG8_WAIT_L(0); PG8_BAR; PG8_MMA(1, 0, At, B0); PG8_MMA(1, 1, At, B1); PG8_BAR; PG8_SCHED;
;             PG8_LDB(B0, 1, 0); PG8_LDB(B1, 1, 1); PG8_SCHED; PG8_LDA(At, 1, 0); PG8_STAGE(PG8_SA(0, 1), a2 + hstepA, voffA);
;             PG8_WAIT_V(8); PG8_WAIT_L(0); PG8_BAR; PG8_MMA(0, 0, At, B0); PG8_MMA(0, 1, At, B1); PG8_BAR; PG8_SCHED;
	v_mfma_f32_16x16x32_bf16 v[66:69], v[164:167], v[206:209], v[66:69]
	v_mfma_f32_16x16x32_bf16 v[62:65], v[172:175], v[206:209], v[62:65]
	v_mfma_f32_16x16x32_bf16 v[50:53], v[164:167], v[214:217], v[50:53]
	v_mfma_f32_16x16x32_bf16 v[46:49], v[172:175], v[214:217], v[46:49]
	v_mfma_f32_16x16x32_bf16 v[34:37], v[164:167], v[232:235], v[34:37]
	v_mfma_f32_16x16x32_bf16 v[30:33], v[172:175], v[232:235], v[30:33]
	v_mfma_f32_16x16x32_bf16 v[18:21], v[164:167], v[240:243], v[18:21]
	v_mfma_f32_16x16x32_bf16 v[14:17], v[172:175], v[240:243], v[14:17]
	v_mfma_f32_16x16x32_bf16 v[66:69], v[168:171], v[210:213], v[66:69]
	v_mfma_f32_16x16x32_bf16 v[62:65], v[176:179], v[210:213], v[62:65]
	v_mfma_f32_16x16x32_bf16 v[50:53], v[168:171], v[228:231], v[50:53]
	v_mfma_f32_16x16x32_bf16 v[46:49], v[176:179], v[228:231], v[46:49]
	v_mfma_f32_16x16x32_bf16 v[34:37], v[168:171], v[236:239], v[34:37]
	v_mfma_f32_16x16x32_bf16 v[30:33], v[176:179], v[236:239], v[30:33]
	v_mfma_f32_16x16x32_bf16 v[18:21], v[168:171], v[244:247], v[18:21]
	v_mfma_f32_16x16x32_bf16 v[14:17], v[176:179], v[244:247], v[14:17]
	v_mfma_f32_16x16x32_bf16 v[58:61], v[180:183], v[206:209], v[58:61]
	v_mfma_f32_16x16x32_bf16 v[54:57], v[198:201], v[206:209], v[54:57]
	v_mfma_f32_16x16x32_bf16 v[42:45], v[180:183], v[214:217], v[42:45]
	v_mfma_f32_16x16x32_bf16 v[38:41], v[198:201], v[214:217], v[38:41]
	v_mfma_f32_16x16x32_bf16 v[26:29], v[180:183], v[232:235], v[26:29]
	v_mfma_f32_16x16x32_bf16 v[22:25], v[198:201], v[232:235], v[22:25]
	v_mfma_f32_16x16x32_bf16 v[10:13], v[180:183], v[240:243], v[10:13]
	v_mfma_f32_16x16x32_bf16 v[6:9], v[198:201], v[240:243], v[6:9]
	v_mfma_f32_16x16x32_bf16 v[58:61], v[194:197], v[210:213], v[58:61]
	v_mfma_f32_16x16x32_bf16 v[54:57], v[202:205], v[210:213], v[54:57]
	v_mfma_f32_16x16x32_bf16 v[42:45], v[194:197], v[228:231], v[42:45]
	v_mfma_f32_16x16x32_bf16 v[38:41], v[202:205], v[228:231], v[38:41]
	v_mfma_f32_16x16x32_bf16 v[26:29], v[194:197], v[236:239], v[26:29]
	v_mfma_f32_16x16x32_bf16 v[22:25], v[202:205], v[236:239], v[22:25]
	v_mfma_f32_16x16x32_bf16 v[10:13], v[194:197], v[244:247], v[10:13]
	v_mfma_f32_16x16x32_bf16 v[6:9], v[202:205], v[244:247], v[6:9]
	s_barrier
	s_add_i32 s64, 0, 0x18000
	s_add_i32 s65, 0, 0x1c000
	ds_read_b128 v[164:167], v152
	ds_read_b128 v[168:171], v152 offset:1024
	ds_read_b128 v[172:175], v152 offset:2048
	ds_read_b128 v[176:179], v152 offset:3072
	ds_read_b128 v[180:183], v154
	ds_read_b128 v[194:197], v154 offset:1024
	ds_read_b128 v[198:201], v154 offset:2048
	ds_read_b128 v[202:205], v154 offset:3072
	s_add_u32 s30, s30, 0x80000
	s_addc_u32 s31, s31, 0
	s_mov_b32 m0, s49
	ds_read_b128 v[206:209], v163 offset:32768
	ds_read_b128 v[210:213], v163 offset:33792
	ds_read_b128 v[214:217], v163 offset:34816
	ds_read_b128 v[228:231], v163 offset:35840
	ds_read_b128 v[232:235], v163 offset:36864
	ds_read_b128 v[236:239], v163 offset:37888
	ds_read_b128 v[240:243], v163 offset:38912
	ds_read_b128 v[244:247], v163 offset:39936
	global_load_lds_dwordx4 v140, s[30:31]
	s_mov_b32 m0, s50
	s_nop 0
	global_load_lds_dwordx4 v136, s[30:31]
	s_waitcnt vmcnt(8)
	s_waitcnt lgkmcnt(0)
	s_barrier
	v_mfma_f32_16x16x32_bf16 v[130:133], v[164:167], v[206:209], v[130:133]
	v_mfma_f32_16x16x32_bf16 v[126:129], v[172:175], v[206:209], v[126:129]
	v_mfma_f32_16x16x32_bf16 v[114:117], v[164:167], v[214:217], v[114:117]
	v_mfma_f32_16x16x32_bf16 v[110:113], v[172:175], v[214:217], v[110:113]
	v_mfma_f32_16x16x32_bf16 v[98:101], v[164:167], v[232:235], v[98:101]
	v_mfma_f32_16x16x32_bf16 v[94:97], v[172:175], v[232:235], v[94:97]
	v_mfma_f32_16x16x32_bf16 v[82:85], v[164:167], v[240:243], v[82:85]
	v_mfma_f32_16x16x32_bf16 v[78:81], v[172:175], v[240:243], v[78:81]
	v_mfma_f32_16x16x32_bf16 v[130:133], v[168:171], v[210:213], v[130:133]
	v_mfma_f32_16x16x32_bf16 v[126:129], v[176:179], v[210:213], v[126:129]
	v_mfma_f32_16x16x32_bf16 v[114:117], v[168:171], v[228:231], v[114:117]
	v_mfma_f32_16x16x32_bf16 v[110:113], v[176:179], v[228:231], v[110:113]
	v_mfma_f32_16x16x32_bf16 v[98:101], v[168:171], v[236:239], v[98:101]
	v_mfma_f32_16x16x32_bf16 v[94:97], v[176:179], v[236:239], v[94:97]
	v_mfma_f32_16x16x32_bf16 v[82:85], v[168:171], v[244:247], v[82:85]
	v_mfma_f32_16x16x32_bf16 v[78:81], v[176:179], v[244:247], v[78:81]
	v_mfma_f32_16x16x32_bf16 v[122:125], v[180:183], v[206:209], v[122:125]
	v_mfma_f32_16x16x32_bf16 v[118:121], v[198:201], v[206:209], v[118:121]
	v_mfma_f32_16x16x32_bf16 v[106:109], v[180:183], v[214:217], v[106:109]
	v_mfma_f32_16x16x32_bf16 v[102:105], v[198:201], v[214:217], v[102:105]
	v_mfma_f32_16x16x32_bf16 v[90:93], v[180:183], v[232:235], v[90:93]
	v_mfma_f32_16x16x32_bf16 v[86:89], v[198:201], v[232:235], v[86:89]
	v_mfma_f32_16x16x32_bf16 v[74:77], v[180:183], v[240:243], v[74:77]
	v_mfma_f32_16x16x32_bf16 v[70:73], v[198:201], v[240:243], v[70:73]
	v_mfma_f32_16x16x32_bf16 v[122:125], v[194:197], v[210:213], v[122:125]
	v_mfma_f32_16x16x32_bf16 v[118:121], v[202:205], v[210:213], v[118:121]
	v_mfma_f32_16x16x32_bf16 v[106:109], v[194:197], v[228:231], v[106:109]
	v_mfma_f32_16x16x32_bf16 v[102:105], v[202:205], v[228:231], v[102:105]
	v_mfma_f32_16x16x32_bf16 v[90:93], v[194:197], v[236:239], v[90:93]
	v_mfma_f32_16x16x32_bf16 v[86:89], v[202:205], v[236:239], v[86:89]
	v_mfma_f32_16x16x32_bf16 v[74:77], v[194:197], v[244:247], v[74:77]
	v_mfma_f32_16x16x32_bf16 v[70:73], v[202:205], v[244:247], v[70:73]
	s_barrier
; #define PG8_STAGE(bufoff, gbase, voff) do { _Pragma("unroll") for (int _i = 0; _i < 2; ++_i) \
;         __builtin_amdgcn_global_load_lds((const unsigned*)((const char*)(gbase) + (voff)[_i]), (PG8_LAS unsigned*)(lds + (bufoff) + ldsw + _i * 8192), 16, 0, 0); } while (0)
; #define PG8_LDA(dst, b, h) do { _Pragma("unroll") for (int m = 0; m < 4; ++m) _Pragma("unroll") for (int k = 0; k < 2; ++k) dst[m][k] = *(const PG8_LAS bf16x8*)(lds + PG8_SA(b, h) + aoff + m * 2048 + k * 1024); } while (0)
; #define PG8_MMA(ai, bj, At, Bt) do { __builtin_amdgcn_s_setprio(1); _Pragma("unroll") for (int m = 0; m < 4; ++m) _Pragma("unroll") for (int n = 0; n < 2; ++n) _Pragma("unroll") for (int k = 0; k < 2; ++k) \
;         acc[ai][bj][m][n] = __builtin_amdgcn_mfma_f32_16x16x32_bf16(Bt[n][k], At[m][k], acc[ai][bj][m][n], 0, 0, 0); __builtin_amdgcn_s_setprio(0); } while (0)
; #define PG8_WAIT_V(n) asm volatile("s_waitcnt vmcnt(" #n ")" ::: "memory")
; #define PG8_WAIT_L(n) asm volatile("s_waitcnt lgkmcnt(" #n ")" ::: "memory")
; #define PG8_BAR __builtin_amdgcn_s_barrier()
; #define PG8_SCHED __builtin_amdgcn_sched_barrier(0)
; template <class Epi, class Sched, bool ALIGN_EPI = false, bool SP2 = false>
; __device__ __forceinline__ void gemm_phase(PG8_LAS unsigned char* lds, const Gemm g, const Sched& S, const Epi& E, const int wv) {
;     ...
;         for (int t = 0; t < nt; t += 2) {
;     ...
;             PG8_LDA(At, 1, 1); PG8_STAGE(PG8_SB(1, 0), b3, voffB); PG8_STAGE(PG8_SB(1, 1), b3 + hstepB, voffB); PG8_STAGE(PG8_SA(1, 0), a3, voffA);
;             PG8_WAIT_V(8); PG8_WAIT_L(0); PG8_BAR; PG8_MMA(1, 0, At, B0); PG8_MMA(1, 1, At, B1); PG8_BAR; PG8_SCHED;
	s_add_i32 s30, s64, s45
	s_add_i32 m0, s30, 0xffffff80
	ds_read_b128 v[206:209], v163 offset:49152
	ds_read_b128 v[210:213], v163 offset:50176
	ds_read_b128 v[214:217], v163 offset:51200
	ds_read_b128 v[228:231], v163 offset:52224
	ds_read_b128 v[232:235], v163 offset:53248
	ds_read_b128 v[236:239], v163 offset:54272
	ds_read_b128 v[240:243], v163 offset:55296
	ds_read_b128 v[244:247], v163 offset:56320
	global_load_lds_dwordx4 v[150:151], off offset:128
	s_add_i32 m0, s30, 0x1f80
	s_add_i32 s30, s65, s45
	global_load_lds_dwordx4 v[184:185], off offset:128
	s_add_i32 m0, s30, 0xffffff80
	s_nop 0
	global_load_lds_dwordx4 v[190:191], off offset:128
	s_add_i32 m0, s30, 0x1f80
	s_nop 0
	global_load_lds_dwordx4 v[192:193], off offset:128
	s_add_i32 m0, s53, 0xffffff80
	s_nop 0
	global_load_lds_dwordx4 v[218:219], off offset:128
	s_add_i32 m0, s54, 0xffffff80
	s_nop 0
	global_load_lds_dwordx4 v[248:249], off offset:128
	s_waitcnt vmcnt(8)
	s_waitcnt lgkmcnt(0)
	s_barrier
	v_mfma_f32_16x16x32_bf16 v[66:69], v[164:167], v[206:209], v[66:69]
	v_mfma_f32_16x16x32_bf16 v[62:65], v[172:175], v[206:209], v[62:65]
	v_mfma_f32_16x16x32_bf16 v[50:53], v[164:167], v[214:217], v[50:53]
	v_mfma_f32_16x16x32_bf16 v[46:49], v[172:175], v[214:217], v[46:49]
	v_mfma_f32_16x16x32_bf16 v[34:37], v[164:167], v[232:235], v[34:37]
	v_mfma_f32_16x16x32_bf16 v[30:33], v[172:175], v[232:235], v[30:33]
	v_mfma_f32_16x16x32_bf16 v[18:21], v[164:167], v[240:243], v[18:21]
	v_mfma_f32_16x16x32_bf16 v[14:17], v[172:175], v[240:243], v[14:17]
	v_mfma_f32_16x16x32_bf16 v[66:69], v[168:171], v[210:213], v[66:69]
	v_mfma_f32_16x16x32_bf16 v[62:65], v[176:179], v[210:213], v[62:65]
	v_mfma_f32_16x16x32_bf16 v[50:53], v[168:171], v[228:231], v[50:53]
	v_mfma_f32_16x16x32_bf16 v[46:49], v[176:179], v[228:231], v[46:49]
	v_mfma_f32_16x16x32_bf16 v[34:37], v[168:171], v[236:239], v[34:37]
	v_mfma_f32_16x16x32_bf16 v[30:33], v[176:179], v[236:239], v[30:33]
	v_mfma_f32_16x16x32_bf16 v[18:21], v[168:171], v[244:247], v[18:21]
	v_mfma_f32_16x16x32_bf16 v[14:17], v[176:179], v[244:247], v[14:17]
	v_mfma_f32_16x16x32_bf16 v[58:61], v[180:183], v[206:209], v[58:61]
	v_mfma_f32_16x16x32_bf16 v[54:57], v[198:201], v[206:209], v[54:57]
	v_mfma_f32_16x16x32_bf16 v[42:45], v[180:183], v[214:217], v[42:45]
	v_mfma_f32_16x16x32_bf16 v[38:41], v[198:201], v[214:217], v[38:41]
	v_mfma_f32_16x16x32_bf16 v[26:29], v[180:183], v[232:235], v[26:29]
	v_mfma_f32_16x16x32_bf16 v[22:25], v[198:201], v[232:235], v[22:25]
	v_mfma_f32_16x16x32_bf16 v[10:13], v[180:183], v[240:243], v[10:13]
	v_mfma_f32_16x16x32_bf16 v[6:9], v[198:201], v[240:243], v[6:9]
	v_mfma_f32_16x16x32_bf16 v[58:61], v[194:197], v[210:213], v[58:61]
	v_mfma_f32_16x16x32_bf16 v[54:57], v[202:205], v[210:213], v[54:57]
	v_mfma_f32_16x16x32_bf16 v[42:45], v[194:197], v[228:231], v[42:45]
	v_mfma_f32_16x16x32_bf16 v[38:41], v[202:205], v[228:231], v[38:41]
	v_mfma_f32_16x16x32_bf16 v[26:29], v[194:197], v[236:239], v[26:29]
	v_mfma_f32_16x16x32_bf16 v[22:25], v[202:205], v[236:239], v[22:25]
	v_mfma_f32_16x16x32_bf16 v[10:13], v[194:197], v[244:247], v[10:13]
	v_mfma_f32_16x16x32_bf16 v[6:9], v[202:205], v[244:247], v[6:9]
	s_barrier
	s_add_u32 s28, s28, 0x100
	s_addc_u32 s29, s29, 0
	s_add_u32 s41, s41, 0x100
	s_addc_u32 s62, s62, 0
	s_cmp_ge_i32 s63, s55
	s_mov_b32 s30, s63
	s_cbranch_scc0 .LBB0_1074
	v_readlane_b32 s67, v255, 30

; #define PG8_STAGE(bufoff, gbase, voff) do { _Pragma("unroll") for (int _i = 0; _i < 2; ++_i) \
;         __builtin_amdgcn_global_load_lds((const unsigned*)((const char*)(gbase) + (voff)[_i]), (PG8_LAS unsigned*)(lds + (bufoff) + ldsw + _i * 8192), 16, 0, 0); } while (0)
; #define PG8_LDA(dst, b, h) do { _Pragma("unroll") for (int m = 0; m < 4; ++m) _Pragma("unroll") for (int k = 0; k < 2; ++k) dst[m][k] = *(const PG8_LAS bf16x8*)(lds + PG8_SA(b, h) + aoff + m * 2048 + k * 1024); } while (0)
; #define PG8_LDB(dst, b, h) do { _Pragma("unroll") for (int n = 0; n < 2; ++n) _Pragma("unroll") for (int k = 0; k < 2; ++k) dst[n][k] = *(const PG8_LAS bf16x8*)(lds + PG8_SB(b, h) + boff + n * 2048 + k * 1024); } while (0)
; #define PG8_MMA(ai, bj, At, Bt) do { __builtin_amdgcn_s_setprio(1); _Pragma("unroll") for (int m = 0; m < 4; ++m) _Pragma("unroll") for (int n = 0; n < 2; ++n) _Pragma("unroll") for (int k = 0; k < 2; ++k) \
;         acc[ai][bj][m][n] = __builtin_amdgcn_mfma_f32_16x16x32_bf16(Bt[n][k], At[m][k], acc[ai][bj][m][n], 0, 0, 0); __builtin_amdgcn_s_setprio(0); } while (0)
; #define PG8_WAIT_V(n) asm volatile("s_waitcnt vmcnt(" #n ")" ::: "memory")
; #define PG8_WAIT_L(n) asm volatile("s_waitcnt lgkmcnt(" #n ")" ::: "memory")
; template <class Epi, class Sched, bool ALIGN_EPI = false, bool SP2 = false>
; __device__ __forceinline__ void gemm_phase(PG8_LAS unsigned char* lds, const Gemm g, const Sched& S, const Epi& E, const int wv) {
;     ...
; #pragma unroll
;     for (int a = 0; a < 2; ++a)
; #pragma unroll
;         for (int b = 0; b < 2; ++b)
; #pragma unroll
;             for (int m = 0; m < 4; ++m)
; #pragma unroll
;                 for (int n = 0; n < 2; ++n) acc[a][b][m][n] = (f32x4){0.f, 0.f, 0.f, 0.f};
;     ...
;             const bool last = (t == nt - 2);
;             const char* a1 = cA + (size_t)(t + 1) * kstep;
;             const char* a2 = last ? nA : cA + (size_t)(t + 2) * kstep; const char* b2 = last ? nB : cB + (size_t)(t + 2) * kstep;
;             const char* a3 = a2 + kstep; const char* b3 = b2 + kstep;
;             if (last && has_next) S.a_ready(nxt);
;             if constexpr (SP2) {
;             PG8_LDB(B0, 0, 0); PG8_LDB(B1, 0, 1); PG8_SCHED; PG8_LDA(At, 0, 0); PG8_STAGE(PG8_SA(1, 1), a1 + hstepA, voffA);
;             PG8_WAIT_V(8); PG8_WAIT_L(0); PG8_BAR; PG8_MMA(0, 0, At, B0); PG8_MMA(0, 1, At, B1); PG8_BAR; PG8_SCHED;
.LBB0_1384:
	s_and_b64 s[44:45], s[44:45], exec
	s_cselect_b32 s13, s49, s53
	s_cselect_b32 s19, s48, s52
	s_add_u32 s44, s52, 0x40080
	s_addc_u32 s45, s53, 0
	s_add_u32 s54, s54, 0x100
	v_mov_b32_e32 v2, 0
	s_addc_u32 s55, s55, 0
	s_mov_b32 s52, 0
	v_mov_b32_e32 v3, v2
	v_pk_mov_b32 v[4:5], v[2:3], v[2:3]
	v_pk_mov_b32 v[6:7], v[2:3], v[2:3]
	v_pk_mov_b32 v[8:9], v[2:3], v[2:3]
	v_pk_mov_b32 v[18:19], v[2:3], v[2:3]
	v_pk_mov_b32 v[20:21], v[2:3], v[2:3]
	v_pk_mov_b32 v[22:23], v[2:3], v[2:3]
	v_pk_mov_b32 v[24:25], v[2:3], v[2:3]
	v_pk_mov_b32 v[34:35], v[2:3], v[2:3]
	v_pk_mov_b32 v[36:37], v[2:3], v[2:3]
	v_pk_mov_b32 v[38:39], v[2:3], v[2:3]
	v_pk_mov_b32 v[40:41], v[2:3], v[2:3]
	v_pk_mov_b32 v[50:51], v[2:3], v[2:3]
	v_pk_mov_b32 v[52:53], v[2:3], v[2:3]
	v_pk_mov_b32 v[54:55], v[2:3], v[2:3]
	v_pk_mov_b32 v[56:57], v[2:3], v[2:3]
	v_pk_mov_b32 v[10:11], v[2:3], v[2:3]
	v_pk_mov_b32 v[12:13], v[2:3], v[2:3]
	v_pk_mov_b32 v[14:15], v[2:3], v[2:3]
	v_pk_mov_b32 v[16:17], v[2:3], v[2:3]
	v_pk_mov_b32 v[26:27], v[2:3], v[2:3]
	v_pk_mov_b32 v[28:29], v[2:3], v[2:3]
	v_pk_mov_b32 v[30:31], v[2:3], v[2:3]
	v_pk_mov_b32 v[32:33], v[2:3], v[2:3]
	v_pk_mov_b32 v[42:43], v[2:3], v[2:3]
	v_pk_mov_b32 v[44:45], v[2:3], v[2:3]
	v_pk_mov_b32 v[46:47], v[2:3], v[2:3]
	v_pk_mov_b32 v[48:49], v[2:3], v[2:3]
	v_pk_mov_b32 v[58:59], v[2:3], v[2:3]
	v_pk_mov_b32 v[60:61], v[2:3], v[2:3]
	v_pk_mov_b32 v[62:63], v[2:3], v[2:3]
	v_pk_mov_b32 v[64:65], v[2:3], v[2:3]
	v_pk_mov_b32 v[66:67], v[2:3], v[2:3]
	v_pk_mov_b32 v[68:69], v[2:3], v[2:3]
	v_pk_mov_b32 v[70:71], v[2:3], v[2:3]
	v_pk_mov_b32 v[72:73], v[2:3], v[2:3]
	v_pk_mov_b32 v[82:83], v[2:3], v[2:3]
	v_pk_mov_b32 v[84:85], v[2:3], v[2:3]
	v_pk_mov_b32 v[86:87], v[2:3], v[2:3]
	v_pk_mov_b32 v[88:89], v[2:3], v[2:3]
	v_pk_mov_b32 v[98:99], v[2:3], v[2:3]
	v_pk_mov_b32 v[100:101], v[2:3], v[2:3]
	v_pk_mov_b32 v[102:103], v[2:3], v[2:3]
	v_pk_mov_b32 v[104:105], v[2:3], v[2:3]
	v_pk_mov_b32 v[118:119], v[2:3], v[2:3]
	v_pk_mov_b32 v[120:121], v[2:3], v[2:3]
	v_pk_mov_b32 v[122:123], v[2:3], v[2:3]
	v_pk_mov_b32 v[124:125], v[2:3], v[2:3]
	v_pk_mov_b32 v[74:75], v[2:3], v[2:3]
	v_pk_mov_b32 v[76:77], v[2:3], v[2:3]
	v_pk_mov_b32 v[78:79], v[2:3], v[2:3]
	v_pk_mov_b32 v[80:81], v[2:3], v[2:3]
	v_pk_mov_b32 v[90:91], v[2:3], v[2:3]
	v_pk_mov_b32 v[92:93], v[2:3], v[2:3]
	v_pk_mov_b32 v[94:95], v[2:3], v[2:3]
	v_pk_mov_b32 v[96:97], v[2:3], v[2:3]
	v_pk_mov_b32 v[106:107], v[2:3], v[2:3]
	v_pk_mov_b32 v[108:109], v[2:3], v[2:3]
	v_pk_mov_b32 v[110:111], v[2:3], v[2:3]
	v_pk_mov_b32 v[112:113], v[2:3], v[2:3]
	v_pk_mov_b32 v[130:131], v[2:3], v[2:3]
	v_pk_mov_b32 v[132:133], v[2:3], v[2:3]
	v_pk_mov_b32 v[134:135], v[2:3], v[2:3]
	v_pk_mov_b32 v[136:137], v[2:3], v[2:3]
	v_add_u32_e32 v201, 0x10000, v230
	v_add_u32_e32 v203, 0x14000, v230
	v_add_u32_e32 v236, 0x18000, v230
	v_add_u32_e32 v237, 0x1c000, v230
.LBB0_1385:
	s_add_i32 s70, s52, 2
	s_add_u32 s71, s44, 0xfffc0080
	s_addc_u32 s53, s45, -1
	s_add_i32 s74, 0, 0x10000
	s_cmp_eq_u32 s65, s52
	s_cselect_b32 s53, s13, s53
	s_cselect_b32 s52, s19, s71
	s_cselect_b32 s73, s15, s55
	s_cselect_b32 s72, s14, s54
	s_add_i32 s71, 0, 0x14000
	ds_read_b128 v[114:117], v201
	ds_read_b128 v[126:129], v201 offset:1024
	ds_read_b128 v[138:141], v201 offset:2048
	ds_read_b128 v[142:145], v201 offset:3072
	ds_read_b128 v[146:149], v203
	ds_read_b128 v[150:153], v203 offset:1024
	ds_read_b128 v[154:157], v203 offset:2048
	ds_read_b128 v[158:161], v203 offset:3072
	s_add_i32 m0, s51, 0xc000
	ds_read_b128 v[162:165], v235
	ds_read_b128 v[166:169], v235 offset:1024
	ds_read_b128 v[170:173], v235 offset:2048
	ds_read_b128 v[174:177], v235 offset:3072
	ds_read_b128 v[178:181], v235 offset:4096
	ds_read_b128 v[182:185], v235 offset:5120
	ds_read_b128 v[204:207], v235 offset:6144
	ds_read_b128 v[208:211], v235 offset:7168
	global_load_lds_dwordx4 v200, s[44:45]
	s_add_i32 m0, s51, 0xe000
	s_nop 0
	global_load_lds_dwordx4 v202, s[44:45]
	s_waitcnt vmcnt(8)
	s_waitcnt lgkmcnt(0)
	s_barrier
	v_mfma_f32_16x16x32_bf16 v[134:137], v[114:117], v[162:165], v[134:137]
	v_mfma_f32_16x16x32_bf16 v[130:133], v[138:141], v[162:165], v[130:133]
	v_mfma_f32_16x16x32_bf16 v[110:113], v[114:117], v[170:173], v[110:113]
	v_mfma_f32_16x16x32_bf16 v[106:109], v[138:141], v[170:173], v[106:109]
	v_mfma_f32_16x16x32_bf16 v[94:97], v[114:117], v[178:181], v[94:97]
	v_mfma_f32_16x16x32_bf16 v[90:93], v[138:141], v[178:181], v[90:93]
	v_mfma_f32_16x16x32_bf16 v[78:81], v[114:117], v[204:207], v[78:81]
	v_mfma_f32_16x16x32_bf16 v[74:77], v[138:141], v[204:207], v[74:77]
	v_mfma_f32_16x16x32_bf16 v[134:137], v[126:129], v[166:169], v[134:137]
	v_mfma_f32_16x16x32_bf16 v[130:133], v[142:145], v[166:169], v[130:133]
	v_mfma_f32_16x16x32_bf16 v[110:113], v[126:129], v[174:177], v[110:113]
	v_mfma_f32_16x16x32_bf16 v[106:109], v[142:145], v[174:177], v[106:109]
	v_mfma_f32_16x16x32_bf16 v[94:97], v[126:129], v[182:185], v[94:97]
	v_mfma_f32_16x16x32_bf16 v[90:93], v[142:145], v[182:185], v[90:93]
	v_mfma_f32_16x16x32_bf16 v[78:81], v[126:129], v[208:211], v[78:81]
	v_mfma_f32_16x16x32_bf16 v[74:77], v[142:145], v[208:211], v[74:77]
	v_mfma_f32_16x16x32_bf16 v[122:125], v[146:149], v[162:165], v[122:125]
	v_mfma_f32_16x16x32_bf16 v[118:121], v[154:157], v[162:165], v[118:121]
	v_mfma_f32_16x16x32_bf16 v[102:105], v[146:149], v[170:173], v[102:105]
	v_mfma_f32_16x16x32_bf16 v[98:101], v[154:157], v[170:173], v[98:101]
	v_mfma_f32_16x16x32_bf16 v[86:89], v[146:149], v[178:181], v[86:89]
	v_mfma_f32_16x16x32_bf16 v[82:85], v[154:157], v[178:181], v[82:85]
	v_mfma_f32_16x16x32_bf16 v[70:73], v[146:149], v[204:207], v[70:73]
	v_mfma_f32_16x16x32_bf16 v[66:69], v[154:157], v[204:207], v[66:69]
	v_mfma_f32_16x16x32_bf16 v[122:125], v[150:153], v[166:169], v[122:125]
	v_mfma_f32_16x16x32_bf16 v[118:121], v[158:161], v[166:169], v[118:121]
	v_mfma_f32_16x16x32_bf16 v[102:105], v[150:153], v[174:177], v[102:105]
	v_mfma_f32_16x16x32_bf16 v[98:101], v[158:161], v[174:177], v[98:101]
	v_mfma_f32_16x16x32_bf16 v[86:89], v[150:153], v[182:185], v[86:89]
	v_mfma_f32_16x16x32_bf16 v[82:85], v[158:161], v[182:185], v[82:85]
	v_mfma_f32_16x16x32_bf16 v[70:73], v[150:153], v[208:211], v[70:73]
	v_mfma_f32_16x16x32_bf16 v[66:69], v[158:161], v[208:211], v[66:69]
	s_barrier
; #define PG8_STAGE(bufoff, gbase, voff) do { _Pragma("unroll") for (int _i = 0; _i < 2; ++_i) \
;         __builtin_amdgcn_global_load_lds((const unsigned*)((const char*)(gbase) + (voff)[_i]), (PG8_LAS unsigned*)(lds + (bufoff) + ldsw + _i * 8192), 16, 0, 0); } while (0)
; #define PG8_LDA(dst, b, h) do { _Pragma("unroll") for (int m = 0; m < 4; ++m) _Pragma("unroll") for (int k = 0; k < 2; ++k) dst[m][k] = *(const PG8_LAS bf16x8*)(lds + PG8_SA(b, h) + aoff + m * 2048 + k * 1024); } while (0)
; #define PG8_LDB(dst, b, h) do { _Pragma("unroll") for (int n = 0; n < 2; ++n) _Pragma("unroll") for (int k = 0; k < 2; ++k) dst[n][k] = *(const PG8_LAS bf16x8*)(lds + PG8_SB(b, h) + boff + n * 2048 + k * 1024); } while (0)
; #define PG8_MMA(ai, bj, At, Bt) do { __builtin_amdgcn_s_setprio(1); _Pragma("unroll") for (int m = 0; m < 4; ++m) _Pragma("unroll") for (int n = 0; n < 2; ++n) _Pragma("unroll") for (int k = 0; k < 2; ++k) \
;         acc[ai][bj][m][n] = __builtin_amdgcn_mfma_f32_16x16x32_bf16(Bt[n][k], At[m][k], acc[ai][bj][m][n], 0, 0, 0); __builtin_amdgcn_s_setprio(0); } while (0)
; #define PG8_WAIT_V(n) asm volatile("s_waitcnt vmcnt(" #n ")" ::: "memory")
; #define PG8_WAIT_L(n) asm volatile("s_waitcnt lgkmcnt(" #n ")" ::: "memory")
; #define PG8_BAR __builtin_amdgcn_s_barrier()
; #define PG8_SCHED __builtin_amdgcn_sched_barrier(0)
; template <class Epi, class Sched, bool ALIGN_EPI = false, bool SP2 = false>
; __device__ __forceinline__ void gemm_phase(PG8_LAS unsigned char* lds, const Gemm g, const Sched& S, const Epi& E, const int wv) {
;     ...
;             PG8_LDA(At, 0, 1); PG8_STAGE(PG8_SB(0, 0), b2, voffB); PG8_STAGE(PG8_SB(0, 1), b2 + hstepB, voffB); PG8_STAGE(PG8_SA(0, 0), a2, voffA);
;             PG8_WAIT_V(8); PG8_WAIT_L(0); PG8_BAR; PG8_MMA(1, 0, At, B0); PG8_MMA(1, 1, At, B1); PG8_BAR; PG8_SCHED;
;             PG8_LDB(B0, 1, 0); PG8_LDB(B1, 1, 1); PG8_SCHED; PG8_LDA(At, 1, 0); PG8_STAGE(PG8_SA(0, 1), a2 + hstepA, voffA);
;             PG8_WAIT_V(8); PG8_WAIT_L(0); PG8_BAR; PG8_MMA(0, 0, At, B0); PG8_MMA(0, 1, At, B1); PG8_BAR; PG8_SCHED;
	s_add_i32 s74, s74, s3
	v_lshl_add_u64 v[190:191], s[72:73], 0, v[0:1]
	s_mov_b32 m0, s74
	ds_read_b128 v[162:165], v235 offset:16384
	ds_read_b128 v[166:169], v235 offset:17408
	ds_read_b128 v[170:173], v235 offset:18432
	ds_read_b128 v[174:177], v235 offset:19456
	ds_read_b128 v[178:181], v235 offset:20480
	ds_read_b128 v[182:185], v235 offset:21504
	ds_read_b128 v[204:207], v235 offset:22528
	ds_read_b128 v[208:211], v235 offset:23552
	global_load_lds_dwordx4 v[190:191], off
	s_add_i32 m0, s74, 0x2000
	v_lshl_add_u64 v[192:193], s[72:73], 0, v[198:199]
	s_add_u32 s72, s72, s24
	s_addc_u32 s73, s73, s25
	s_add_i32 s71, s71, s3
	global_load_lds_dwordx4 v[192:193], off
	v_lshl_add_u64 v[212:213], s[72:73], 0, v[0:1]
	s_mov_b32 m0, s71
	v_lshl_add_u64 v[214:215], s[72:73], 0, v[198:199]
	global_load_lds_dwordx4 v[212:213], off
	s_add_i32 m0, s71, 0x2000
	v_lshl_add_u64 v[216:217], s[52:53], 0, v[194:195]
	global_load_lds_dwordx4 v[214:215], off
	s_mov_b32 m0, s51
	v_lshl_add_u64 v[218:219], s[52:53], 0, v[196:197]
	global_load_lds_dwordx4 v[216:217], off
	s_mov_b32 m0, s59
	s_nop 0
	global_load_lds_dwordx4 v[218:219], off
	s_waitcnt vmcnt(8)
	s_waitcnt lgkmcnt(0)
	s_barrier
	v_mfma_f32_16x16x32_bf16 v[62:65], v[114:117], v[162:165], v[62:65]
	v_mfma_f32_16x16x32_bf16 v[58:61], v[138:141], v[162:165], v[58:61]
	v_mfma_f32_16x16x32_bf16 v[46:49], v[114:117], v[170:173], v[46:49]
	v_mfma_f32_16x16x32_bf16 v[42:45], v[138:141], v[170:173], v[42:45]
	v_mfma_f32_16x16x32_bf16 v[30:33], v[114:117], v[178:181], v[30:33]
	v_mfma_f32_16x16x32_bf16 v[26:29], v[138:141], v[178:181], v[26:29]
	v_mfma_f32_16x16x32_bf16 v[14:17], v[114:117], v[204:207], v[14:17]
	v_mfma_f32_16x16x32_bf16 v[10:13], v[138:141], v[204:207], v[10:13]
	v_mfma_f32_16x16x32_bf16 v[62:65], v[126:129], v[166:169], v[62:65]
	v_mfma_f32_16x16x32_bf16 v[58:61], v[142:145], v[166:169], v[58:61]
	v_mfma_f32_16x16x32_bf16 v[46:49], v[126:129], v[174:177], v[46:49]
	v_mfma_f32_16x16x32_bf16 v[42:45], v[142:145], v[174:177], v[42:45]
	v_mfma_f32_16x16x32_bf16 v[30:33], v[126:129], v[182:185], v[30:33]
	v_mfma_f32_16x16x32_bf16 v[26:29], v[142:145], v[182:185], v[26:29]
	v_mfma_f32_16x16x32_bf16 v[14:17], v[126:129], v[208:211], v[14:17]
	v_mfma_f32_16x16x32_bf16 v[10:13], v[142:145], v[208:211], v[10:13]
	v_mfma_f32_16x16x32_bf16 v[54:57], v[146:149], v[162:165], v[54:57]
	v_mfma_f32_16x16x32_bf16 v[50:53], v[154:157], v[162:165], v[50:53]
	v_mfma_f32_16x16x32_bf16 v[38:41], v[146:149], v[170:173], v[38:41]
	v_mfma_f32_16x16x32_bf16 v[34:37], v[154:157], v[170:173], v[34:37]
	v_mfma_f32_16x16x32_bf16 v[22:25], v[146:149], v[178:181], v[22:25]
	v_mfma_f32_16x16x32_bf16 v[18:21], v[154:157], v[178:181], v[18:21]
	v_mfma_f32_16x16x32_bf16 v[6:9], v[146:149], v[204:207], v[6:9]
	v_mfma_f32_16x16x32_bf16 v[2:5], v[154:157], v[204:207], v[2:5]
	v_mfma_f32_16x16x32_bf16 v[54:57], v[150:153], v[166:169], v[54:57]
	v_mfma_f32_16x16x32_bf16 v[50:53], v[158:161], v[166:169], v[50:53]
	v_mfma_f32_16x16x32_bf16 v[38:41], v[150:153], v[174:177], v[38:41]
	v_mfma_f32_16x16x32_bf16 v[34:37], v[158:161], v[174:177], v[34:37]
	v_mfma_f32_16x16x32_bf16 v[22:25], v[150:153], v[182:185], v[22:25]
	v_mfma_f32_16x16x32_bf16 v[18:21], v[158:161], v[182:185], v[18:21]
	v_mfma_f32_16x16x32_bf16 v[6:9], v[150:153], v[208:211], v[6:9]
	v_mfma_f32_16x16x32_bf16 v[2:5], v[158:161], v[208:211], v[2:5]
	s_barrier
	s_add_i32 s71, 0, 0x18000
	s_add_i32 s72, 0, 0x1c000
	ds_read_b128 v[114:117], v236
	ds_read_b128 v[126:129], v236 offset:1024
	ds_read_b128 v[138:141], v236 offset:2048
	ds_read_b128 v[142:145], v236 offset:3072
	ds_read_b128 v[146:149], v237
	ds_read_b128 v[150:153], v237 offset:1024
	ds_read_b128 v[154:157], v237 offset:2048
	ds_read_b128 v[158:161], v237 offset:3072
	s_add_u32 s52, s52, 0x40000
	s_addc_u32 s53, s53, 0
	s_mov_b32 m0, s60
	ds_read_b128 v[162:165], v235 offset:32768
	ds_read_b128 v[166:169], v235 offset:33792
	ds_read_b128 v[170:173], v235 offset:34816
	ds_read_b128 v[174:177], v235 offset:35840
	ds_read_b128 v[178:181], v235 offset:36864
	ds_read_b128 v[182:185], v235 offset:37888
	ds_read_b128 v[204:207], v235 offset:38912
	ds_read_b128 v[208:211], v235 offset:39936
	global_load_lds_dwordx4 v194, s[52:53]
	s_mov_b32 m0, s61
	s_nop 0
	global_load_lds_dwordx4 v196, s[52:53]
	s_waitcnt vmcnt(8)
	s_waitcnt lgkmcnt(0)
	s_barrier
; #define PG8_STAGE(bufoff, gbase, voff) do { _Pragma("unroll") for (int _i = 0; _i < 2; ++_i) \
;         __builtin_amdgcn_global_load_lds((const unsigned*)((const char*)(gbase) + (voff)[_i]), (PG8_LAS unsigned*)(lds + (bufoff) + ldsw + _i * 8192), 16, 0, 0); } while (0)
; #define PG8_LDA(dst, b, h) do { _Pragma("unroll") for (int m = 0; m < 4; ++m) _Pragma("unroll") for (int k = 0; k < 2; ++k) dst[m][k] = *(const PG8_LAS bf16x8*)(lds + PG8_SA(b, h) + aoff + m * 2048 + k * 1024); } while (0)
; #define PG8_MMA(ai, bj, At, Bt) do { __builtin_amdgcn_s_setprio(1); _Pragma("unroll") for (int m = 0; m < 4; ++m) _Pragma("unroll") for (int n = 0; n < 2; ++n) _Pragma("unroll") for (int k = 0; k < 2; ++k) \
;         acc[ai][bj][m][n] = __builtin_amdgcn_mfma_f32_16x16x32_bf16(Bt[n][k], At[m][k], acc[ai][bj][m][n], 0, 0, 0); __builtin_amdgcn_s_setprio(0); } while (0)
; #define PG8_WAIT_V(n) asm volatile("s_waitcnt vmcnt(" #n ")" ::: "memory")
; #define PG8_WAIT_L(n) asm volatile("s_waitcnt lgkmcnt(" #n ")" ::: "memory")
; #define PG8_BAR __builtin_amdgcn_s_barrier()
; #define PG8_SCHED __builtin_amdgcn_sched_barrier(0)
; template <class Epi, class Sched, bool ALIGN_EPI = false, bool SP2 = false>
; __device__ __forceinline__ void gemm_phase(PG8_LAS unsigned char* lds, const Gemm g, const Sched& S, const Epi& E, const int wv) {
;     ...
;             PG8_WAIT_V(8); PG8_WAIT_L(0); PG8_BAR; PG8_MMA(0, 0, At, B0); PG8_MMA(0, 1, At, B1); PG8_BAR; PG8_SCHED;
;             PG8_LDA(At, 1, 1); PG8_STAGE(PG8_SB(1, 0), b3, voffB); PG8_STAGE(PG8_SB(1, 1), b3 + hstepB, voffB); PG8_STAGE(PG8_SA(1, 0), a3, voffA);
;             PG8_WAIT_V(8); PG8_WAIT_L(0); PG8_BAR; PG8_MMA(1, 0, At, B0); PG8_MMA(1, 1, At, B1); PG8_BAR; PG8_SCHED;
	v_mfma_f32_16x16x32_bf16 v[134:137], v[114:117], v[162:165], v[134:137]
	v_mfma_f32_16x16x32_bf16 v[130:133], v[138:141], v[162:165], v[130:133]
	v_mfma_f32_16x16x32_bf16 v[110:113], v[114:117], v[170:173], v[110:113]
	v_mfma_f32_16x16x32_bf16 v[106:109], v[138:141], v[170:173], v[106:109]
	v_mfma_f32_16x16x32_bf16 v[94:97], v[114:117], v[178:181], v[94:97]
	v_mfma_f32_16x16x32_bf16 v[90:93], v[138:141], v[178:181], v[90:93]
	v_mfma_f32_16x16x32_bf16 v[78:81], v[114:117], v[204:207], v[78:81]
	v_mfma_f32_16x16x32_bf16 v[74:77], v[138:141], v[204:207], v[74:77]
	v_mfma_f32_16x16x32_bf16 v[134:137], v[126:129], v[166:169], v[134:137]
	v_mfma_f32_16x16x32_bf16 v[130:133], v[142:145], v[166:169], v[130:133]
	v_mfma_f32_16x16x32_bf16 v[110:113], v[126:129], v[174:177], v[110:113]
	v_mfma_f32_16x16x32_bf16 v[106:109], v[142:145], v[174:177], v[106:109]
	v_mfma_f32_16x16x32_bf16 v[94:97], v[126:129], v[182:185], v[94:97]
	v_mfma_f32_16x16x32_bf16 v[90:93], v[142:145], v[182:185], v[90:93]
	v_mfma_f32_16x16x32_bf16 v[78:81], v[126:129], v[208:211], v[78:81]
	v_mfma_f32_16x16x32_bf16 v[74:77], v[142:145], v[208:211], v[74:77]
	v_mfma_f32_16x16x32_bf16 v[122:125], v[146:149], v[162:165], v[122:125]
	v_mfma_f32_16x16x32_bf16 v[118:121], v[154:157], v[162:165], v[118:121]
	v_mfma_f32_16x16x32_bf16 v[102:105], v[146:149], v[170:173], v[102:105]
	v_mfma_f32_16x16x32_bf16 v[98:101], v[154:157], v[170:173], v[98:101]
	v_mfma_f32_16x16x32_bf16 v[86:89], v[146:149], v[178:181], v[86:89]
	v_mfma_f32_16x16x32_bf16 v[82:85], v[154:157], v[178:181], v[82:85]
	v_mfma_f32_16x16x32_bf16 v[70:73], v[146:149], v[204:207], v[70:73]
	v_mfma_f32_16x16x32_bf16 v[66:69], v[154:157], v[204:207], v[66:69]
	v_mfma_f32_16x16x32_bf16 v[122:125], v[150:153], v[166:169], v[122:125]
	v_mfma_f32_16x16x32_bf16 v[118:121], v[158:161], v[166:169], v[118:121]
	v_mfma_f32_16x16x32_bf16 v[102:105], v[150:153], v[174:177], v[102:105]
	v_mfma_f32_16x16x32_bf16 v[98:101], v[158:161], v[174:177], v[98:101]
	v_mfma_f32_16x16x32_bf16 v[86:89], v[150:153], v[182:185], v[86:89]
	v_mfma_f32_16x16x32_bf16 v[82:85], v[158:161], v[182:185], v[82:85]
	v_mfma_f32_16x16x32_bf16 v[70:73], v[150:153], v[208:211], v[70:73]
	v_mfma_f32_16x16x32_bf16 v[66:69], v[158:161], v[208:211], v[66:69]
	s_barrier
	s_add_i32 s52, s71, s3
	s_add_i32 m0, s52, 0xffffff80
	ds_read_b128 v[162:165], v235 offset:49152
	ds_read_b128 v[166:169], v235 offset:50176
	ds_read_b128 v[170:173], v235 offset:51200
	ds_read_b128 v[174:177], v235 offset:52224
	ds_read_b128 v[178:181], v235 offset:53248
	ds_read_b128 v[182:185], v235 offset:54272
	ds_read_b128 v[204:207], v235 offset:55296
	ds_read_b128 v[208:211], v235 offset:56320
	global_load_lds_dwordx4 v[190:191], off offset:128
	s_add_i32 m0, s52, 0x1f80
	s_add_i32 s52, s72, s3
	global_load_lds_dwordx4 v[192:193], off offset:128
	s_add_i32 m0, s52, 0xffffff80
	s_nop 0
	global_load_lds_dwordx4 v[212:213], off offset:128
	s_add_i32 m0, s52, 0x1f80
	s_nop 0
	global_load_lds_dwordx4 v[214:215], off offset:128
	s_add_i32 m0, s63, 0xffffff80
	s_nop 0
	global_load_lds_dwordx4 v[216:217], off offset:128
	s_add_i32 m0, s64, 0xffffff80
	s_nop 0
	global_load_lds_dwordx4 v[218:219], off offset:128
	s_waitcnt vmcnt(8)
	s_waitcnt lgkmcnt(0)
	s_barrier
	v_mfma_f32_16x16x32_bf16 v[62:65], v[114:117], v[162:165], v[62:65]
	v_mfma_f32_16x16x32_bf16 v[58:61], v[138:141], v[162:165], v[58:61]
	v_mfma_f32_16x16x32_bf16 v[46:49], v[114:117], v[170:173], v[46:49]
	v_mfma_f32_16x16x32_bf16 v[42:45], v[138:141], v[170:173], v[42:45]
	v_mfma_f32_16x16x32_bf16 v[30:33], v[114:117], v[178:181], v[30:33]
	v_mfma_f32_16x16x32_bf16 v[26:29], v[138:141], v[178:181], v[26:29]
	v_mfma_f32_16x16x32_bf16 v[14:17], v[114:117], v[204:207], v[14:17]
	v_mfma_f32_16x16x32_bf16 v[10:13], v[138:141], v[204:207], v[10:13]
	v_mfma_f32_16x16x32_bf16 v[62:65], v[126:129], v[166:169], v[62:65]
	v_mfma_f32_16x16x32_bf16 v[58:61], v[142:145], v[166:169], v[58:61]
	v_mfma_f32_16x16x32_bf16 v[46:49], v[126:129], v[174:177], v[46:49]
	v_mfma_f32_16x16x32_bf16 v[42:45], v[142:145], v[174:177], v[42:45]
	v_mfma_f32_16x16x32_bf16 v[30:33], v[126:129], v[182:185], v[30:33]
	v_mfma_f32_16x16x32_bf16 v[26:29], v[142:145], v[182:185], v[26:29]
	v_mfma_f32_16x16x32_bf16 v[14:17], v[126:129], v[208:211], v[14:17]
	v_mfma_f32_16x16x32_bf16 v[10:13], v[142:145], v[208:211], v[10:13]
	v_mfma_f32_16x16x32_bf16 v[54:57], v[146:149], v[162:165], v[54:57]
	v_mfma_f32_16x16x32_bf16 v[50:53], v[154:157], v[162:165], v[50:53]
	v_mfma_f32_16x16x32_bf16 v[38:41], v[146:149], v[170:173], v[38:41]
	v_mfma_f32_16x16x32_bf16 v[34:37], v[154:157], v[170:173], v[34:37]
	v_mfma_f32_16x16x32_bf16 v[22:25], v[146:149], v[178:181], v[22:25]
	v_mfma_f32_16x16x32_bf16 v[18:21], v[154:157], v[178:181], v[18:21]
	v_mfma_f32_16x16x32_bf16 v[6:9], v[146:149], v[204:207], v[6:9]
	v_mfma_f32_16x16x32_bf16 v[2:5], v[154:157], v[204:207], v[2:5]
	v_mfma_f32_16x16x32_bf16 v[54:57], v[150:153], v[166:169], v[54:57]
	v_mfma_f32_16x16x32_bf16 v[50:53], v[158:161], v[166:169], v[50:53]
	v_mfma_f32_16x16x32_bf16 v[38:41], v[150:153], v[174:177], v[38:41]
	v_mfma_f32_16x16x32_bf16 v[34:37], v[158:161], v[174:177], v[34:37]
	v_mfma_f32_16x16x32_bf16 v[22:25], v[150:153], v[182:185], v[22:25]
	v_mfma_f32_16x16x32_bf16 v[18:21], v[158:161], v[182:185], v[18:21]
	v_mfma_f32_16x16x32_bf16 v[6:9], v[150:153], v[208:211], v[6:9]
	v_mfma_f32_16x16x32_bf16 v[2:5], v[158:161], v[208:211], v[2:5]
	s_barrier
	s_add_u32 s44, s44, 0x100
	s_addc_u32 s45, s45, 0
	s_add_u32 s54, s54, 0x100
	s_addc_u32 s55, s55, 0
	s_cmp_ge_i32 s70, s62
	s_mov_b32 s52, s70
	s_cbranch_scc0 .LBB0_1385
	s_mov_b32 s72, 0x10000
	s_mov_b32 s73, 0x12000
	s_mov_b32 s74, 0x14000
	s_mov_b32 s70, 0x18000
	s_mov_b32 s71, 0x3f317217
	s_and_b64 vcc, exec, s[46:47]
	s_cbranch_vccz .LBB0_1361

; #define PG8_STAGE(bufoff, gbase, voff) do { _Pragma("unroll") for (int _i = 0; _i < 2; ++_i) \
;         __builtin_amdgcn_global_load_lds((const unsigned*)((const char*)(gbase) + (voff)[_i]), (PG8_LAS unsigned*)(lds + (bufoff) + ldsw + _i * 8192), 16, 0, 0); } while (0)
; #define PG8_LDA(dst, b, h) do { _Pragma("unroll") for (int m = 0; m < 4; ++m) _Pragma("unroll") for (int k = 0; k < 2; ++k) dst[m][k] = *(const PG8_LAS bf16x8*)(lds + PG8_SA(b, h) + aoff + m * 2048 + k * 1024); } while (0)
; #define PG8_LDB(dst, b, h) do { _Pragma("unroll") for (int n = 0; n < 2; ++n) _Pragma("unroll") for (int k = 0; k < 2; ++k) dst[n][k] = *(const PG8_LAS bf16x8*)(lds + PG8_SB(b, h) + boff + n * 2048 + k * 1024); } while (0)
; #define PG8_MMA(ai, bj, At, Bt) do { __builtin_amdgcn_s_setprio(1); _Pragma("unroll") for (int m = 0; m < 4; ++m) _Pragma("unroll") for (int n = 0; n < 2; ++n) _Pragma("unroll") for (int k = 0; k < 2; ++k) \
;         acc[ai][bj][m][n] = __builtin_amdgcn_mfma_f32_16x16x32_bf16(Bt[n][k], At[m][k], acc[ai][bj][m][n], 0, 0, 0); __builtin_amdgcn_s_setprio(0); } while (0)
; #define PG8_WAIT_V(n) asm volatile("s_waitcnt vmcnt(" #n ")" ::: "memory")
; #define PG8_WAIT_L(n) asm volatile("s_waitcnt lgkmcnt(" #n ")" ::: "memory")
; template <class Epi, class Sched, bool ALIGN_EPI = false, bool SP2 = false>
; __device__ __forceinline__ void gemm_phase(PG8_LAS unsigned char* lds, const Gemm g, const Sched& S, const Epi& E, const int wv) {
;     ...
;             const bool last = (t == nt - 2);
;             const char* a1 = cA + (size_t)(t + 1) * kstep;
;             const char* a2 = last ? nA : cA + (size_t)(t + 2) * kstep; const char* b2 = last ? nB : cB + (size_t)(t + 2) * kstep;
;             const char* a3 = a2 + kstep; const char* b3 = b2 + kstep;
;             if (last && has_next) S.a_ready(nxt);
;             if constexpr (SP2) {
;             PG8_LDB(B0, 0, 0); PG8_LDB(B1, 0, 1); PG8_SCHED; PG8_LDA(At, 0, 0); PG8_STAGE(PG8_SA(1, 1), a1 + hstepA, voffA);
;             PG8_WAIT_V(8); PG8_WAIT_L(0); PG8_BAR; PG8_MMA(0, 0, At, B0); PG8_MMA(0, 1, At, B1); PG8_BAR; PG8_SCHED;
;             PG8_LDA(At, 0, 1); PG8_STAGE(PG8_SB(0, 0), b2, voffB); PG8_STAGE(PG8_SB(0, 1), b2 + hstepB, voffB); PG8_STAGE(PG8_SA(0, 0), a2, voffA);
;             PG8_WAIT_V(8); PG8_WAIT_L(0); PG8_BAR; PG8_MMA(1, 0, At, B0); PG8_MMA(1, 1, At, B1); PG8_BAR; PG8_SCHED;
.LBB0_1495:
	s_add_i32 s52, s46, 2
	s_add_u32 s14, s48, 0x100
	s_addc_u32 s15, s49, 0
	s_add_i32 s53, 0, 0x10000
	s_cmp_eq_u32 s72, s46
	s_cselect_b32 s47, s11, s15
	s_cselect_b32 s46, s13, s14
	s_cselect_b32 s77, s87, s51
	s_cselect_b32 s76, s86, s35
	s_add_i32 s78, 0, 0x14000
	ds_read_b128 v[138:141], v192
	ds_read_b128 v[142:145], v192 offset:1024
	ds_read_b128 v[146:149], v192 offset:2048
	ds_read_b128 v[150:153], v192 offset:3072
	ds_read_b128 v[154:157], v193
	ds_read_b128 v[158:161], v193 offset:1024
	ds_read_b128 v[162:165], v193 offset:2048
	ds_read_b128 v[166:169], v193 offset:3072
	s_add_i32 m0, s64, 0xc000
	ds_read_b128 v[194:197], v211
	ds_read_b128 v[198:201], v211 offset:1024
	ds_read_b128 v[202:205], v211 offset:2048
	ds_read_b128 v[214:217], v211 offset:3072
	ds_read_b128 v[228:231], v211 offset:4096
	ds_read_b128 v[232:235], v211 offset:5120
	ds_read_b128 v[236:239], v211 offset:6144
	ds_read_b128 v[240:243], v211 offset:7168
	global_load_lds_dwordx4 v182, s[48:49]
	v_lshl_add_u64 v[190:191], s[48:49], 0, v[184:185]
	s_add_i32 m0, s64, 0xe000
	s_nop 0
	global_load_lds_dwordx4 v[190:191], off
	s_waitcnt vmcnt(8)
	s_waitcnt lgkmcnt(0)
	s_barrier
	v_mfma_f32_16x16x32_bf16 v[118:121], v[138:141], v[194:197], v[118:121]
	v_mfma_f32_16x16x32_bf16 v[46:49], v[146:149], v[194:197], v[46:49]
	v_mfma_f32_16x16x32_bf16 v[110:113], v[138:141], v[202:205], v[110:113]
	v_mfma_f32_16x16x32_bf16 v[38:41], v[146:149], v[202:205], v[38:41]
	v_mfma_f32_16x16x32_bf16 v[134:137], v[138:141], v[228:231], v[134:137]
	v_mfma_f32_16x16x32_bf16 v[62:65], v[146:149], v[228:231], v[62:65]
	v_mfma_f32_16x16x32_bf16 v[130:133], v[138:141], v[236:239], v[130:133]
	v_mfma_f32_16x16x32_bf16 v[58:61], v[146:149], v[236:239], v[58:61]
	v_mfma_f32_16x16x32_bf16 v[118:121], v[142:145], v[198:201], v[118:121]
	v_mfma_f32_16x16x32_bf16 v[46:49], v[150:153], v[198:201], v[46:49]
	v_mfma_f32_16x16x32_bf16 v[110:113], v[142:145], v[214:217], v[110:113]
	v_mfma_f32_16x16x32_bf16 v[38:41], v[150:153], v[214:217], v[38:41]
	v_mfma_f32_16x16x32_bf16 v[134:137], v[142:145], v[232:235], v[134:137]
	v_mfma_f32_16x16x32_bf16 v[62:65], v[150:153], v[232:235], v[62:65]
	v_mfma_f32_16x16x32_bf16 v[130:133], v[142:145], v[240:243], v[130:133]
	v_mfma_f32_16x16x32_bf16 v[58:61], v[150:153], v[240:243], v[58:61]
	v_mfma_f32_16x16x32_bf16 v[114:117], v[154:157], v[194:197], v[114:117]
	v_mfma_f32_16x16x32_bf16 v[42:45], v[162:165], v[194:197], v[42:45]
	v_mfma_f32_16x16x32_bf16 v[106:109], v[154:157], v[202:205], v[106:109]
	v_mfma_f32_16x16x32_bf16 v[34:37], v[162:165], v[202:205], v[34:37]
	v_mfma_f32_16x16x32_bf16 v[126:129], v[154:157], v[228:231], v[126:129]
	v_mfma_f32_16x16x32_bf16 v[54:57], v[162:165], v[228:231], v[54:57]
	v_mfma_f32_16x16x32_bf16 v[122:125], v[154:157], v[236:239], v[122:125]
	v_mfma_f32_16x16x32_bf16 v[50:53], v[162:165], v[236:239], v[50:53]
	v_mfma_f32_16x16x32_bf16 v[114:117], v[158:161], v[198:201], v[114:117]
	v_mfma_f32_16x16x32_bf16 v[42:45], v[166:169], v[198:201], v[42:45]
	v_mfma_f32_16x16x32_bf16 v[106:109], v[158:161], v[214:217], v[106:109]
	v_mfma_f32_16x16x32_bf16 v[34:37], v[166:169], v[214:217], v[34:37]
	v_mfma_f32_16x16x32_bf16 v[126:129], v[158:161], v[232:235], v[126:129]
	v_mfma_f32_16x16x32_bf16 v[54:57], v[166:169], v[232:235], v[54:57]
	v_mfma_f32_16x16x32_bf16 v[122:125], v[158:161], v[240:243], v[122:125]
	v_mfma_f32_16x16x32_bf16 v[50:53], v[166:169], v[240:243], v[50:53]
	s_barrier
	s_add_i32 s48, s53, s63
	s_mov_b32 m0, s48
	ds_read_b128 v[194:197], v211 offset:16384
	ds_read_b128 v[198:201], v211 offset:17408
	ds_read_b128 v[202:205], v211 offset:18432
	ds_read_b128 v[214:217], v211 offset:19456
	ds_read_b128 v[228:231], v211 offset:20480
	ds_read_b128 v[232:235], v211 offset:21504
	ds_read_b128 v[236:239], v211 offset:22528
	ds_read_b128 v[240:243], v211 offset:23552
	global_load_lds_dwordx4 v0, s[76:77]
	s_add_i32 m0, s48, 0x2000
	s_add_u32 s48, s76, s16
	s_addc_u32 s49, s77, s17
	s_add_i32 s53, s78, s63
	global_load_lds_dwordx4 v174, s[76:77]
	v_lshl_add_u64 v[218:219], s[48:49], 0, v[0:1]
	s_mov_b32 m0, s53
	v_lshl_add_u64 v[244:245], s[48:49], 0, v[174:175]
	global_load_lds_dwordx4 v[218:219], off
	s_add_i32 m0, s53, 0x2000
	v_lshl_add_u64 v[246:247], s[46:47], 0, v[170:171]
	global_load_lds_dwordx4 v[244:245], off
	s_mov_b32 m0, s64
	v_lshl_add_u64 v[248:249], s[46:47], 0, v[172:173]
	global_load_lds_dwordx4 v[246:247], off
	s_mov_b32 m0, s65
	s_nop 0
	global_load_lds_dwordx4 v[248:249], off
	s_waitcnt vmcnt(8)
	s_waitcnt lgkmcnt(0)
	s_barrier
; #define PG8_STAGE(bufoff, gbase, voff) do { _Pragma("unroll") for (int _i = 0; _i < 2; ++_i) \
;         __builtin_amdgcn_global_load_lds((const unsigned*)((const char*)(gbase) + (voff)[_i]), (PG8_LAS unsigned*)(lds + (bufoff) + ldsw + _i * 8192), 16, 0, 0); } while (0)
; #define PG8_LDA(dst, b, h) do { _Pragma("unroll") for (int m = 0; m < 4; ++m) _Pragma("unroll") for (int k = 0; k < 2; ++k) dst[m][k] = *(const PG8_LAS bf16x8*)(lds + PG8_SA(b, h) + aoff + m * 2048 + k * 1024); } while (0)
; #define PG8_LDB(dst, b, h) do { _Pragma("unroll") for (int n = 0; n < 2; ++n) _Pragma("unroll") for (int k = 0; k < 2; ++k) dst[n][k] = *(const PG8_LAS bf16x8*)(lds + PG8_SB(b, h) + boff + n * 2048 + k * 1024); } while (0)
; #define PG8_MMA(ai, bj, At, Bt) do { __builtin_amdgcn_s_setprio(1); _Pragma("unroll") for (int m = 0; m < 4; ++m) _Pragma("unroll") for (int n = 0; n < 2; ++n) _Pragma("unroll") for (int k = 0; k < 2; ++k) \
;         acc[ai][bj][m][n] = __builtin_amdgcn_mfma_f32_16x16x32_bf16(Bt[n][k], At[m][k], acc[ai][bj][m][n], 0, 0, 0); __builtin_amdgcn_s_setprio(0); } while (0)
; #define PG8_WAIT_V(n) asm volatile("s_waitcnt vmcnt(" #n ")" ::: "memory")
; #define PG8_WAIT_L(n) asm volatile("s_waitcnt lgkmcnt(" #n ")" ::: "memory")
; #define PG8_BAR __builtin_amdgcn_s_barrier()
; #define PG8_SCHED __builtin_amdgcn_sched_barrier(0)
; template <class Epi, class Sched, bool ALIGN_EPI = false, bool SP2 = false>
; __device__ __forceinline__ void gemm_phase(PG8_LAS unsigned char* lds, const Gemm g, const Sched& S, const Epi& E, const int wv) {
;     ...
;             PG8_WAIT_V(8); PG8_WAIT_L(0); PG8_BAR; PG8_MMA(1, 0, At, B0); PG8_MMA(1, 1, At, B1); PG8_BAR; PG8_SCHED;
;             PG8_LDB(B0, 1, 0); PG8_LDB(B1, 1, 1); PG8_SCHED; PG8_LDA(At, 1, 0); PG8_STAGE(PG8_SA(0, 1), a2 + hstepA, voffA);
;             PG8_WAIT_V(8); PG8_WAIT_L(0); PG8_BAR; PG8_MMA(0, 0, At, B0); PG8_MMA(0, 1, At, B1); PG8_BAR; PG8_SCHED;
	v_mfma_f32_16x16x32_bf16 v[86:89], v[138:141], v[194:197], v[86:89]
	v_mfma_f32_16x16x32_bf16 v[14:17], v[146:149], v[194:197], v[14:17]
	v_mfma_f32_16x16x32_bf16 v[70:73], v[138:141], v[202:205], v[70:73]
	v_mfma_f32_16x16x32_bf16 v[6:9], v[146:149], v[202:205], v[6:9]
	v_mfma_f32_16x16x32_bf16 v[102:105], v[138:141], v[228:231], v[102:105]
	v_mfma_f32_16x16x32_bf16 v[30:33], v[146:149], v[228:231], v[30:33]
	v_mfma_f32_16x16x32_bf16 v[98:101], v[138:141], v[236:239], v[98:101]
	v_mfma_f32_16x16x32_bf16 v[26:29], v[146:149], v[236:239], v[26:29]
	v_mfma_f32_16x16x32_bf16 v[86:89], v[142:145], v[198:201], v[86:89]
	v_mfma_f32_16x16x32_bf16 v[14:17], v[150:153], v[198:201], v[14:17]
	v_mfma_f32_16x16x32_bf16 v[70:73], v[142:145], v[214:217], v[70:73]
	v_mfma_f32_16x16x32_bf16 v[6:9], v[150:153], v[214:217], v[6:9]
	v_mfma_f32_16x16x32_bf16 v[102:105], v[142:145], v[232:235], v[102:105]
	v_mfma_f32_16x16x32_bf16 v[30:33], v[150:153], v[232:235], v[30:33]
	v_mfma_f32_16x16x32_bf16 v[98:101], v[142:145], v[240:243], v[98:101]
	v_mfma_f32_16x16x32_bf16 v[26:29], v[150:153], v[240:243], v[26:29]
	v_mfma_f32_16x16x32_bf16 v[82:85], v[154:157], v[194:197], v[82:85]
	v_mfma_f32_16x16x32_bf16 v[10:13], v[162:165], v[194:197], v[10:13]
	v_mfma_f32_16x16x32_bf16 v[66:69], v[154:157], v[202:205], v[66:69]
	v_mfma_f32_16x16x32_bf16 v[2:5], v[162:165], v[202:205], v[2:5]
	v_mfma_f32_16x16x32_bf16 v[94:97], v[154:157], v[228:231], v[94:97]
	v_mfma_f32_16x16x32_bf16 v[22:25], v[162:165], v[228:231], v[22:25]
	v_mfma_f32_16x16x32_bf16 v[90:93], v[154:157], v[236:239], v[90:93]
	v_mfma_f32_16x16x32_bf16 v[18:21], v[162:165], v[236:239], v[18:21]
	v_mfma_f32_16x16x32_bf16 v[82:85], v[158:161], v[198:201], v[82:85]
	v_mfma_f32_16x16x32_bf16 v[10:13], v[166:169], v[198:201], v[10:13]
	v_mfma_f32_16x16x32_bf16 v[66:69], v[158:161], v[214:217], v[66:69]
	v_mfma_f32_16x16x32_bf16 v[2:5], v[166:169], v[214:217], v[2:5]
	v_mfma_f32_16x16x32_bf16 v[94:97], v[158:161], v[232:235], v[94:97]
	v_mfma_f32_16x16x32_bf16 v[22:25], v[166:169], v[232:235], v[22:25]
	v_mfma_f32_16x16x32_bf16 v[90:93], v[158:161], v[240:243], v[90:93]
	v_mfma_f32_16x16x32_bf16 v[18:21], v[166:169], v[240:243], v[18:21]
	s_barrier
	s_add_i32 s48, 0, 0x18000
	s_add_i32 s49, 0, 0x1c000
	ds_read_b128 v[138:141], v213
	ds_read_b128 v[142:145], v213 offset:1024
	ds_read_b128 v[146:149], v213 offset:2048
	ds_read_b128 v[150:153], v213 offset:3072
	ds_read_b128 v[154:157], v227
	ds_read_b128 v[158:161], v227 offset:1024
	ds_read_b128 v[162:165], v227 offset:2048
	ds_read_b128 v[166:169], v227 offset:3072
	s_add_u32 s46, s46, 0x80000
	s_addc_u32 s47, s47, 0
	s_mov_b32 m0, s66
	ds_read_b128 v[194:197], v211 offset:32768
	ds_read_b128 v[198:201], v211 offset:33792
	ds_read_b128 v[202:205], v211 offset:34816
	ds_read_b128 v[214:217], v211 offset:35840
	ds_read_b128 v[228:231], v211 offset:36864
	ds_read_b128 v[232:235], v211 offset:37888
	ds_read_b128 v[236:239], v211 offset:38912
	ds_read_b128 v[240:243], v211 offset:39936
	global_load_lds_dwordx4 v170, s[46:47]
	s_mov_b32 m0, s67
	s_nop 0
	global_load_lds_dwordx4 v172, s[46:47]
	s_waitcnt vmcnt(8)
	s_waitcnt lgkmcnt(0)
	s_barrier
	v_mfma_f32_16x16x32_bf16 v[118:121], v[138:141], v[194:197], v[118:121]
	v_mfma_f32_16x16x32_bf16 v[46:49], v[146:149], v[194:197], v[46:49]
	v_mfma_f32_16x16x32_bf16 v[110:113], v[138:141], v[202:205], v[110:113]
	v_mfma_f32_16x16x32_bf16 v[38:41], v[146:149], v[202:205], v[38:41]
	v_mfma_f32_16x16x32_bf16 v[134:137], v[138:141], v[228:231], v[134:137]
	v_mfma_f32_16x16x32_bf16 v[62:65], v[146:149], v[228:231], v[62:65]
	v_mfma_f32_16x16x32_bf16 v[130:133], v[138:141], v[236:239], v[130:133]
	v_mfma_f32_16x16x32_bf16 v[58:61], v[146:149], v[236:239], v[58:61]
	v_mfma_f32_16x16x32_bf16 v[118:121], v[142:145], v[198:201], v[118:121]
	v_mfma_f32_16x16x32_bf16 v[46:49], v[150:153], v[198:201], v[46:49]
	v_mfma_f32_16x16x32_bf16 v[110:113], v[142:145], v[214:217], v[110:113]
	v_mfma_f32_16x16x32_bf16 v[38:41], v[150:153], v[214:217], v[38:41]
	v_mfma_f32_16x16x32_bf16 v[134:137], v[142:145], v[232:235], v[134:137]
	v_mfma_f32_16x16x32_bf16 v[62:65], v[150:153], v[232:235], v[62:65]
	v_mfma_f32_16x16x32_bf16 v[130:133], v[142:145], v[240:243], v[130:133]
	v_mfma_f32_16x16x32_bf16 v[58:61], v[150:153], v[240:243], v[58:61]
	v_mfma_f32_16x16x32_bf16 v[114:117], v[154:157], v[194:197], v[114:117]
	v_mfma_f32_16x16x32_bf16 v[42:45], v[162:165], v[194:197], v[42:45]
	v_mfma_f32_16x16x32_bf16 v[106:109], v[154:157], v[202:205], v[106:109]
	v_mfma_f32_16x16x32_bf16 v[34:37], v[162:165], v[202:205], v[34:37]
	v_mfma_f32_16x16x32_bf16 v[126:129], v[154:157], v[228:231], v[126:129]
	v_mfma_f32_16x16x32_bf16 v[54:57], v[162:165], v[228:231], v[54:57]
	v_mfma_f32_16x16x32_bf16 v[122:125], v[154:157], v[236:239], v[122:125]
	v_mfma_f32_16x16x32_bf16 v[50:53], v[162:165], v[236:239], v[50:53]
	v_mfma_f32_16x16x32_bf16 v[114:117], v[158:161], v[198:201], v[114:117]
	v_mfma_f32_16x16x32_bf16 v[42:45], v[166:169], v[198:201], v[42:45]
	v_mfma_f32_16x16x32_bf16 v[106:109], v[158:161], v[214:217], v[106:109]
	v_mfma_f32_16x16x32_bf16 v[34:37], v[166:169], v[214:217], v[34:37]
	v_mfma_f32_16x16x32_bf16 v[126:129], v[158:161], v[232:235], v[126:129]
	v_mfma_f32_16x16x32_bf16 v[54:57], v[166:169], v[232:235], v[54:57]
	v_mfma_f32_16x16x32_bf16 v[122:125], v[158:161], v[240:243], v[122:125]
	v_mfma_f32_16x16x32_bf16 v[50:53], v[166:169], v[240:243], v[50:53]
	s_barrier
; #define PG8_STAGE(bufoff, gbase, voff) do { _Pragma("unroll") for (int _i = 0; _i < 2; ++_i) \
;         __builtin_amdgcn_global_load_lds((const unsigned*)((const char*)(gbase) + (voff)[_i]), (PG8_LAS unsigned*)(lds + (bufoff) + ldsw + _i * 8192), 16, 0, 0); } while (0)
; #define PG8_LDA(dst, b, h) do { _Pragma("unroll") for (int m = 0; m < 4; ++m) _Pragma("unroll") for (int k = 0; k < 2; ++k) dst[m][k] = *(const PG8_LAS bf16x8*)(lds + PG8_SA(b, h) + aoff + m * 2048 + k * 1024); } while (0)
; #define PG8_MMA(ai, bj, At, Bt) do { __builtin_amdgcn_s_setprio(1); _Pragma("unroll") for (int m = 0; m < 4; ++m) _Pragma("unroll") for (int n = 0; n < 2; ++n) _Pragma("unroll") for (int k = 0; k < 2; ++k) \
;         acc[ai][bj][m][n] = __builtin_amdgcn_mfma_f32_16x16x32_bf16(Bt[n][k], At[m][k], acc[ai][bj][m][n], 0, 0, 0); __builtin_amdgcn_s_setprio(0); } while (0)
; #define PG8_WAIT_V(n) asm volatile("s_waitcnt vmcnt(" #n ")" ::: "memory")
; #define PG8_WAIT_L(n) asm volatile("s_waitcnt lgkmcnt(" #n ")" ::: "memory")
; #define PG8_BAR __builtin_amdgcn_s_barrier()
; #define PG8_SCHED __builtin_amdgcn_sched_barrier(0)
; template <class Epi, class Sched, bool ALIGN_EPI = false, bool SP2 = false>
; __device__ __forceinline__ void gemm_phase(PG8_LAS unsigned char* lds, const Gemm g, const Sched& S, const Epi& E, const int wv) {
;     ...
;             PG8_LDA(At, 1, 1); PG8_STAGE(PG8_SB(1, 0), b3, voffB); PG8_STAGE(PG8_SB(1, 1), b3 + hstepB, voffB); PG8_STAGE(PG8_SA(1, 0), a3, voffA);
;             PG8_WAIT_V(8); PG8_WAIT_L(0); PG8_BAR; PG8_MMA(1, 0, At, B0); PG8_MMA(1, 1, At, B1); PG8_BAR; PG8_SCHED;
	s_add_i32 s46, s48, s63
	s_add_i32 m0, s46, 0xffffff80
	ds_read_b128 v[194:197], v211 offset:49152
	ds_read_b128 v[198:201], v211 offset:50176
	ds_read_b128 v[202:205], v211 offset:51200
	ds_read_b128 v[214:217], v211 offset:52224
	ds_read_b128 v[228:231], v211 offset:53248
	ds_read_b128 v[232:235], v211 offset:54272
	ds_read_b128 v[236:239], v211 offset:55296
	ds_read_b128 v[240:243], v211 offset:56320
	global_load_lds_dwordx4 v0, s[76:77] offset:128
	s_add_i32 m0, s46, 0x1f80
	s_add_i32 s46, s49, s63
	global_load_lds_dwordx4 v174, s[76:77] offset:128
	s_add_i32 m0, s46, 0xffffff80
	s_nop 0
	global_load_lds_dwordx4 v[218:219], off offset:128
	s_add_i32 m0, s46, 0x1f80
	s_nop 0
	global_load_lds_dwordx4 v[244:245], off offset:128
	s_add_i32 m0, s70, 0xffffff80
	s_nop 0
	global_load_lds_dwordx4 v[246:247], off offset:128
	s_add_i32 m0, s71, 0xffffff80
	s_nop 0
	global_load_lds_dwordx4 v[248:249], off offset:128
	s_waitcnt vmcnt(8)
	s_waitcnt lgkmcnt(0)
	s_barrier
	v_mfma_f32_16x16x32_bf16 v[86:89], v[138:141], v[194:197], v[86:89]
	v_mfma_f32_16x16x32_bf16 v[14:17], v[146:149], v[194:197], v[14:17]
	v_mfma_f32_16x16x32_bf16 v[70:73], v[138:141], v[202:205], v[70:73]
	v_mfma_f32_16x16x32_bf16 v[6:9], v[146:149], v[202:205], v[6:9]
	v_mfma_f32_16x16x32_bf16 v[102:105], v[138:141], v[228:231], v[102:105]
	v_mfma_f32_16x16x32_bf16 v[30:33], v[146:149], v[228:231], v[30:33]
	v_mfma_f32_16x16x32_bf16 v[98:101], v[138:141], v[236:239], v[98:101]
	v_mfma_f32_16x16x32_bf16 v[26:29], v[146:149], v[236:239], v[26:29]
	v_mfma_f32_16x16x32_bf16 v[86:89], v[142:145], v[198:201], v[86:89]
	v_mfma_f32_16x16x32_bf16 v[14:17], v[150:153], v[198:201], v[14:17]
	v_mfma_f32_16x16x32_bf16 v[70:73], v[142:145], v[214:217], v[70:73]
	v_mfma_f32_16x16x32_bf16 v[6:9], v[150:153], v[214:217], v[6:9]
	v_mfma_f32_16x16x32_bf16 v[102:105], v[142:145], v[232:235], v[102:105]
	v_mfma_f32_16x16x32_bf16 v[30:33], v[150:153], v[232:235], v[30:33]
	v_mfma_f32_16x16x32_bf16 v[98:101], v[142:145], v[240:243], v[98:101]
	v_mfma_f32_16x16x32_bf16 v[26:29], v[150:153], v[240:243], v[26:29]
	v_mfma_f32_16x16x32_bf16 v[82:85], v[154:157], v[194:197], v[82:85]
	v_mfma_f32_16x16x32_bf16 v[10:13], v[162:165], v[194:197], v[10:13]
	v_mfma_f32_16x16x32_bf16 v[66:69], v[154:157], v[202:205], v[66:69]
	v_mfma_f32_16x16x32_bf16 v[2:5], v[162:165], v[202:205], v[2:5]
	v_mfma_f32_16x16x32_bf16 v[94:97], v[154:157], v[228:231], v[94:97]
	v_mfma_f32_16x16x32_bf16 v[22:25], v[162:165], v[228:231], v[22:25]
	v_mfma_f32_16x16x32_bf16 v[90:93], v[154:157], v[236:239], v[90:93]
	v_mfma_f32_16x16x32_bf16 v[18:21], v[162:165], v[236:239], v[18:21]
	v_mfma_f32_16x16x32_bf16 v[82:85], v[158:161], v[198:201], v[82:85]
	v_mfma_f32_16x16x32_bf16 v[10:13], v[166:169], v[198:201], v[10:13]
	v_mfma_f32_16x16x32_bf16 v[66:69], v[158:161], v[214:217], v[66:69]
	v_mfma_f32_16x16x32_bf16 v[2:5], v[166:169], v[214:217], v[2:5]
	v_mfma_f32_16x16x32_bf16 v[94:97], v[158:161], v[232:235], v[94:97]
	v_mfma_f32_16x16x32_bf16 v[22:25], v[166:169], v[232:235], v[22:25]
	v_mfma_f32_16x16x32_bf16 v[90:93], v[158:161], v[240:243], v[90:93]
	v_mfma_f32_16x16x32_bf16 v[18:21], v[166:169], v[240:243], v[18:21]
	s_barrier
	s_add_u32 s35, s35, 0x100
	s_addc_u32 s51, s51, 0
	s_cmp_ge_i32 s52, s68
	s_mov_b64 s[48:49], s[14:15]
	s_mov_b32 s46, s52
	s_cbranch_scc0 .LBB0_1495
	s_movk_i32 s78, 0x7ff
	s_movk_i32 s76, 0x3000
	s_and_b64 vcc, exec, s[30:31]
	s_cbranch_vccz .LBB0_1470

; #define PG8_STAGE(bufoff, gbase, voff) do { _Pragma("unroll") for (int _i = 0; _i < 2; ++_i) \
;         __builtin_amdgcn_global_load_lds((const unsigned*)((const char*)(gbase) + (voff)[_i]), (PG8_LAS unsigned*)(lds + (bufoff) + ldsw + _i * 8192), 16, 0, 0); } while (0)
; #define PG8_LDA(dst, b, h) do { _Pragma("unroll") for (int m = 0; m < 4; ++m) _Pragma("unroll") for (int k = 0; k < 2; ++k) dst[m][k] = *(const PG8_LAS bf16x8*)(lds + PG8_SA(b, h) + aoff + m * 2048 + k * 1024); } while (0)
; #define PG8_LDB(dst, b, h) do { _Pragma("unroll") for (int n = 0; n < 2; ++n) _Pragma("unroll") for (int k = 0; k < 2; ++k) dst[n][k] = *(const PG8_LAS bf16x8*)(lds + PG8_SB(b, h) + boff + n * 2048 + k * 1024); } while (0)
; #define PG8_MMA(ai, bj, At, Bt) do { __builtin_amdgcn_s_setprio(1); _Pragma("unroll") for (int m = 0; m < 4; ++m) _Pragma("unroll") for (int n = 0; n < 2; ++n) _Pragma("unroll") for (int k = 0; k < 2; ++k) \
;         acc[ai][bj][m][n] = __builtin_amdgcn_mfma_f32_16x16x32_bf16(Bt[n][k], At[m][k], acc[ai][bj][m][n], 0, 0, 0); __builtin_amdgcn_s_setprio(0); } while (0)
; #define PG8_WAIT_V(n) asm volatile("s_waitcnt vmcnt(" #n ")" ::: "memory")
; #define PG8_WAIT_L(n) asm volatile("s_waitcnt lgkmcnt(" #n ")" ::: "memory")
; template <class Epi, class Sched, bool ALIGN_EPI = false, bool SP2 = false>
; __device__ __forceinline__ void gemm_phase(PG8_LAS unsigned char* lds, const Gemm g, const Sched& S, const Epi& E, const int wv) {
;     ...
;             const bool last = (t == nt - 2);
;             const char* a1 = cA + (size_t)(t + 1) * kstep;
;             const char* a2 = last ? nA : cA + (size_t)(t + 2) * kstep; const char* b2 = last ? nB : cB + (size_t)(t + 2) * kstep;
;             const char* a3 = a2 + kstep; const char* b3 = b2 + kstep;
;             if (last && has_next) S.a_ready(nxt);
;             if constexpr (SP2) {
;             PG8_LDB(B0, 0, 0); PG8_LDB(B1, 0, 1); PG8_SCHED; PG8_LDA(At, 0, 0); PG8_STAGE(PG8_SA(1, 1), a1 + hstepA, voffA);
;             PG8_WAIT_V(8); PG8_WAIT_L(0); PG8_BAR; PG8_MMA(0, 0, At, B0); PG8_MMA(0, 1, At, B1); PG8_BAR; PG8_SCHED;
;             PG8_LDA(At, 0, 1); PG8_STAGE(PG8_SB(0, 0), b2, voffB); PG8_STAGE(PG8_SB(0, 1), b2 + hstepB, voffB); PG8_STAGE(PG8_SA(0, 0), a2, voffA);
;             PG8_WAIT_V(8); PG8_WAIT_L(0); PG8_BAR; PG8_MMA(1, 0, At, B0); PG8_MMA(1, 1, At, B1); PG8_BAR; PG8_SCHED;
.LBB0_1676:
	s_add_i32 s67, s44, 2
	s_add_u32 s34, s30, 0x100
	s_addc_u32 s35, s31, 0
	s_add_i32 s70, 0, 0x10000
	s_cmp_eq_u32 s59, s44
	s_cselect_b32 s45, s13, s35
	s_cselect_b32 s44, s12, s34
	s_cselect_b32 s69, s15, s66
	s_cselect_b32 s68, s14, s65
	s_add_i32 s71, 0, 0x14000
	ds_read_b128 v[114:117], v197
	ds_read_b128 v[126:129], v197 offset:1024
	ds_read_b128 v[138:141], v197 offset:2048
	ds_read_b128 v[142:145], v197 offset:3072
	ds_read_b128 v[146:149], v201
	ds_read_b128 v[150:153], v201 offset:1024
	ds_read_b128 v[154:157], v201 offset:2048
	ds_read_b128 v[158:161], v201 offset:3072
	s_add_i32 m0, s52, 0xc000
	ds_read_b128 v[162:165], v235
	ds_read_b128 v[166:169], v235 offset:1024
	ds_read_b128 v[170:173], v235 offset:2048
	ds_read_b128 v[174:177], v235 offset:3072
	ds_read_b128 v[178:181], v235 offset:4096
	ds_read_b128 v[182:185], v235 offset:5120
	ds_read_b128 v[204:207], v235 offset:6144
	ds_read_b128 v[208:211], v235 offset:7168
	global_load_lds_dwordx4 v200, s[30:31]
	s_add_i32 m0, s52, 0xe000
	s_nop 0
	global_load_lds_dwordx4 v202, s[30:31]
	s_waitcnt vmcnt(8)
	s_waitcnt lgkmcnt(0)
	s_barrier
	v_mfma_f32_16x16x32_bf16 v[134:137], v[114:117], v[162:165], v[134:137]
	v_mfma_f32_16x16x32_bf16 v[130:133], v[138:141], v[162:165], v[130:133]
	v_mfma_f32_16x16x32_bf16 v[110:113], v[114:117], v[170:173], v[110:113]
	v_mfma_f32_16x16x32_bf16 v[106:109], v[138:141], v[170:173], v[106:109]
	v_mfma_f32_16x16x32_bf16 v[94:97], v[114:117], v[178:181], v[94:97]
	v_mfma_f32_16x16x32_bf16 v[90:93], v[138:141], v[178:181], v[90:93]
	v_mfma_f32_16x16x32_bf16 v[78:81], v[114:117], v[204:207], v[78:81]
	v_mfma_f32_16x16x32_bf16 v[74:77], v[138:141], v[204:207], v[74:77]
	v_mfma_f32_16x16x32_bf16 v[134:137], v[126:129], v[166:169], v[134:137]
	v_mfma_f32_16x16x32_bf16 v[130:133], v[142:145], v[166:169], v[130:133]
	v_mfma_f32_16x16x32_bf16 v[110:113], v[126:129], v[174:177], v[110:113]
	v_mfma_f32_16x16x32_bf16 v[106:109], v[142:145], v[174:177], v[106:109]
	v_mfma_f32_16x16x32_bf16 v[94:97], v[126:129], v[182:185], v[94:97]
	v_mfma_f32_16x16x32_bf16 v[90:93], v[142:145], v[182:185], v[90:93]
	v_mfma_f32_16x16x32_bf16 v[78:81], v[126:129], v[208:211], v[78:81]
	v_mfma_f32_16x16x32_bf16 v[74:77], v[142:145], v[208:211], v[74:77]
	v_mfma_f32_16x16x32_bf16 v[122:125], v[146:149], v[162:165], v[122:125]
	v_mfma_f32_16x16x32_bf16 v[118:121], v[154:157], v[162:165], v[118:121]
	v_mfma_f32_16x16x32_bf16 v[102:105], v[146:149], v[170:173], v[102:105]
	v_mfma_f32_16x16x32_bf16 v[98:101], v[154:157], v[170:173], v[98:101]
	v_mfma_f32_16x16x32_bf16 v[86:89], v[146:149], v[178:181], v[86:89]
	v_mfma_f32_16x16x32_bf16 v[82:85], v[154:157], v[178:181], v[82:85]
	v_mfma_f32_16x16x32_bf16 v[70:73], v[146:149], v[204:207], v[70:73]
	v_mfma_f32_16x16x32_bf16 v[66:69], v[154:157], v[204:207], v[66:69]
	v_mfma_f32_16x16x32_bf16 v[122:125], v[150:153], v[166:169], v[122:125]
	v_mfma_f32_16x16x32_bf16 v[118:121], v[158:161], v[166:169], v[118:121]
	v_mfma_f32_16x16x32_bf16 v[102:105], v[150:153], v[174:177], v[102:105]
	v_mfma_f32_16x16x32_bf16 v[98:101], v[158:161], v[174:177], v[98:101]
	v_mfma_f32_16x16x32_bf16 v[86:89], v[150:153], v[182:185], v[86:89]
	v_mfma_f32_16x16x32_bf16 v[82:85], v[158:161], v[182:185], v[82:85]
	v_mfma_f32_16x16x32_bf16 v[70:73], v[150:153], v[208:211], v[70:73]
	v_mfma_f32_16x16x32_bf16 v[66:69], v[158:161], v[208:211], v[66:69]
	s_barrier
	s_add_i32 s30, s70, s47
	v_lshl_add_u64 v[190:191], s[68:69], 0, v[0:1]
	s_mov_b32 m0, s30
	ds_read_b128 v[162:165], v235 offset:16384
	ds_read_b128 v[166:169], v235 offset:17408
	ds_read_b128 v[170:173], v235 offset:18432
	ds_read_b128 v[174:177], v235 offset:19456
	ds_read_b128 v[178:181], v235 offset:20480
	ds_read_b128 v[182:185], v235 offset:21504
	ds_read_b128 v[204:207], v235 offset:22528
	ds_read_b128 v[208:211], v235 offset:23552
	global_load_lds_dwordx4 v[190:191], off
	s_add_i32 m0, s30, 0x2000
	s_add_u32 s30, s68, s2
	v_lshl_add_u64 v[192:193], s[68:69], 0, v[198:199]
	s_addc_u32 s31, s69, s3
	s_add_i32 s68, s71, s47
	global_load_lds_dwordx4 v[192:193], off
	v_lshl_add_u64 v[212:213], s[30:31], 0, v[0:1]
	s_mov_b32 m0, s68
	v_lshl_add_u64 v[214:215], s[30:31], 0, v[198:199]
	global_load_lds_dwordx4 v[212:213], off
	s_add_i32 m0, s68, 0x2000
	global_load_lds_dwordx4 v[214:215], off
	s_mov_b32 m0, s52
	global_load_lds_dwordx4 v194, s[44:45]
	s_mov_b32 m0, s53
	s_nop 0
	global_load_lds_dwordx4 v196, s[44:45]
	s_waitcnt vmcnt(8)
	s_waitcnt lgkmcnt(0)
	s_barrier
	v_mfma_f32_16x16x32_bf16 v[62:65], v[114:117], v[162:165], v[62:65]
	v_mfma_f32_16x16x32_bf16 v[58:61], v[138:141], v[162:165], v[58:61]
	v_mfma_f32_16x16x32_bf16 v[46:49], v[114:117], v[170:173], v[46:49]
	v_mfma_f32_16x16x32_bf16 v[42:45], v[138:141], v[170:173], v[42:45]
	v_mfma_f32_16x16x32_bf16 v[30:33], v[114:117], v[178:181], v[30:33]
	v_mfma_f32_16x16x32_bf16 v[26:29], v[138:141], v[178:181], v[26:29]
	v_mfma_f32_16x16x32_bf16 v[14:17], v[114:117], v[204:207], v[14:17]
	v_mfma_f32_16x16x32_bf16 v[10:13], v[138:141], v[204:207], v[10:13]
	v_mfma_f32_16x16x32_bf16 v[62:65], v[126:129], v[166:169], v[62:65]
	v_mfma_f32_16x16x32_bf16 v[58:61], v[142:145], v[166:169], v[58:61]
	v_mfma_f32_16x16x32_bf16 v[46:49], v[126:129], v[174:177], v[46:49]
	v_mfma_f32_16x16x32_bf16 v[42:45], v[142:145], v[174:177], v[42:45]
	v_mfma_f32_16x16x32_bf16 v[30:33], v[126:129], v[182:185], v[30:33]
	v_mfma_f32_16x16x32_bf16 v[26:29], v[142:145], v[182:185], v[26:29]
	v_mfma_f32_16x16x32_bf16 v[14:17], v[126:129], v[208:211], v[14:17]
	v_mfma_f32_16x16x32_bf16 v[10:13], v[142:145], v[208:211], v[10:13]
	v_mfma_f32_16x16x32_bf16 v[54:57], v[146:149], v[162:165], v[54:57]
	v_mfma_f32_16x16x32_bf16 v[50:53], v[154:157], v[162:165], v[50:53]
	v_mfma_f32_16x16x32_bf16 v[38:41], v[146:149], v[170:173], v[38:41]
	v_mfma_f32_16x16x32_bf16 v[34:37], v[154:157], v[170:173], v[34:37]
	v_mfma_f32_16x16x32_bf16 v[22:25], v[146:149], v[178:181], v[22:25]
	v_mfma_f32_16x16x32_bf16 v[18:21], v[154:157], v[178:181], v[18:21]
	v_mfma_f32_16x16x32_bf16 v[6:9], v[146:149], v[204:207], v[6:9]
	v_mfma_f32_16x16x32_bf16 v[2:5], v[154:157], v[204:207], v[2:5]
	v_mfma_f32_16x16x32_bf16 v[54:57], v[150:153], v[166:169], v[54:57]
	v_mfma_f32_16x16x32_bf16 v[50:53], v[158:161], v[166:169], v[50:53]
	v_mfma_f32_16x16x32_bf16 v[38:41], v[150:153], v[174:177], v[38:41]
	v_mfma_f32_16x16x32_bf16 v[34:37], v[158:161], v[174:177], v[34:37]
	v_mfma_f32_16x16x32_bf16 v[22:25], v[150:153], v[182:185], v[22:25]
	v_mfma_f32_16x16x32_bf16 v[18:21], v[158:161], v[182:185], v[18:21]
	v_mfma_f32_16x16x32_bf16 v[6:9], v[150:153], v[208:211], v[6:9]
	v_mfma_f32_16x16x32_bf16 v[2:5], v[158:161], v[208:211], v[2:5]
	s_barrier
; #define PG8_STAGE(bufoff, gbase, voff) do { _Pragma("unroll") for (int _i = 0; _i < 2; ++_i) \
;         __builtin_amdgcn_global_load_lds((const unsigned*)((const char*)(gbase) + (voff)[_i]), (PG8_LAS unsigned*)(lds + (bufoff) + ldsw + _i * 8192), 16, 0, 0); } while (0)
; #define PG8_LDA(dst, b, h) do { _Pragma("unroll") for (int m = 0; m < 4; ++m) _Pragma("unroll") for (int k = 0; k < 2; ++k) dst[m][k] = *(const PG8_LAS bf16x8*)(lds + PG8_SA(b, h) + aoff + m * 2048 + k * 1024); } while (0)
; #define PG8_LDB(dst, b, h) do { _Pragma("unroll") for (int n = 0; n < 2; ++n) _Pragma("unroll") for (int k = 0; k < 2; ++k) dst[n][k] = *(const PG8_LAS bf16x8*)(lds + PG8_SB(b, h) + boff + n * 2048 + k * 1024); } while (0)
; #define PG8_MMA(ai, bj, At, Bt) do { __builtin_amdgcn_s_setprio(1); _Pragma("unroll") for (int m = 0; m < 4; ++m) _Pragma("unroll") for (int n = 0; n < 2; ++n) _Pragma("unroll") for (int k = 0; k < 2; ++k) \
;         acc[ai][bj][m][n] = __builtin_amdgcn_mfma_f32_16x16x32_bf16(Bt[n][k], At[m][k], acc[ai][bj][m][n], 0, 0, 0); __builtin_amdgcn_s_setprio(0); } while (0)
; #define PG8_WAIT_V(n) asm volatile("s_waitcnt vmcnt(" #n ")" ::: "memory")
; #define PG8_WAIT_L(n) asm volatile("s_waitcnt lgkmcnt(" #n ")" ::: "memory")
; #define PG8_BAR __builtin_amdgcn_s_barrier()
; #define PG8_SCHED __builtin_amdgcn_sched_barrier(0)
; template <class Epi, class Sched, bool ALIGN_EPI = false, bool SP2 = false>
; __device__ __forceinline__ void gemm_phase(PG8_LAS unsigned char* lds, const Gemm g, const Sched& S, const Epi& E, const int wv) {
;     ...
;             PG8_LDB(B0, 1, 0); PG8_LDB(B1, 1, 1); PG8_SCHED; PG8_LDA(At, 1, 0); PG8_STAGE(PG8_SA(0, 1), a2 + hstepA, voffA);
;             PG8_WAIT_V(8); PG8_WAIT_L(0); PG8_BAR; PG8_MMA(0, 0, At, B0); PG8_MMA(0, 1, At, B1); PG8_BAR; PG8_SCHED;
;             PG8_LDA(At, 1, 1); PG8_STAGE(PG8_SB(1, 0), b3, voffB); PG8_STAGE(PG8_SB(1, 1), b3 + hstepB, voffB); PG8_STAGE(PG8_SA(1, 0), a3, voffA);
;             PG8_WAIT_V(8); PG8_WAIT_L(0); PG8_BAR; PG8_MMA(1, 0, At, B0); PG8_MMA(1, 1, At, B1); PG8_BAR; PG8_SCHED;
	s_add_i32 s68, 0, 0x18000
	s_add_i32 s69, 0, 0x1c000
	ds_read_b128 v[114:117], v203
	ds_read_b128 v[126:129], v203 offset:1024
	ds_read_b128 v[138:141], v203 offset:2048
	ds_read_b128 v[142:145], v203 offset:3072
	ds_read_b128 v[146:149], v216
	ds_read_b128 v[150:153], v216 offset:1024
	ds_read_b128 v[154:157], v216 offset:2048
	ds_read_b128 v[158:161], v216 offset:3072
	s_add_u32 s30, s44, 0x180000
	s_addc_u32 s31, s45, 0
	s_mov_b32 m0, s54
	ds_read_b128 v[162:165], v235 offset:32768
	ds_read_b128 v[166:169], v235 offset:33792
	ds_read_b128 v[170:173], v235 offset:34816
	ds_read_b128 v[174:177], v235 offset:35840
	ds_read_b128 v[178:181], v235 offset:36864
	ds_read_b128 v[182:185], v235 offset:37888
	ds_read_b128 v[204:207], v235 offset:38912
	ds_read_b128 v[208:211], v235 offset:39936
	global_load_lds_dwordx4 v194, s[30:31]
	s_mov_b32 m0, s55
	s_nop 0
	global_load_lds_dwordx4 v196, s[30:31]
	s_waitcnt vmcnt(8)
	s_waitcnt lgkmcnt(0)
	s_barrier
	v_mfma_f32_16x16x32_bf16 v[134:137], v[114:117], v[162:165], v[134:137]
	v_mfma_f32_16x16x32_bf16 v[130:133], v[138:141], v[162:165], v[130:133]
	v_mfma_f32_16x16x32_bf16 v[110:113], v[114:117], v[170:173], v[110:113]
	v_mfma_f32_16x16x32_bf16 v[106:109], v[138:141], v[170:173], v[106:109]
	v_mfma_f32_16x16x32_bf16 v[94:97], v[114:117], v[178:181], v[94:97]
	v_mfma_f32_16x16x32_bf16 v[90:93], v[138:141], v[178:181], v[90:93]
	v_mfma_f32_16x16x32_bf16 v[78:81], v[114:117], v[204:207], v[78:81]
	v_mfma_f32_16x16x32_bf16 v[74:77], v[138:141], v[204:207], v[74:77]
	v_mfma_f32_16x16x32_bf16 v[134:137], v[126:129], v[166:169], v[134:137]
	v_mfma_f32_16x16x32_bf16 v[130:133], v[142:145], v[166:169], v[130:133]
	v_mfma_f32_16x16x32_bf16 v[110:113], v[126:129], v[174:177], v[110:113]
	v_mfma_f32_16x16x32_bf16 v[106:109], v[142:145], v[174:177], v[106:109]
	v_mfma_f32_16x16x32_bf16 v[94:97], v[126:129], v[182:185], v[94:97]
	v_mfma_f32_16x16x32_bf16 v[90:93], v[142:145], v[182:185], v[90:93]
	v_mfma_f32_16x16x32_bf16 v[78:81], v[126:129], v[208:211], v[78:81]
	v_mfma_f32_16x16x32_bf16 v[74:77], v[142:145], v[208:211], v[74:77]
	v_mfma_f32_16x16x32_bf16 v[122:125], v[146:149], v[162:165], v[122:125]
	v_mfma_f32_16x16x32_bf16 v[118:121], v[154:157], v[162:165], v[118:121]
	v_mfma_f32_16x16x32_bf16 v[102:105], v[146:149], v[170:173], v[102:105]
	v_mfma_f32_16x16x32_bf16 v[98:101], v[154:157], v[170:173], v[98:101]
	v_mfma_f32_16x16x32_bf16 v[86:89], v[146:149], v[178:181], v[86:89]
	v_mfma_f32_16x16x32_bf16 v[82:85], v[154:157], v[178:181], v[82:85]
	v_mfma_f32_16x16x32_bf16 v[70:73], v[146:149], v[204:207], v[70:73]
	v_mfma_f32_16x16x32_bf16 v[66:69], v[154:157], v[204:207], v[66:69]
	v_mfma_f32_16x16x32_bf16 v[122:125], v[150:153], v[166:169], v[122:125]
	v_mfma_f32_16x16x32_bf16 v[118:121], v[158:161], v[166:169], v[118:121]
	v_mfma_f32_16x16x32_bf16 v[102:105], v[150:153], v[174:177], v[102:105]
	v_mfma_f32_16x16x32_bf16 v[98:101], v[158:161], v[174:177], v[98:101]
	v_mfma_f32_16x16x32_bf16 v[86:89], v[150:153], v[182:185], v[86:89]
	v_mfma_f32_16x16x32_bf16 v[82:85], v[158:161], v[182:185], v[82:85]
	v_mfma_f32_16x16x32_bf16 v[70:73], v[150:153], v[208:211], v[70:73]
	v_mfma_f32_16x16x32_bf16 v[66:69], v[158:161], v[208:211], v[66:69]
	s_barrier
	s_add_i32 s30, s68, s47
	s_add_i32 m0, s30, 0xffffff80
	ds_read_b128 v[162:165], v235 offset:49152
	ds_read_b128 v[166:169], v235 offset:50176
	ds_read_b128 v[170:173], v235 offset:51200
	ds_read_b128 v[174:177], v235 offset:52224
	ds_read_b128 v[178:181], v235 offset:53248
	ds_read_b128 v[182:185], v235 offset:54272
	ds_read_b128 v[204:207], v235 offset:55296
	ds_read_b128 v[208:211], v235 offset:56320
	global_load_lds_dwordx4 v[190:191], off offset:128
	s_add_i32 m0, s30, 0x1f80
	s_add_i32 s30, s69, s47
	global_load_lds_dwordx4 v[192:193], off offset:128
	s_add_i32 m0, s30, 0xffffff80
	s_nop 0
	global_load_lds_dwordx4 v[212:213], off offset:128
	s_add_i32 m0, s30, 0x1f80
	s_nop 0
	global_load_lds_dwordx4 v[214:215], off offset:128
	s_add_i32 m0, s57, 0xffffff80
	s_nop 0
	global_load_lds_dwordx4 v194, s[44:45] offset:128
	s_add_i32 m0, s58, 0xffffff80
	s_nop 0
	global_load_lds_dwordx4 v196, s[44:45] offset:128
	s_waitcnt vmcnt(8)
	s_waitcnt lgkmcnt(0)
	s_barrier
	v_mfma_f32_16x16x32_bf16 v[62:65], v[114:117], v[162:165], v[62:65]
	v_mfma_f32_16x16x32_bf16 v[58:61], v[138:141], v[162:165], v[58:61]
	v_mfma_f32_16x16x32_bf16 v[46:49], v[114:117], v[170:173], v[46:49]
	v_mfma_f32_16x16x32_bf16 v[42:45], v[138:141], v[170:173], v[42:45]
	v_mfma_f32_16x16x32_bf16 v[30:33], v[114:117], v[178:181], v[30:33]
	v_mfma_f32_16x16x32_bf16 v[26:29], v[138:141], v[178:181], v[26:29]
	v_mfma_f32_16x16x32_bf16 v[14:17], v[114:117], v[204:207], v[14:17]
	v_mfma_f32_16x16x32_bf16 v[10:13], v[138:141], v[204:207], v[10:13]
	v_mfma_f32_16x16x32_bf16 v[62:65], v[126:129], v[166:169], v[62:65]
	v_mfma_f32_16x16x32_bf16 v[58:61], v[142:145], v[166:169], v[58:61]
	v_mfma_f32_16x16x32_bf16 v[46:49], v[126:129], v[174:177], v[46:49]
	v_mfma_f32_16x16x32_bf16 v[42:45], v[142:145], v[174:177], v[42:45]
	v_mfma_f32_16x16x32_bf16 v[30:33], v[126:129], v[182:185], v[30:33]
	v_mfma_f32_16x16x32_bf16 v[26:29], v[142:145], v[182:185], v[26:29]
	v_mfma_f32_16x16x32_bf16 v[14:17], v[126:129], v[208:211], v[14:17]
	v_mfma_f32_16x16x32_bf16 v[10:13], v[142:145], v[208:211], v[10:13]
	v_mfma_f32_16x16x32_bf16 v[54:57], v[146:149], v[162:165], v[54:57]
	v_mfma_f32_16x16x32_bf16 v[50:53], v[154:157], v[162:165], v[50:53]
	v_mfma_f32_16x16x32_bf16 v[38:41], v[146:149], v[170:173], v[38:41]
	v_mfma_f32_16x16x32_bf16 v[34:37], v[154:157], v[170:173], v[34:37]
	v_mfma_f32_16x16x32_bf16 v[22:25], v[146:149], v[178:181], v[22:25]
	v_mfma_f32_16x16x32_bf16 v[18:21], v[154:157], v[178:181], v[18:21]
	v_mfma_f32_16x16x32_bf16 v[6:9], v[146:149], v[204:207], v[6:9]
	v_mfma_f32_16x16x32_bf16 v[2:5], v[154:157], v[204:207], v[2:5]
	v_mfma_f32_16x16x32_bf16 v[54:57], v[150:153], v[166:169], v[54:57]
	v_mfma_f32_16x16x32_bf16 v[50:53], v[158:161], v[166:169], v[50:53]
	v_mfma_f32_16x16x32_bf16 v[38:41], v[150:153], v[174:177], v[38:41]
	v_mfma_f32_16x16x32_bf16 v[34:37], v[158:161], v[174:177], v[34:37]
	v_mfma_f32_16x16x32_bf16 v[22:25], v[150:153], v[182:185], v[22:25]
	v_mfma_f32_16x16x32_bf16 v[18:21], v[158:161], v[182:185], v[18:21]
	v_mfma_f32_16x16x32_bf16 v[6:9], v[150:153], v[208:211], v[6:9]
	v_mfma_f32_16x16x32_bf16 v[2:5], v[158:161], v[208:211], v[2:5]
	s_barrier
	s_add_u32 s65, s65, 0x100
	s_addc_u32 s66, s66, 0
	s_cmp_ge_i32 s67, s56
	s_mov_b64 s[30:31], s[34:35]
	s_mov_b32 s44, s67
	s_cbranch_scc0 .LBB0_1676
	s_movk_i32 s68, 0x4000
	s_movk_i32 s69, 0x6000
	s_mov_b32 s70, 0x18000
	s_mov_b32 s71, 0x3f317217
	s_and_b64 vcc, exec, s[28:29]
	s_cbranch_vccz .LBB0_1652
